# early post-MFMA barrier: s_barrier moved up 2 MFMAs, leftover MFMAs at setprio 2 (hides barrier hand-off bubble)
# speedup vs baseline: 1.0044x; 1.0044x over previous
.LBB0_344:
	ds_read_b128 v[148:151], v143
	ds_read_b128 v[152:155], v143 offset:1024
	ds_read_b128 v[156:159], v143 offset:2048
	ds_read_b128 v[160:163], v143 offset:3072
	ds_read_b128 v[164:167], v144
	ds_read_b128 v[168:171], v144 offset:1024
	ds_read_b128 v[172:175], v144 offset:2048
	ds_read_b128 v[176:179], v144 offset:3072
	s_cmp_eq_u32 s81, 28
	s_cselect_b32 s21, s9, s78
	s_cselect_b32 s20, s76, s77
	s_cselect_b32 s23, s11, s80
	s_cselect_b32 s22, s75, s79
	ds_read_b128 v[180:183], v145
	ds_read_b128 v[184:187], v145 offset:1024
	ds_read_b128 v[188:191], v145 offset:2048
	ds_read_b128 v[192:195], v145 offset:3072
	ds_read_b128 v[196:199], v145 offset:4096
	ds_read_b128 v[200:203], v145 offset:5120
	ds_read_b128 v[204:207], v145 offset:6144
	ds_read_b128 v[208:211], v145 offset:7168
	s_add_u32 s82, s18, 0xfff80000
	s_addc_u32 s83, s19, -1
	s_mov_b32 s86, m0
	s_mov_b32 m0, s64
	s_nop 0
	global_load_lds_dwordx4 v138, s[82:83]
	s_mov_b32 m0, s86
	s_nop 0
	s_mov_b32 s86, m0
	s_mov_b32 m0, s67
	s_nop 0
	global_load_lds_dwordx4 v140, s[82:83]
	s_mov_b32 m0, s86
	s_mov_b32 s82, m0
	s_mov_b32 m0, s65
	s_nop 0
	global_load_lds_dwordx4 v138, s[18:19]
	s_mov_b32 m0, s82
	s_nop 0
	s_mov_b32 s82, m0
	s_mov_b32 m0, s73
	s_nop 0
	global_load_lds_dwordx4 v140, s[18:19]
	s_mov_b32 m0, s82
	s_waitcnt vmcnt(8)
	s_waitcnt lgkmcnt(0)
	s_barrier
	s_setprio 1
	s_waitcnt lgkmcnt(7)
	v_mfma_f32_16x16x32_bf16 v[126:129], v[148:151], v[180:183], v[126:129]
	v_mfma_f32_16x16x32_bf16 v[122:125], v[156:159], v[180:183], v[122:125]
	s_waitcnt lgkmcnt(5)
	v_mfma_f32_16x16x32_bf16 v[110:113], v[148:151], v[188:191], v[110:113]
	v_mfma_f32_16x16x32_bf16 v[106:109], v[156:159], v[188:191], v[106:109]
	s_waitcnt lgkmcnt(3)
	v_mfma_f32_16x16x32_bf16 v[94:97], v[148:151], v[196:199], v[94:97]
	v_mfma_f32_16x16x32_bf16 v[90:93], v[156:159], v[196:199], v[90:93]
	s_waitcnt lgkmcnt(1)
	v_mfma_f32_16x16x32_bf16 v[78:81], v[148:151], v[204:207], v[78:81]
	v_mfma_f32_16x16x32_bf16 v[74:77], v[156:159], v[204:207], v[74:77]
	v_mfma_f32_16x16x32_bf16 v[126:129], v[152:155], v[184:187], v[126:129]
	v_mfma_f32_16x16x32_bf16 v[122:125], v[160:163], v[184:187], v[122:125]
	v_mfma_f32_16x16x32_bf16 v[110:113], v[152:155], v[192:195], v[110:113]
	v_mfma_f32_16x16x32_bf16 v[106:109], v[160:163], v[192:195], v[106:109]
	v_mfma_f32_16x16x32_bf16 v[94:97], v[152:155], v[200:203], v[94:97]
	v_mfma_f32_16x16x32_bf16 v[90:93], v[160:163], v[200:203], v[90:93]
	s_waitcnt lgkmcnt(0)
	v_mfma_f32_16x16x32_bf16 v[78:81], v[152:155], v[208:211], v[78:81]
	v_mfma_f32_16x16x32_bf16 v[74:77], v[160:163], v[208:211], v[74:77]
	s_setprio 0
	s_setprio 1
	v_mfma_f32_16x16x32_bf16 v[118:121], v[164:167], v[180:183], v[118:121]
	v_mfma_f32_16x16x32_bf16 v[114:117], v[172:175], v[180:183], v[114:117]
	v_mfma_f32_16x16x32_bf16 v[102:105], v[164:167], v[188:191], v[102:105]
	v_mfma_f32_16x16x32_bf16 v[98:101], v[172:175], v[188:191], v[98:101]
	v_mfma_f32_16x16x32_bf16 v[86:89], v[164:167], v[196:199], v[86:89]
	v_mfma_f32_16x16x32_bf16 v[82:85], v[172:175], v[196:199], v[82:85]
	v_mfma_f32_16x16x32_bf16 v[70:73], v[164:167], v[204:207], v[70:73]
	v_mfma_f32_16x16x32_bf16 v[66:69], v[172:175], v[204:207], v[66:69]
	v_mfma_f32_16x16x32_bf16 v[118:121], v[168:171], v[184:187], v[118:121]
	v_mfma_f32_16x16x32_bf16 v[114:117], v[176:179], v[184:187], v[114:117]
	v_mfma_f32_16x16x32_bf16 v[102:105], v[168:171], v[192:195], v[102:105]
	v_mfma_f32_16x16x32_bf16 v[98:101], v[176:179], v[192:195], v[98:101]
	v_mfma_f32_16x16x32_bf16 v[86:89], v[168:171], v[200:203], v[86:89]
	v_mfma_f32_16x16x32_bf16 v[82:85], v[176:179], v[200:203], v[82:85]
	s_setprio 2
	s_barrier
	v_mfma_f32_16x16x32_bf16 v[70:73], v[168:171], v[208:211], v[70:73]
	v_mfma_f32_16x16x32_bf16 v[66:69], v[176:179], v[208:211], v[66:69]
	s_setprio 0
	ds_read_b128 v[180:183], v145 offset:16384
	ds_read_b128 v[184:187], v145 offset:17408
	ds_read_b128 v[188:191], v145 offset:18432
	ds_read_b128 v[192:195], v145 offset:19456
	ds_read_b128 v[196:199], v145 offset:20480
	ds_read_b128 v[200:203], v145 offset:21504
	ds_read_b128 v[204:207], v145 offset:22528
	ds_read_b128 v[208:211], v145 offset:23552
	s_mov_b32 s82, m0
	s_mov_b32 m0, s35
	s_nop 0
	global_load_lds_dwordx4 v139, s[20:21]
	s_mov_b32 m0, s82
	s_nop 0
	s_mov_b32 s82, m0
	s_mov_b32 m0, s36
	s_nop 0
	global_load_lds_dwordx4 v141, s[20:21]
	s_mov_b32 m0, s82
	s_add_u32 s82, s20, 0x80000
	s_addc_u32 s83, s21, 0
	s_mov_b32 s86, m0
	s_mov_b32 m0, s37
	s_nop 0
	global_load_lds_dwordx4 v139, s[82:83]
	s_mov_b32 m0, s86
	s_nop 0
	s_mov_b32 s86, m0
	s_mov_b32 m0, s42
	s_nop 0
	global_load_lds_dwordx4 v141, s[82:83]
	s_mov_b32 m0, s86
	s_waitcnt vmcnt(4)
	s_waitcnt lgkmcnt(0)
	s_barrier
	s_setprio 1
	s_waitcnt lgkmcnt(7)
	v_mfma_f32_16x16x32_bf16 v[62:65], v[148:151], v[180:183], v[62:65]
	v_mfma_f32_16x16x32_bf16 v[58:61], v[156:159], v[180:183], v[58:61]
	s_waitcnt lgkmcnt(5)
	v_mfma_f32_16x16x32_bf16 v[46:49], v[148:151], v[188:191], v[46:49]
	v_mfma_f32_16x16x32_bf16 v[42:45], v[156:159], v[188:191], v[42:45]
	s_waitcnt lgkmcnt(3)
	v_mfma_f32_16x16x32_bf16 v[30:33], v[148:151], v[196:199], v[30:33]
	v_mfma_f32_16x16x32_bf16 v[26:29], v[156:159], v[196:199], v[26:29]
	s_waitcnt lgkmcnt(1)
	v_mfma_f32_16x16x32_bf16 v[14:17], v[148:151], v[204:207], v[14:17]
	v_mfma_f32_16x16x32_bf16 v[10:13], v[156:159], v[204:207], v[10:13]
	v_mfma_f32_16x16x32_bf16 v[62:65], v[152:155], v[184:187], v[62:65]
	v_mfma_f32_16x16x32_bf16 v[58:61], v[160:163], v[184:187], v[58:61]
	v_mfma_f32_16x16x32_bf16 v[46:49], v[152:155], v[192:195], v[46:49]
	v_mfma_f32_16x16x32_bf16 v[42:45], v[160:163], v[192:195], v[42:45]
	v_mfma_f32_16x16x32_bf16 v[30:33], v[152:155], v[200:203], v[30:33]
	v_mfma_f32_16x16x32_bf16 v[26:29], v[160:163], v[200:203], v[26:29]
	s_waitcnt lgkmcnt(0)
	v_mfma_f32_16x16x32_bf16 v[14:17], v[152:155], v[208:211], v[14:17]
	v_mfma_f32_16x16x32_bf16 v[10:13], v[160:163], v[208:211], v[10:13]
	s_setprio 0
	s_setprio 1
	v_mfma_f32_16x16x32_bf16 v[54:57], v[164:167], v[180:183], v[54:57]
	v_mfma_f32_16x16x32_bf16 v[50:53], v[172:175], v[180:183], v[50:53]
	v_mfma_f32_16x16x32_bf16 v[38:41], v[164:167], v[188:191], v[38:41]
	v_mfma_f32_16x16x32_bf16 v[34:37], v[172:175], v[188:191], v[34:37]
	v_mfma_f32_16x16x32_bf16 v[22:25], v[164:167], v[196:199], v[22:25]
	v_mfma_f32_16x16x32_bf16 v[18:21], v[172:175], v[196:199], v[18:21]
	v_mfma_f32_16x16x32_bf16 v[6:9], v[164:167], v[204:207], v[6:9]
	v_mfma_f32_16x16x32_bf16 v[2:5], v[172:175], v[204:207], v[2:5]
	v_mfma_f32_16x16x32_bf16 v[54:57], v[168:171], v[184:187], v[54:57]
	v_mfma_f32_16x16x32_bf16 v[50:53], v[176:179], v[184:187], v[50:53]
	v_mfma_f32_16x16x32_bf16 v[38:41], v[168:171], v[192:195], v[38:41]
	v_mfma_f32_16x16x32_bf16 v[34:37], v[176:179], v[192:195], v[34:37]
	v_mfma_f32_16x16x32_bf16 v[22:25], v[168:171], v[200:203], v[22:25]
	v_mfma_f32_16x16x32_bf16 v[18:21], v[176:179], v[200:203], v[18:21]
	s_setprio 2
	s_barrier
	v_mfma_f32_16x16x32_bf16 v[6:9], v[168:171], v[208:211], v[6:9]
	v_mfma_f32_16x16x32_bf16 v[2:5], v[176:179], v[208:211], v[2:5]
	s_setprio 0
	ds_read_b128 v[148:151], v146
	ds_read_b128 v[152:155], v146 offset:1024
	ds_read_b128 v[156:159], v146 offset:2048
	ds_read_b128 v[160:163], v146 offset:3072
	ds_read_b128 v[164:167], v147
	ds_read_b128 v[168:171], v147 offset:1024
	ds_read_b128 v[172:175], v147 offset:2048
	ds_read_b128 v[176:179], v147 offset:3072
	ds_read_b128 v[180:183], v145 offset:32768
	ds_read_b128 v[184:187], v145 offset:33792
	ds_read_b128 v[188:191], v145 offset:34816
	ds_read_b128 v[192:195], v145 offset:35840
	ds_read_b128 v[196:199], v145 offset:36864
	ds_read_b128 v[200:203], v145 offset:37888
	ds_read_b128 v[204:207], v145 offset:38912
	ds_read_b128 v[208:211], v145 offset:39936
	s_mov_b32 s82, m0
	s_mov_b32 m0, s31
	s_nop 0
	global_load_lds_dwordx4 v138, s[22:23]
	s_mov_b32 m0, s82
	s_nop 0
	s_mov_b32 s82, m0
	s_mov_b32 m0, s43
	s_nop 0
	global_load_lds_dwordx4 v140, s[22:23]
	s_mov_b32 m0, s82
	s_add_u32 s22, s22, 0x80000
	s_addc_u32 s23, s23, 0
	s_mov_b32 s82, m0
	s_mov_b32 m0, s46
	s_nop 0
	global_load_lds_dwordx4 v138, s[22:23]
	s_mov_b32 m0, s82
	s_nop 0
	s_mov_b32 s82, m0
	s_mov_b32 m0, s47
	s_nop 0
	global_load_lds_dwordx4 v140, s[22:23]
	s_mov_b32 m0, s82
	s_waitcnt vmcnt(8)
	s_waitcnt lgkmcnt(0)
	s_barrier
	s_setprio 1
	s_waitcnt lgkmcnt(7)
	v_mfma_f32_16x16x32_bf16 v[126:129], v[148:151], v[180:183], v[126:129]
	v_mfma_f32_16x16x32_bf16 v[122:125], v[156:159], v[180:183], v[122:125]
	s_waitcnt lgkmcnt(5)
	v_mfma_f32_16x16x32_bf16 v[110:113], v[148:151], v[188:191], v[110:113]
	v_mfma_f32_16x16x32_bf16 v[106:109], v[156:159], v[188:191], v[106:109]
	s_waitcnt lgkmcnt(3)
	v_mfma_f32_16x16x32_bf16 v[94:97], v[148:151], v[196:199], v[94:97]
	v_mfma_f32_16x16x32_bf16 v[90:93], v[156:159], v[196:199], v[90:93]
	s_waitcnt lgkmcnt(1)
	v_mfma_f32_16x16x32_bf16 v[78:81], v[148:151], v[204:207], v[78:81]
	v_mfma_f32_16x16x32_bf16 v[74:77], v[156:159], v[204:207], v[74:77]
	v_mfma_f32_16x16x32_bf16 v[126:129], v[152:155], v[184:187], v[126:129]
	v_mfma_f32_16x16x32_bf16 v[122:125], v[160:163], v[184:187], v[122:125]
	v_mfma_f32_16x16x32_bf16 v[110:113], v[152:155], v[192:195], v[110:113]
	v_mfma_f32_16x16x32_bf16 v[106:109], v[160:163], v[192:195], v[106:109]
	v_mfma_f32_16x16x32_bf16 v[94:97], v[152:155], v[200:203], v[94:97]
	v_mfma_f32_16x16x32_bf16 v[90:93], v[160:163], v[200:203], v[90:93]
	s_waitcnt lgkmcnt(0)
	v_mfma_f32_16x16x32_bf16 v[78:81], v[152:155], v[208:211], v[78:81]
	v_mfma_f32_16x16x32_bf16 v[74:77], v[160:163], v[208:211], v[74:77]
	s_setprio 0
	s_setprio 1
	v_mfma_f32_16x16x32_bf16 v[118:121], v[164:167], v[180:183], v[118:121]
	v_mfma_f32_16x16x32_bf16 v[114:117], v[172:175], v[180:183], v[114:117]
	v_mfma_f32_16x16x32_bf16 v[102:105], v[164:167], v[188:191], v[102:105]
	v_mfma_f32_16x16x32_bf16 v[98:101], v[172:175], v[188:191], v[98:101]
	v_mfma_f32_16x16x32_bf16 v[86:89], v[164:167], v[196:199], v[86:89]
	v_mfma_f32_16x16x32_bf16 v[82:85], v[172:175], v[196:199], v[82:85]
	v_mfma_f32_16x16x32_bf16 v[70:73], v[164:167], v[204:207], v[70:73]
	v_mfma_f32_16x16x32_bf16 v[66:69], v[172:175], v[204:207], v[66:69]
	v_mfma_f32_16x16x32_bf16 v[118:121], v[168:171], v[184:187], v[118:121]
	v_mfma_f32_16x16x32_bf16 v[114:117], v[176:179], v[184:187], v[114:117]
	v_mfma_f32_16x16x32_bf16 v[102:105], v[168:171], v[192:195], v[102:105]
	v_mfma_f32_16x16x32_bf16 v[98:101], v[176:179], v[192:195], v[98:101]
	v_mfma_f32_16x16x32_bf16 v[86:89], v[168:171], v[200:203], v[86:89]
	v_mfma_f32_16x16x32_bf16 v[82:85], v[176:179], v[200:203], v[82:85]
	s_setprio 2
	s_barrier
	v_mfma_f32_16x16x32_bf16 v[70:73], v[168:171], v[208:211], v[70:73]
	v_mfma_f32_16x16x32_bf16 v[66:69], v[176:179], v[208:211], v[66:69]
	s_setprio 0
	ds_read_b128 v[180:183], v145 offset:49152
	ds_read_b128 v[184:187], v145 offset:50176
	ds_read_b128 v[188:191], v145 offset:51200
	ds_read_b128 v[192:195], v145 offset:52224
	ds_read_b128 v[196:199], v145 offset:53248
	ds_read_b128 v[200:203], v145 offset:54272
	ds_read_b128 v[204:207], v145 offset:55296
	ds_read_b128 v[208:211], v145 offset:56320
	s_add_u32 s22, s20, 0x80
	s_addc_u32 s23, s21, 0
	s_mov_b32 s82, m0
	s_mov_b32 m0, s48
	s_nop 0
	global_load_lds_dwordx4 v139, s[22:23]
	s_mov_b32 m0, s82
	s_add_u32 s20, s20, 0x80080
	s_mov_b32 s82, m0
	s_mov_b32 m0, s49
	s_nop 0
	global_load_lds_dwordx4 v141, s[22:23]
	s_mov_b32 m0, s82
	s_addc_u32 s21, s21, 0
	s_mov_b32 s22, m0
	s_mov_b32 m0, s56
	s_nop 0
	global_load_lds_dwordx4 v139, s[20:21]
	s_mov_b32 m0, s22
	s_nop 0
	s_mov_b32 s22, m0
	s_mov_b32 m0, s57
	s_nop 0
	global_load_lds_dwordx4 v141, s[20:21]
	s_mov_b32 m0, s22
	s_waitcnt vmcnt(4)
	s_waitcnt lgkmcnt(0)
	s_barrier
	s_setprio 1
	s_waitcnt lgkmcnt(7)
	v_mfma_f32_16x16x32_bf16 v[62:65], v[148:151], v[180:183], v[62:65]
	v_mfma_f32_16x16x32_bf16 v[58:61], v[156:159], v[180:183], v[58:61]
	s_waitcnt lgkmcnt(5)
	v_mfma_f32_16x16x32_bf16 v[46:49], v[148:151], v[188:191], v[46:49]
	v_mfma_f32_16x16x32_bf16 v[42:45], v[156:159], v[188:191], v[42:45]
	s_waitcnt lgkmcnt(3)
	v_mfma_f32_16x16x32_bf16 v[30:33], v[148:151], v[196:199], v[30:33]
	v_mfma_f32_16x16x32_bf16 v[26:29], v[156:159], v[196:199], v[26:29]
	s_waitcnt lgkmcnt(1)
	v_mfma_f32_16x16x32_bf16 v[14:17], v[148:151], v[204:207], v[14:17]
	v_mfma_f32_16x16x32_bf16 v[10:13], v[156:159], v[204:207], v[10:13]
	v_mfma_f32_16x16x32_bf16 v[62:65], v[152:155], v[184:187], v[62:65]
	v_mfma_f32_16x16x32_bf16 v[58:61], v[160:163], v[184:187], v[58:61]
	v_mfma_f32_16x16x32_bf16 v[46:49], v[152:155], v[192:195], v[46:49]
	v_mfma_f32_16x16x32_bf16 v[42:45], v[160:163], v[192:195], v[42:45]
	v_mfma_f32_16x16x32_bf16 v[30:33], v[152:155], v[200:203], v[30:33]
	v_mfma_f32_16x16x32_bf16 v[26:29], v[160:163], v[200:203], v[26:29]
	s_waitcnt lgkmcnt(0)
	v_mfma_f32_16x16x32_bf16 v[14:17], v[152:155], v[208:211], v[14:17]
	v_mfma_f32_16x16x32_bf16 v[10:13], v[160:163], v[208:211], v[10:13]
	s_setprio 0
	s_setprio 1
	v_mfma_f32_16x16x32_bf16 v[54:57], v[164:167], v[180:183], v[54:57]
	v_mfma_f32_16x16x32_bf16 v[50:53], v[172:175], v[180:183], v[50:53]
	v_mfma_f32_16x16x32_bf16 v[38:41], v[164:167], v[188:191], v[38:41]
	v_mfma_f32_16x16x32_bf16 v[34:37], v[172:175], v[188:191], v[34:37]
	v_mfma_f32_16x16x32_bf16 v[22:25], v[164:167], v[196:199], v[22:25]
	v_mfma_f32_16x16x32_bf16 v[18:21], v[172:175], v[196:199], v[18:21]
	v_mfma_f32_16x16x32_bf16 v[6:9], v[164:167], v[204:207], v[6:9]
	v_mfma_f32_16x16x32_bf16 v[2:5], v[172:175], v[204:207], v[2:5]
	v_mfma_f32_16x16x32_bf16 v[54:57], v[168:171], v[184:187], v[54:57]
	v_mfma_f32_16x16x32_bf16 v[50:53], v[176:179], v[184:187], v[50:53]
	v_mfma_f32_16x16x32_bf16 v[38:41], v[168:171], v[192:195], v[38:41]
	v_mfma_f32_16x16x32_bf16 v[34:37], v[176:179], v[192:195], v[34:37]
	v_mfma_f32_16x16x32_bf16 v[22:25], v[168:171], v[200:203], v[22:25]
	v_mfma_f32_16x16x32_bf16 v[18:21], v[176:179], v[200:203], v[18:21]
	s_setprio 2
	s_barrier
	v_mfma_f32_16x16x32_bf16 v[6:9], v[168:171], v[208:211], v[6:9]
	v_mfma_f32_16x16x32_bf16 v[2:5], v[176:179], v[208:211], v[2:5]
	s_setprio 0
	s_add_i32 s81, s81, 2
	s_add_u32 s77, s77, 0x100
	s_addc_u32 s78, s78, 0
	s_add_u32 s18, s18, 0x100
	s_addc_u32 s19, s19, 0
	s_add_u32 s79, s79, 0x100
	s_addc_u32 s80, s80, 0
	s_cmp_gt_u32 s81, 29
	s_cbranch_scc0 .LBB0_344
	s_and_b64 vcc, exec, s[6:7]
	s_cbranch_vccz .LBB0_347
	s_barrier

.LBB0_473:
	ds_read_b128 v[134:137], v161
	ds_read_b128 v[138:141], v161 offset:1024
	ds_read_b128 v[142:145], v161 offset:2048
	ds_read_b128 v[146:149], v161 offset:3072
	ds_read_b128 v[150:153], v162
	ds_read_b128 v[166:169], v162 offset:1024
	ds_read_b128 v[170:173], v162 offset:2048
	ds_read_b128 v[174:177], v162 offset:3072
	s_cmpk_eq_i32 s82, 0x52
	s_cselect_b32 s23, s11, s79
	s_cselect_b32 s22, s77, s78
	s_cselect_b32 s25, s13, s81
	s_cselect_b32 s24, s76, s80
	ds_read_b128 v[178:181], v163
	ds_read_b128 v[182:185], v163 offset:1024
	ds_read_b128 v[186:189], v163 offset:2048
	ds_read_b128 v[190:193], v163 offset:3072
	ds_read_b128 v[194:197], v163 offset:4096
	ds_read_b128 v[198:201], v163 offset:5120
	ds_read_b128 v[202:205], v163 offset:6144
	ds_read_b128 v[206:209], v163 offset:7168
	s_add_u32 s86, s20, 0xffffc000
	s_addc_u32 s87, s21, -1
	s_mov_b32 s83, m0
	s_mov_b32 m0, s65
	s_nop 0
	global_load_lds_dwordx4 v1, s[86:87]
	s_mov_b32 m0, s83
	s_nop 0
	s_mov_b32 s83, m0
	s_mov_b32 m0, s67
	s_nop 0
	global_load_lds_dwordx4 v157, s[86:87]
	s_mov_b32 m0, s83
	s_nop 0
	s_mov_b32 s83, m0
	s_mov_b32 m0, s66
	s_nop 0
	global_load_lds_dwordx4 v1, s[20:21]
	s_mov_b32 m0, s83
	s_nop 0
	s_mov_b32 s83, m0
	s_mov_b32 m0, s73
	s_nop 0
	global_load_lds_dwordx4 v157, s[20:21]
	s_mov_b32 m0, s83
	s_waitcnt vmcnt(8)
	s_waitcnt lgkmcnt(0)
	s_barrier
	s_setprio 1
	s_waitcnt lgkmcnt(7)
	v_mfma_f32_16x16x32_bf16 v[126:129], v[134:137], v[178:181], v[126:129]
	v_mfma_f32_16x16x32_bf16 v[122:125], v[142:145], v[178:181], v[122:125]
	s_waitcnt lgkmcnt(5)
	v_mfma_f32_16x16x32_bf16 v[118:121], v[134:137], v[186:189], v[118:121]
	v_mfma_f32_16x16x32_bf16 v[114:117], v[142:145], v[186:189], v[114:117]
	s_waitcnt lgkmcnt(3)
	v_mfma_f32_16x16x32_bf16 v[102:105], v[134:137], v[194:197], v[102:105]
	v_mfma_f32_16x16x32_bf16 v[94:97], v[142:145], v[194:197], v[94:97]
	s_waitcnt lgkmcnt(1)
	v_mfma_f32_16x16x32_bf16 v[86:89], v[134:137], v[202:205], v[86:89]
	v_mfma_f32_16x16x32_bf16 v[78:81], v[142:145], v[202:205], v[78:81]
	v_mfma_f32_16x16x32_bf16 v[126:129], v[138:141], v[182:185], v[126:129]
	v_mfma_f32_16x16x32_bf16 v[122:125], v[146:149], v[182:185], v[122:125]
	v_mfma_f32_16x16x32_bf16 v[118:121], v[138:141], v[190:193], v[118:121]
	v_mfma_f32_16x16x32_bf16 v[114:117], v[146:149], v[190:193], v[114:117]
	v_mfma_f32_16x16x32_bf16 v[102:105], v[138:141], v[198:201], v[102:105]
	v_mfma_f32_16x16x32_bf16 v[94:97], v[146:149], v[198:201], v[94:97]
	s_waitcnt lgkmcnt(0)
	v_mfma_f32_16x16x32_bf16 v[86:89], v[138:141], v[206:209], v[86:89]
	v_mfma_f32_16x16x32_bf16 v[78:81], v[146:149], v[206:209], v[78:81]
	s_setprio 0
	s_setprio 1
	v_mfma_f32_16x16x32_bf16 v[110:113], v[150:153], v[178:181], v[110:113]
	v_mfma_f32_16x16x32_bf16 v[106:109], v[170:173], v[178:181], v[106:109]
	v_mfma_f32_16x16x32_bf16 v[98:101], v[150:153], v[186:189], v[98:101]
	v_mfma_f32_16x16x32_bf16 v[90:93], v[170:173], v[186:189], v[90:93]
	v_mfma_f32_16x16x32_bf16 v[82:85], v[150:153], v[194:197], v[82:85]
	v_mfma_f32_16x16x32_bf16 v[74:77], v[170:173], v[194:197], v[74:77]
	v_mfma_f32_16x16x32_bf16 v[70:73], v[150:153], v[202:205], v[70:73]
	v_mfma_f32_16x16x32_bf16 v[66:69], v[170:173], v[202:205], v[66:69]
	v_mfma_f32_16x16x32_bf16 v[110:113], v[166:169], v[182:185], v[110:113]
	v_mfma_f32_16x16x32_bf16 v[106:109], v[174:177], v[182:185], v[106:109]
	v_mfma_f32_16x16x32_bf16 v[98:101], v[166:169], v[190:193], v[98:101]
	v_mfma_f32_16x16x32_bf16 v[90:93], v[174:177], v[190:193], v[90:93]
	v_mfma_f32_16x16x32_bf16 v[82:85], v[166:169], v[198:201], v[82:85]
	v_mfma_f32_16x16x32_bf16 v[74:77], v[174:177], v[198:201], v[74:77]
	s_setprio 2
	s_barrier
	v_mfma_f32_16x16x32_bf16 v[70:73], v[166:169], v[206:209], v[70:73]
	v_mfma_f32_16x16x32_bf16 v[66:69], v[174:177], v[206:209], v[66:69]
	s_setprio 0
	ds_read_b128 v[178:181], v163 offset:16384
	ds_read_b128 v[182:185], v163 offset:17408
	ds_read_b128 v[186:189], v163 offset:18432
	ds_read_b128 v[190:193], v163 offset:19456
	ds_read_b128 v[194:197], v163 offset:20480
	ds_read_b128 v[198:201], v163 offset:21504
	ds_read_b128 v[202:205], v163 offset:22528
	ds_read_b128 v[206:209], v163 offset:23552
	s_mov_b32 s83, m0
	s_mov_b32 m0, s19
	s_nop 0
	global_load_lds_dwordx4 v156, s[22:23]
	s_mov_b32 m0, s83
	s_add_u32 s86, s22, 0x4000
	s_mov_b32 s83, m0
	s_mov_b32 m0, s35
	s_nop 0
	global_load_lds_dwordx4 v158, s[22:23]
	s_mov_b32 m0, s83
	s_addc_u32 s87, s23, 0
	s_mov_b32 s83, m0
	s_mov_b32 m0, s36
	s_nop 0
	global_load_lds_dwordx4 v156, s[86:87]
	s_mov_b32 m0, s83
	s_nop 0
	s_mov_b32 s83, m0
	s_mov_b32 m0, s37
	s_nop 0
	global_load_lds_dwordx4 v158, s[86:87]
	s_mov_b32 m0, s83
	s_waitcnt vmcnt(4)
	s_waitcnt lgkmcnt(0)
	s_barrier
	s_setprio 1
	s_waitcnt lgkmcnt(7)
	v_mfma_f32_16x16x32_bf16 v[62:65], v[134:137], v[178:181], v[62:65]
	v_mfma_f32_16x16x32_bf16 v[58:61], v[142:145], v[178:181], v[58:61]
	s_waitcnt lgkmcnt(5)
	v_mfma_f32_16x16x32_bf16 v[54:57], v[134:137], v[186:189], v[54:57]
	v_mfma_f32_16x16x32_bf16 v[46:49], v[142:145], v[186:189], v[46:49]
	s_waitcnt lgkmcnt(3)
	v_mfma_f32_16x16x32_bf16 v[38:41], v[134:137], v[194:197], v[38:41]
	v_mfma_f32_16x16x32_bf16 v[30:33], v[142:145], v[194:197], v[30:33]
	s_waitcnt lgkmcnt(1)
	v_mfma_f32_16x16x32_bf16 v[22:25], v[134:137], v[202:205], v[22:25]
	v_mfma_f32_16x16x32_bf16 v[14:17], v[142:145], v[202:205], v[14:17]
	v_mfma_f32_16x16x32_bf16 v[62:65], v[138:141], v[182:185], v[62:65]
	v_mfma_f32_16x16x32_bf16 v[58:61], v[146:149], v[182:185], v[58:61]
	v_mfma_f32_16x16x32_bf16 v[54:57], v[138:141], v[190:193], v[54:57]
	v_mfma_f32_16x16x32_bf16 v[46:49], v[146:149], v[190:193], v[46:49]
	v_mfma_f32_16x16x32_bf16 v[38:41], v[138:141], v[198:201], v[38:41]
	v_mfma_f32_16x16x32_bf16 v[30:33], v[146:149], v[198:201], v[30:33]
	s_waitcnt lgkmcnt(0)
	v_mfma_f32_16x16x32_bf16 v[22:25], v[138:141], v[206:209], v[22:25]
	v_mfma_f32_16x16x32_bf16 v[14:17], v[146:149], v[206:209], v[14:17]
	s_setprio 0
	s_setprio 1
	v_mfma_f32_16x16x32_bf16 v[50:53], v[150:153], v[178:181], v[50:53]
	v_mfma_f32_16x16x32_bf16 v[42:45], v[170:173], v[178:181], v[42:45]
	v_mfma_f32_16x16x32_bf16 v[34:37], v[150:153], v[186:189], v[34:37]
	v_mfma_f32_16x16x32_bf16 v[26:29], v[170:173], v[186:189], v[26:29]
	v_mfma_f32_16x16x32_bf16 v[18:21], v[150:153], v[194:197], v[18:21]
	v_mfma_f32_16x16x32_bf16 v[10:13], v[170:173], v[194:197], v[10:13]
	v_mfma_f32_16x16x32_bf16 v[6:9], v[150:153], v[202:205], v[6:9]
	v_mfma_f32_16x16x32_bf16 v[2:5], v[170:173], v[202:205], v[2:5]
	v_mfma_f32_16x16x32_bf16 v[50:53], v[166:169], v[182:185], v[50:53]
	v_mfma_f32_16x16x32_bf16 v[42:45], v[174:177], v[182:185], v[42:45]
	v_mfma_f32_16x16x32_bf16 v[34:37], v[166:169], v[190:193], v[34:37]
	v_mfma_f32_16x16x32_bf16 v[26:29], v[174:177], v[190:193], v[26:29]
	v_mfma_f32_16x16x32_bf16 v[18:21], v[166:169], v[198:201], v[18:21]
	v_mfma_f32_16x16x32_bf16 v[10:13], v[174:177], v[198:201], v[10:13]
	s_setprio 2
	s_barrier
	v_mfma_f32_16x16x32_bf16 v[6:9], v[166:169], v[206:209], v[6:9]
	v_mfma_f32_16x16x32_bf16 v[2:5], v[174:177], v[206:209], v[2:5]
	s_setprio 0
	ds_read_b128 v[134:137], v164
	ds_read_b128 v[138:141], v164 offset:1024
	ds_read_b128 v[142:145], v164 offset:2048
	ds_read_b128 v[146:149], v164 offset:3072
	ds_read_b128 v[150:153], v165
	ds_read_b128 v[166:169], v165 offset:1024
	ds_read_b128 v[170:173], v165 offset:2048
	ds_read_b128 v[174:177], v165 offset:3072
	ds_read_b128 v[178:181], v163 offset:32768
	ds_read_b128 v[182:185], v163 offset:33792
	ds_read_b128 v[186:189], v163 offset:34816
	ds_read_b128 v[190:193], v163 offset:35840
	ds_read_b128 v[194:197], v163 offset:36864
	ds_read_b128 v[198:201], v163 offset:37888
	ds_read_b128 v[202:205], v163 offset:38912
	ds_read_b128 v[206:209], v163 offset:39936
	s_mov_b32 s83, m0
	s_mov_b32 m0, s34
	s_nop 0
	global_load_lds_dwordx4 v1, s[24:25]
	s_mov_b32 m0, s83
	s_nop 0
	s_mov_b32 s83, m0
	s_mov_b32 m0, s42
	s_nop 0
	global_load_lds_dwordx4 v157, s[24:25]
	s_mov_b32 m0, s83
	s_add_u32 s24, s24, 0x4000
	s_addc_u32 s25, s25, 0
	s_mov_b32 s83, m0
	s_mov_b32 m0, s43
	s_nop 0
	global_load_lds_dwordx4 v1, s[24:25]
	s_mov_b32 m0, s83
	s_nop 0
	s_mov_b32 s83, m0
	s_mov_b32 m0, s46
	s_nop 0
	global_load_lds_dwordx4 v157, s[24:25]
	s_mov_b32 m0, s83
	s_waitcnt vmcnt(8)
	s_waitcnt lgkmcnt(0)
	s_barrier
	s_setprio 1
	s_waitcnt lgkmcnt(7)
	v_mfma_f32_16x16x32_bf16 v[126:129], v[134:137], v[178:181], v[126:129]
	v_mfma_f32_16x16x32_bf16 v[122:125], v[142:145], v[178:181], v[122:125]
	s_waitcnt lgkmcnt(5)
	v_mfma_f32_16x16x32_bf16 v[118:121], v[134:137], v[186:189], v[118:121]
	v_mfma_f32_16x16x32_bf16 v[114:117], v[142:145], v[186:189], v[114:117]
	s_waitcnt lgkmcnt(3)
	v_mfma_f32_16x16x32_bf16 v[102:105], v[134:137], v[194:197], v[102:105]
	v_mfma_f32_16x16x32_bf16 v[94:97], v[142:145], v[194:197], v[94:97]
	s_waitcnt lgkmcnt(1)
	v_mfma_f32_16x16x32_bf16 v[86:89], v[134:137], v[202:205], v[86:89]
	v_mfma_f32_16x16x32_bf16 v[78:81], v[142:145], v[202:205], v[78:81]
	v_mfma_f32_16x16x32_bf16 v[126:129], v[138:141], v[182:185], v[126:129]
	v_mfma_f32_16x16x32_bf16 v[122:125], v[146:149], v[182:185], v[122:125]
	v_mfma_f32_16x16x32_bf16 v[118:121], v[138:141], v[190:193], v[118:121]
	v_mfma_f32_16x16x32_bf16 v[114:117], v[146:149], v[190:193], v[114:117]
	v_mfma_f32_16x16x32_bf16 v[102:105], v[138:141], v[198:201], v[102:105]
	v_mfma_f32_16x16x32_bf16 v[94:97], v[146:149], v[198:201], v[94:97]
	s_waitcnt lgkmcnt(0)
	v_mfma_f32_16x16x32_bf16 v[86:89], v[138:141], v[206:209], v[86:89]
	v_mfma_f32_16x16x32_bf16 v[78:81], v[146:149], v[206:209], v[78:81]
	s_setprio 0
	s_setprio 1
	v_mfma_f32_16x16x32_bf16 v[110:113], v[150:153], v[178:181], v[110:113]
	v_mfma_f32_16x16x32_bf16 v[106:109], v[170:173], v[178:181], v[106:109]
	v_mfma_f32_16x16x32_bf16 v[98:101], v[150:153], v[186:189], v[98:101]
	v_mfma_f32_16x16x32_bf16 v[90:93], v[170:173], v[186:189], v[90:93]
	v_mfma_f32_16x16x32_bf16 v[82:85], v[150:153], v[194:197], v[82:85]
	v_mfma_f32_16x16x32_bf16 v[74:77], v[170:173], v[194:197], v[74:77]
	v_mfma_f32_16x16x32_bf16 v[70:73], v[150:153], v[202:205], v[70:73]
	v_mfma_f32_16x16x32_bf16 v[66:69], v[170:173], v[202:205], v[66:69]
	v_mfma_f32_16x16x32_bf16 v[110:113], v[166:169], v[182:185], v[110:113]
	v_mfma_f32_16x16x32_bf16 v[106:109], v[174:177], v[182:185], v[106:109]
	v_mfma_f32_16x16x32_bf16 v[98:101], v[166:169], v[190:193], v[98:101]
	v_mfma_f32_16x16x32_bf16 v[90:93], v[174:177], v[190:193], v[90:93]
	v_mfma_f32_16x16x32_bf16 v[82:85], v[166:169], v[198:201], v[82:85]
	v_mfma_f32_16x16x32_bf16 v[74:77], v[174:177], v[198:201], v[74:77]
	s_setprio 2
	s_barrier
	v_mfma_f32_16x16x32_bf16 v[70:73], v[166:169], v[206:209], v[70:73]
	v_mfma_f32_16x16x32_bf16 v[66:69], v[174:177], v[206:209], v[66:69]
	s_setprio 0
	ds_read_b128 v[178:181], v163 offset:49152
	ds_read_b128 v[182:185], v163 offset:50176
	ds_read_b128 v[186:189], v163 offset:51200
	ds_read_b128 v[190:193], v163 offset:52224
	ds_read_b128 v[194:197], v163 offset:53248
	ds_read_b128 v[198:201], v163 offset:54272
	ds_read_b128 v[202:205], v163 offset:55296
	ds_read_b128 v[206:209], v163 offset:56320
	s_add_u32 s24, s22, 0x40000
	s_addc_u32 s25, s23, 0
	s_mov_b32 s83, m0
	s_mov_b32 m0, s47
	s_nop 0
	global_load_lds_dwordx4 v156, s[24:25]
	s_mov_b32 m0, s83
	s_add_u32 s22, s22, 0x44000
	s_mov_b32 s83, m0
	s_mov_b32 m0, s48
	s_nop 0
	global_load_lds_dwordx4 v158, s[24:25]
	s_mov_b32 m0, s83
	s_addc_u32 s23, s23, 0
	s_mov_b32 s24, m0
	s_mov_b32 m0, s49
	s_nop 0
	global_load_lds_dwordx4 v156, s[22:23]
	s_mov_b32 m0, s24
	s_nop 0
	s_mov_b32 s24, m0
	s_mov_b32 m0, s56
	s_nop 0
	global_load_lds_dwordx4 v158, s[22:23]
	s_mov_b32 m0, s24
	s_waitcnt vmcnt(4)
	s_waitcnt lgkmcnt(0)
	s_barrier
	s_setprio 1
	s_waitcnt lgkmcnt(7)
	v_mfma_f32_16x16x32_bf16 v[62:65], v[134:137], v[178:181], v[62:65]
	v_mfma_f32_16x16x32_bf16 v[58:61], v[142:145], v[178:181], v[58:61]
	s_waitcnt lgkmcnt(5)
	v_mfma_f32_16x16x32_bf16 v[54:57], v[134:137], v[186:189], v[54:57]
	v_mfma_f32_16x16x32_bf16 v[46:49], v[142:145], v[186:189], v[46:49]
	s_waitcnt lgkmcnt(3)
	v_mfma_f32_16x16x32_bf16 v[38:41], v[134:137], v[194:197], v[38:41]
	v_mfma_f32_16x16x32_bf16 v[30:33], v[142:145], v[194:197], v[30:33]
	s_waitcnt lgkmcnt(1)
	v_mfma_f32_16x16x32_bf16 v[22:25], v[134:137], v[202:205], v[22:25]
	v_mfma_f32_16x16x32_bf16 v[14:17], v[142:145], v[202:205], v[14:17]
	v_mfma_f32_16x16x32_bf16 v[62:65], v[138:141], v[182:185], v[62:65]
	v_mfma_f32_16x16x32_bf16 v[58:61], v[146:149], v[182:185], v[58:61]
	v_mfma_f32_16x16x32_bf16 v[54:57], v[138:141], v[190:193], v[54:57]
	v_mfma_f32_16x16x32_bf16 v[46:49], v[146:149], v[190:193], v[46:49]
	v_mfma_f32_16x16x32_bf16 v[38:41], v[138:141], v[198:201], v[38:41]
	v_mfma_f32_16x16x32_bf16 v[30:33], v[146:149], v[198:201], v[30:33]
	s_waitcnt lgkmcnt(0)
	v_mfma_f32_16x16x32_bf16 v[22:25], v[138:141], v[206:209], v[22:25]
	v_mfma_f32_16x16x32_bf16 v[14:17], v[146:149], v[206:209], v[14:17]
	s_setprio 0
	s_setprio 1
	v_mfma_f32_16x16x32_bf16 v[50:53], v[150:153], v[178:181], v[50:53]
	v_mfma_f32_16x16x32_bf16 v[42:45], v[170:173], v[178:181], v[42:45]
	v_mfma_f32_16x16x32_bf16 v[34:37], v[150:153], v[186:189], v[34:37]
	v_mfma_f32_16x16x32_bf16 v[26:29], v[170:173], v[186:189], v[26:29]
	v_mfma_f32_16x16x32_bf16 v[18:21], v[150:153], v[194:197], v[18:21]
	v_mfma_f32_16x16x32_bf16 v[10:13], v[170:173], v[194:197], v[10:13]
	v_mfma_f32_16x16x32_bf16 v[6:9], v[150:153], v[202:205], v[6:9]
	v_mfma_f32_16x16x32_bf16 v[2:5], v[170:173], v[202:205], v[2:5]
	v_mfma_f32_16x16x32_bf16 v[50:53], v[166:169], v[182:185], v[50:53]
	v_mfma_f32_16x16x32_bf16 v[42:45], v[174:177], v[182:185], v[42:45]
	v_mfma_f32_16x16x32_bf16 v[34:37], v[166:169], v[190:193], v[34:37]
	v_mfma_f32_16x16x32_bf16 v[26:29], v[174:177], v[190:193], v[26:29]
	v_mfma_f32_16x16x32_bf16 v[18:21], v[166:169], v[198:201], v[18:21]
	v_mfma_f32_16x16x32_bf16 v[10:13], v[174:177], v[198:201], v[10:13]
	s_setprio 2
	s_barrier
	v_mfma_f32_16x16x32_bf16 v[6:9], v[166:169], v[206:209], v[6:9]
	v_mfma_f32_16x16x32_bf16 v[2:5], v[174:177], v[206:209], v[2:5]
	s_setprio 0
	s_add_i32 s82, s82, 2
	s_add_u32 s78, s78, 0x80000
	s_addc_u32 s79, s79, 0
	s_add_u32 s20, s20, 0x400000
	s_addc_u32 s21, s21, 0
	s_add_u32 s80, s80, 0x400000
	s_addc_u32 s81, s81, 0
	s_cmpk_gt_u32 s82, 0x53
	s_cbranch_scc0 .LBB0_473
	s_and_b64 vcc, exec, s[8:9]
	s_cbranch_vccz .LBB0_476
	s_barrier

.LBB0_654:
	ds_read_b128 v[130:133], v161
	ds_read_b128 v[138:141], v161 offset:1024
	ds_read_b128 v[142:145], v161 offset:2048
	ds_read_b128 v[146:149], v161 offset:3072
	ds_read_b128 v[150:153], v162
	ds_read_b128 v[168:171], v162 offset:1024
	ds_read_b128 v[172:175], v162 offset:2048
	ds_read_b128 v[176:179], v162 offset:3072
	s_cmp_eq_u32 s74, 28
	s_cselect_b32 s11, s21, s31
	s_cselect_b32 s10, s23, s30
	s_cselect_b32 s29, s7, s73
	s_cselect_b32 s28, s9, s33
	ds_read_b128 v[180:183], v163
	ds_read_b128 v[184:187], v163 offset:1024
	ds_read_b128 v[188:191], v163 offset:2048
	ds_read_b128 v[192:195], v163 offset:3072
	ds_read_b128 v[196:199], v163 offset:4096
	ds_read_b128 v[200:203], v163 offset:5120
	ds_read_b128 v[204:207], v163 offset:6144
	ds_read_b128 v[208:211], v163 offset:7168
	s_add_u32 s76, s4, 0xfff80000
	s_addc_u32 s77, s5, -1
	s_mov_b32 s75, m0
	s_mov_b32 m0, s80
	s_nop 0
	global_load_lds_dwordx4 v1, s[76:77]
	s_mov_b32 m0, s75
	s_nop 0
	s_mov_b32 s75, m0
	s_mov_b32 m0, s82
	s_nop 0
	global_load_lds_dwordx4 v157, s[76:77]
	s_mov_b32 m0, s75
	s_nop 0
	s_mov_b32 s75, m0
	s_mov_b32 m0, s81
	s_nop 0
	global_load_lds_dwordx4 v1, s[4:5]
	s_mov_b32 m0, s75
	s_nop 0
	s_mov_b32 s75, m0
	s_mov_b32 m0, s83
	s_nop 0
	global_load_lds_dwordx4 v157, s[4:5]
	s_mov_b32 m0, s75
	s_waitcnt vmcnt(8)
	s_waitcnt lgkmcnt(0)
	s_barrier
	s_setprio 1
	s_waitcnt lgkmcnt(7)
	v_mfma_f32_16x16x32_bf16 v[126:129], v[130:133], v[180:183], v[126:129]
	v_mfma_f32_16x16x32_bf16 v[122:125], v[142:145], v[180:183], v[122:125]
	s_waitcnt lgkmcnt(5)
	v_mfma_f32_16x16x32_bf16 v[110:113], v[130:133], v[188:191], v[110:113]
	v_mfma_f32_16x16x32_bf16 v[106:109], v[142:145], v[188:191], v[106:109]
	s_waitcnt lgkmcnt(3)
	v_mfma_f32_16x16x32_bf16 v[94:97], v[130:133], v[196:199], v[94:97]
	v_mfma_f32_16x16x32_bf16 v[90:93], v[142:145], v[196:199], v[90:93]
	s_waitcnt lgkmcnt(1)
	v_mfma_f32_16x16x32_bf16 v[78:81], v[130:133], v[204:207], v[78:81]
	v_mfma_f32_16x16x32_bf16 v[74:77], v[142:145], v[204:207], v[74:77]
	v_mfma_f32_16x16x32_bf16 v[126:129], v[138:141], v[184:187], v[126:129]
	v_mfma_f32_16x16x32_bf16 v[122:125], v[146:149], v[184:187], v[122:125]
	v_mfma_f32_16x16x32_bf16 v[110:113], v[138:141], v[192:195], v[110:113]
	v_mfma_f32_16x16x32_bf16 v[106:109], v[146:149], v[192:195], v[106:109]
	v_mfma_f32_16x16x32_bf16 v[94:97], v[138:141], v[200:203], v[94:97]
	v_mfma_f32_16x16x32_bf16 v[90:93], v[146:149], v[200:203], v[90:93]
	s_waitcnt lgkmcnt(0)
	v_mfma_f32_16x16x32_bf16 v[78:81], v[138:141], v[208:211], v[78:81]
	v_mfma_f32_16x16x32_bf16 v[74:77], v[146:149], v[208:211], v[74:77]
	s_setprio 0
	s_setprio 1
	v_mfma_f32_16x16x32_bf16 v[118:121], v[150:153], v[180:183], v[118:121]
	v_mfma_f32_16x16x32_bf16 v[114:117], v[172:175], v[180:183], v[114:117]
	v_mfma_f32_16x16x32_bf16 v[102:105], v[150:153], v[188:191], v[102:105]
	v_mfma_f32_16x16x32_bf16 v[98:101], v[172:175], v[188:191], v[98:101]
	v_mfma_f32_16x16x32_bf16 v[86:89], v[150:153], v[196:199], v[86:89]
	v_mfma_f32_16x16x32_bf16 v[82:85], v[172:175], v[196:199], v[82:85]
	v_mfma_f32_16x16x32_bf16 v[70:73], v[150:153], v[204:207], v[70:73]
	v_mfma_f32_16x16x32_bf16 v[66:69], v[172:175], v[204:207], v[66:69]
	v_mfma_f32_16x16x32_bf16 v[118:121], v[168:171], v[184:187], v[118:121]
	v_mfma_f32_16x16x32_bf16 v[114:117], v[176:179], v[184:187], v[114:117]
	v_mfma_f32_16x16x32_bf16 v[102:105], v[168:171], v[192:195], v[102:105]
	v_mfma_f32_16x16x32_bf16 v[98:101], v[176:179], v[192:195], v[98:101]
	v_mfma_f32_16x16x32_bf16 v[86:89], v[168:171], v[200:203], v[86:89]
	v_mfma_f32_16x16x32_bf16 v[82:85], v[176:179], v[200:203], v[82:85]
	s_setprio 2
	s_barrier
	v_mfma_f32_16x16x32_bf16 v[70:73], v[168:171], v[208:211], v[70:73]
	v_mfma_f32_16x16x32_bf16 v[66:69], v[176:179], v[208:211], v[66:69]
	s_setprio 0
	ds_read_b128 v[180:183], v163 offset:16384
	ds_read_b128 v[184:187], v163 offset:17408
	ds_read_b128 v[188:191], v163 offset:18432
	ds_read_b128 v[192:195], v163 offset:19456
	ds_read_b128 v[196:199], v163 offset:20480
	ds_read_b128 v[200:203], v163 offset:21504
	ds_read_b128 v[204:207], v163 offset:22528
	ds_read_b128 v[208:211], v163 offset:23552
	s_mov_b32 s75, m0
	s_mov_b32 m0, s43
	s_nop 0
	global_load_lds_dwordx4 v156, s[10:11]
	s_mov_b32 m0, s75
	s_add_u32 s76, s10, 0x80000
	s_mov_b32 s75, m0
	s_mov_b32 m0, s46
	s_nop 0
	global_load_lds_dwordx4 v158, s[10:11]
	s_mov_b32 m0, s75
	s_addc_u32 s77, s11, 0
	s_mov_b32 s75, m0
	s_mov_b32 m0, s47
	s_nop 0
	global_load_lds_dwordx4 v156, s[76:77]
	s_mov_b32 m0, s75
	s_nop 0
	s_mov_b32 s75, m0
	s_mov_b32 m0, s48
	s_nop 0
	global_load_lds_dwordx4 v158, s[76:77]
	s_mov_b32 m0, s75
	s_waitcnt vmcnt(4)
	s_waitcnt lgkmcnt(0)
	s_barrier
	s_setprio 1
	s_waitcnt lgkmcnt(7)
	v_mfma_f32_16x16x32_bf16 v[62:65], v[130:133], v[180:183], v[62:65]
	v_mfma_f32_16x16x32_bf16 v[58:61], v[142:145], v[180:183], v[58:61]
	s_waitcnt lgkmcnt(5)
	v_mfma_f32_16x16x32_bf16 v[46:49], v[130:133], v[188:191], v[46:49]
	v_mfma_f32_16x16x32_bf16 v[42:45], v[142:145], v[188:191], v[42:45]
	s_waitcnt lgkmcnt(3)
	v_mfma_f32_16x16x32_bf16 v[30:33], v[130:133], v[196:199], v[30:33]
	v_mfma_f32_16x16x32_bf16 v[26:29], v[142:145], v[196:199], v[26:29]
	s_waitcnt lgkmcnt(1)
	v_mfma_f32_16x16x32_bf16 v[14:17], v[130:133], v[204:207], v[14:17]
	v_mfma_f32_16x16x32_bf16 v[10:13], v[142:145], v[204:207], v[10:13]
	v_mfma_f32_16x16x32_bf16 v[62:65], v[138:141], v[184:187], v[62:65]
	v_mfma_f32_16x16x32_bf16 v[58:61], v[146:149], v[184:187], v[58:61]
	v_mfma_f32_16x16x32_bf16 v[46:49], v[138:141], v[192:195], v[46:49]
	v_mfma_f32_16x16x32_bf16 v[42:45], v[146:149], v[192:195], v[42:45]
	v_mfma_f32_16x16x32_bf16 v[30:33], v[138:141], v[200:203], v[30:33]
	v_mfma_f32_16x16x32_bf16 v[26:29], v[146:149], v[200:203], v[26:29]
	s_waitcnt lgkmcnt(0)
	v_mfma_f32_16x16x32_bf16 v[14:17], v[138:141], v[208:211], v[14:17]
	v_mfma_f32_16x16x32_bf16 v[10:13], v[146:149], v[208:211], v[10:13]
	s_setprio 0
	s_setprio 1
	v_mfma_f32_16x16x32_bf16 v[54:57], v[150:153], v[180:183], v[54:57]
	v_mfma_f32_16x16x32_bf16 v[50:53], v[172:175], v[180:183], v[50:53]
	v_mfma_f32_16x16x32_bf16 v[38:41], v[150:153], v[188:191], v[38:41]
	v_mfma_f32_16x16x32_bf16 v[34:37], v[172:175], v[188:191], v[34:37]
	v_mfma_f32_16x16x32_bf16 v[22:25], v[150:153], v[196:199], v[22:25]
	v_mfma_f32_16x16x32_bf16 v[18:21], v[172:175], v[196:199], v[18:21]
	v_mfma_f32_16x16x32_bf16 v[6:9], v[150:153], v[204:207], v[6:9]
	v_mfma_f32_16x16x32_bf16 v[2:5], v[172:175], v[204:207], v[2:5]
	v_mfma_f32_16x16x32_bf16 v[54:57], v[168:171], v[184:187], v[54:57]
	v_mfma_f32_16x16x32_bf16 v[50:53], v[176:179], v[184:187], v[50:53]
	v_mfma_f32_16x16x32_bf16 v[38:41], v[168:171], v[192:195], v[38:41]
	v_mfma_f32_16x16x32_bf16 v[34:37], v[176:179], v[192:195], v[34:37]
	v_mfma_f32_16x16x32_bf16 v[22:25], v[168:171], v[200:203], v[22:25]
	v_mfma_f32_16x16x32_bf16 v[18:21], v[176:179], v[200:203], v[18:21]
	s_setprio 2
	s_barrier
	v_mfma_f32_16x16x32_bf16 v[6:9], v[168:171], v[208:211], v[6:9]
	v_mfma_f32_16x16x32_bf16 v[2:5], v[176:179], v[208:211], v[2:5]
	s_setprio 0
	ds_read_b128 v[130:133], v164
	ds_read_b128 v[138:141], v164 offset:1024
	ds_read_b128 v[142:145], v164 offset:2048
	ds_read_b128 v[146:149], v164 offset:3072
	ds_read_b128 v[150:153], v165
	ds_read_b128 v[168:171], v165 offset:1024
	ds_read_b128 v[172:175], v165 offset:2048
	ds_read_b128 v[176:179], v165 offset:3072
	ds_read_b128 v[180:183], v163 offset:32768
	ds_read_b128 v[184:187], v163 offset:33792
	ds_read_b128 v[188:191], v163 offset:34816
	ds_read_b128 v[192:195], v163 offset:35840
	ds_read_b128 v[196:199], v163 offset:36864
	ds_read_b128 v[200:203], v163 offset:37888
	ds_read_b128 v[204:207], v163 offset:38912
	ds_read_b128 v[208:211], v163 offset:39936
	s_mov_b32 s75, m0
	s_mov_b32 m0, s42
	s_nop 0
	global_load_lds_dwordx4 v1, s[28:29]
	s_mov_b32 m0, s75
	s_nop 0
	s_mov_b32 s75, m0
	s_mov_b32 m0, s49
	s_nop 0
	global_load_lds_dwordx4 v157, s[28:29]
	s_mov_b32 m0, s75
	s_add_u32 s28, s28, 0x80000
	s_addc_u32 s29, s29, 0
	s_mov_b32 s75, m0
	s_mov_b32 m0, s56
	s_nop 0
	global_load_lds_dwordx4 v1, s[28:29]
	s_mov_b32 m0, s75
	s_nop 0
	s_mov_b32 s75, m0
	s_mov_b32 m0, s57
	s_nop 0
	global_load_lds_dwordx4 v157, s[28:29]
	s_mov_b32 m0, s75
	s_waitcnt vmcnt(8)
	s_waitcnt lgkmcnt(0)
	s_barrier
	s_setprio 1
	s_waitcnt lgkmcnt(7)
	v_mfma_f32_16x16x32_bf16 v[126:129], v[130:133], v[180:183], v[126:129]
	v_mfma_f32_16x16x32_bf16 v[122:125], v[142:145], v[180:183], v[122:125]
	s_waitcnt lgkmcnt(5)
	v_mfma_f32_16x16x32_bf16 v[110:113], v[130:133], v[188:191], v[110:113]
	v_mfma_f32_16x16x32_bf16 v[106:109], v[142:145], v[188:191], v[106:109]
	s_waitcnt lgkmcnt(3)
	v_mfma_f32_16x16x32_bf16 v[94:97], v[130:133], v[196:199], v[94:97]
	v_mfma_f32_16x16x32_bf16 v[90:93], v[142:145], v[196:199], v[90:93]
	s_waitcnt lgkmcnt(1)
	v_mfma_f32_16x16x32_bf16 v[78:81], v[130:133], v[204:207], v[78:81]
	v_mfma_f32_16x16x32_bf16 v[74:77], v[142:145], v[204:207], v[74:77]
	v_mfma_f32_16x16x32_bf16 v[126:129], v[138:141], v[184:187], v[126:129]
	v_mfma_f32_16x16x32_bf16 v[122:125], v[146:149], v[184:187], v[122:125]
	v_mfma_f32_16x16x32_bf16 v[110:113], v[138:141], v[192:195], v[110:113]
	v_mfma_f32_16x16x32_bf16 v[106:109], v[146:149], v[192:195], v[106:109]
	v_mfma_f32_16x16x32_bf16 v[94:97], v[138:141], v[200:203], v[94:97]
	v_mfma_f32_16x16x32_bf16 v[90:93], v[146:149], v[200:203], v[90:93]
	s_waitcnt lgkmcnt(0)
	v_mfma_f32_16x16x32_bf16 v[78:81], v[138:141], v[208:211], v[78:81]
	v_mfma_f32_16x16x32_bf16 v[74:77], v[146:149], v[208:211], v[74:77]
	s_setprio 0
	s_setprio 1
	v_mfma_f32_16x16x32_bf16 v[118:121], v[150:153], v[180:183], v[118:121]
	v_mfma_f32_16x16x32_bf16 v[114:117], v[172:175], v[180:183], v[114:117]
	v_mfma_f32_16x16x32_bf16 v[102:105], v[150:153], v[188:191], v[102:105]
	v_mfma_f32_16x16x32_bf16 v[98:101], v[172:175], v[188:191], v[98:101]
	v_mfma_f32_16x16x32_bf16 v[86:89], v[150:153], v[196:199], v[86:89]
	v_mfma_f32_16x16x32_bf16 v[82:85], v[172:175], v[196:199], v[82:85]
	v_mfma_f32_16x16x32_bf16 v[70:73], v[150:153], v[204:207], v[70:73]
	v_mfma_f32_16x16x32_bf16 v[66:69], v[172:175], v[204:207], v[66:69]
	v_mfma_f32_16x16x32_bf16 v[118:121], v[168:171], v[184:187], v[118:121]
	v_mfma_f32_16x16x32_bf16 v[114:117], v[176:179], v[184:187], v[114:117]
	v_mfma_f32_16x16x32_bf16 v[102:105], v[168:171], v[192:195], v[102:105]
	v_mfma_f32_16x16x32_bf16 v[98:101], v[176:179], v[192:195], v[98:101]
	v_mfma_f32_16x16x32_bf16 v[86:89], v[168:171], v[200:203], v[86:89]
	v_mfma_f32_16x16x32_bf16 v[82:85], v[176:179], v[200:203], v[82:85]
	s_setprio 2
	s_barrier
	v_mfma_f32_16x16x32_bf16 v[70:73], v[168:171], v[208:211], v[70:73]
	v_mfma_f32_16x16x32_bf16 v[66:69], v[176:179], v[208:211], v[66:69]
	s_setprio 0
	ds_read_b128 v[180:183], v163 offset:49152
	ds_read_b128 v[184:187], v163 offset:50176
	ds_read_b128 v[188:191], v163 offset:51200
	ds_read_b128 v[192:195], v163 offset:52224
	ds_read_b128 v[196:199], v163 offset:53248
	ds_read_b128 v[200:203], v163 offset:54272
	ds_read_b128 v[204:207], v163 offset:55296
	ds_read_b128 v[208:211], v163 offset:56320
	s_add_u32 s28, s10, 0x80
	s_addc_u32 s29, s11, 0
	s_mov_b32 s75, m0
	s_mov_b32 m0, s64
	s_nop 0
	global_load_lds_dwordx4 v156, s[28:29]
	s_mov_b32 m0, s75
	s_add_u32 s10, s10, 0x80080
	s_mov_b32 s75, m0
	s_mov_b32 m0, s65
	s_nop 0
	global_load_lds_dwordx4 v158, s[28:29]
	s_mov_b32 m0, s75
	s_addc_u32 s11, s11, 0
	s_mov_b32 s28, m0
	s_mov_b32 m0, s66
	s_nop 0
	global_load_lds_dwordx4 v156, s[10:11]
	s_mov_b32 m0, s28
	s_nop 0
	s_mov_b32 s28, m0
	s_mov_b32 m0, s67
	s_nop 0
	global_load_lds_dwordx4 v158, s[10:11]
	s_mov_b32 m0, s28
	s_waitcnt vmcnt(4)
	s_waitcnt lgkmcnt(0)
	s_barrier
	s_setprio 1
	s_waitcnt lgkmcnt(7)
	v_mfma_f32_16x16x32_bf16 v[62:65], v[130:133], v[180:183], v[62:65]
	v_mfma_f32_16x16x32_bf16 v[58:61], v[142:145], v[180:183], v[58:61]
	s_waitcnt lgkmcnt(5)
	v_mfma_f32_16x16x32_bf16 v[46:49], v[130:133], v[188:191], v[46:49]
	v_mfma_f32_16x16x32_bf16 v[42:45], v[142:145], v[188:191], v[42:45]
	s_waitcnt lgkmcnt(3)
	v_mfma_f32_16x16x32_bf16 v[30:33], v[130:133], v[196:199], v[30:33]
	v_mfma_f32_16x16x32_bf16 v[26:29], v[142:145], v[196:199], v[26:29]
	s_waitcnt lgkmcnt(1)
	v_mfma_f32_16x16x32_bf16 v[14:17], v[130:133], v[204:207], v[14:17]
	v_mfma_f32_16x16x32_bf16 v[10:13], v[142:145], v[204:207], v[10:13]
	v_mfma_f32_16x16x32_bf16 v[62:65], v[138:141], v[184:187], v[62:65]
	v_mfma_f32_16x16x32_bf16 v[58:61], v[146:149], v[184:187], v[58:61]
	v_mfma_f32_16x16x32_bf16 v[46:49], v[138:141], v[192:195], v[46:49]
	v_mfma_f32_16x16x32_bf16 v[42:45], v[146:149], v[192:195], v[42:45]
	v_mfma_f32_16x16x32_bf16 v[30:33], v[138:141], v[200:203], v[30:33]
	v_mfma_f32_16x16x32_bf16 v[26:29], v[146:149], v[200:203], v[26:29]
	s_waitcnt lgkmcnt(0)
	v_mfma_f32_16x16x32_bf16 v[14:17], v[138:141], v[208:211], v[14:17]
	v_mfma_f32_16x16x32_bf16 v[10:13], v[146:149], v[208:211], v[10:13]
	s_setprio 0
	s_setprio 1
	v_mfma_f32_16x16x32_bf16 v[54:57], v[150:153], v[180:183], v[54:57]
	v_mfma_f32_16x16x32_bf16 v[50:53], v[172:175], v[180:183], v[50:53]
	v_mfma_f32_16x16x32_bf16 v[38:41], v[150:153], v[188:191], v[38:41]
	v_mfma_f32_16x16x32_bf16 v[34:37], v[172:175], v[188:191], v[34:37]
	v_mfma_f32_16x16x32_bf16 v[22:25], v[150:153], v[196:199], v[22:25]
	v_mfma_f32_16x16x32_bf16 v[18:21], v[172:175], v[196:199], v[18:21]
	v_mfma_f32_16x16x32_bf16 v[6:9], v[150:153], v[204:207], v[6:9]
	v_mfma_f32_16x16x32_bf16 v[2:5], v[172:175], v[204:207], v[2:5]
	v_mfma_f32_16x16x32_bf16 v[54:57], v[168:171], v[184:187], v[54:57]
	v_mfma_f32_16x16x32_bf16 v[50:53], v[176:179], v[184:187], v[50:53]
	v_mfma_f32_16x16x32_bf16 v[38:41], v[168:171], v[192:195], v[38:41]
	v_mfma_f32_16x16x32_bf16 v[34:37], v[176:179], v[192:195], v[34:37]
	v_mfma_f32_16x16x32_bf16 v[22:25], v[168:171], v[200:203], v[22:25]
	v_mfma_f32_16x16x32_bf16 v[18:21], v[176:179], v[200:203], v[18:21]
	s_setprio 2
	s_barrier
	v_mfma_f32_16x16x32_bf16 v[6:9], v[168:171], v[208:211], v[6:9]
	v_mfma_f32_16x16x32_bf16 v[2:5], v[176:179], v[208:211], v[2:5]
	s_setprio 0
	s_add_i32 s74, s74, 2
	s_add_u32 s30, s30, 0x100
	s_addc_u32 s31, s31, 0
	s_add_u32 s4, s4, 0x100
	s_addc_u32 s5, s5, 0
	s_add_u32 s33, s33, 0x100
	s_addc_u32 s73, s73, 0
	s_cmp_gt_u32 s74, 29
	s_cbranch_scc0 .LBB0_654
	s_and_b64 vcc, exec, s[18:19]
	s_cbranch_vccz .LBB0_657
	s_barrier

.LBB0_1053:
	ds_read_b128 v[130:133], v181
	ds_read_b128 v[134:137], v181 offset:1024
	ds_read_b128 v[138:141], v181 offset:2048
	ds_read_b128 v[142:145], v181 offset:3072
	ds_read_b128 v[146:149], v182
	ds_read_b128 v[150:153], v182 offset:1024
	ds_read_b128 v[154:157], v182 offset:2048
	ds_read_b128 v[158:161], v182 offset:3072
	s_cmp_eq_u32 s78, 28
	s_cselect_b32 s23, s11, s75
	s_cselect_b32 s22, s73, s74
	s_cselect_b32 s25, s13, s77
	s_cselect_b32 s24, s67, s76
	ds_read_b128 v[166:169], v183
	ds_read_b128 v[170:173], v183 offset:1024
	ds_read_b128 v[186:189], v183 offset:2048
	ds_read_b128 v[190:193], v183 offset:3072
	ds_read_b128 v[194:197], v183 offset:4096
	ds_read_b128 v[198:201], v183 offset:5120
	ds_read_b128 v[202:205], v183 offset:6144
	ds_read_b128 v[206:209], v183 offset:7168
	s_add_u32 s80, s20, 0xfff80000
	s_addc_u32 s81, s21, -1
	s_mov_b32 s79, m0
	s_mov_b32 m0, s58
	s_nop 0
	global_load_lds_dwordx4 v1, s[80:81]
	s_mov_b32 m0, s79
	s_nop 0
	s_mov_b32 s79, m0
	s_mov_b32 m0, s64
	s_nop 0
	global_load_lds_dwordx4 v177, s[80:81]
	s_mov_b32 m0, s79
	s_nop 0
	s_mov_b32 s79, m0
	s_mov_b32 m0, s59
	s_nop 0
	global_load_lds_dwordx4 v1, s[20:21]
	s_mov_b32 m0, s79
	s_nop 0
	s_mov_b32 s79, m0
	s_mov_b32 m0, s65
	s_nop 0
	global_load_lds_dwordx4 v177, s[20:21]
	s_mov_b32 m0, s79
	s_waitcnt vmcnt(8)
	s_waitcnt lgkmcnt(0)
	s_barrier
	s_setprio 1
	s_waitcnt lgkmcnt(7)
	v_mfma_f32_16x16x32_bf16 v[126:129], v[130:133], v[166:169], v[126:129]
	v_mfma_f32_16x16x32_bf16 v[122:125], v[138:141], v[166:169], v[122:125]
	s_waitcnt lgkmcnt(5)
	v_mfma_f32_16x16x32_bf16 v[118:121], v[130:133], v[186:189], v[118:121]
	v_mfma_f32_16x16x32_bf16 v[114:117], v[138:141], v[186:189], v[114:117]
	s_waitcnt lgkmcnt(3)
	v_mfma_f32_16x16x32_bf16 v[94:97], v[130:133], v[194:197], v[94:97]
	v_mfma_f32_16x16x32_bf16 v[90:93], v[138:141], v[194:197], v[90:93]
	s_waitcnt lgkmcnt(1)
	v_mfma_f32_16x16x32_bf16 v[86:89], v[130:133], v[202:205], v[86:89]
	v_mfma_f32_16x16x32_bf16 v[78:81], v[138:141], v[202:205], v[78:81]
	v_mfma_f32_16x16x32_bf16 v[126:129], v[134:137], v[170:173], v[126:129]
	v_mfma_f32_16x16x32_bf16 v[122:125], v[142:145], v[170:173], v[122:125]
	v_mfma_f32_16x16x32_bf16 v[118:121], v[134:137], v[190:193], v[118:121]
	v_mfma_f32_16x16x32_bf16 v[114:117], v[142:145], v[190:193], v[114:117]
	v_mfma_f32_16x16x32_bf16 v[94:97], v[134:137], v[198:201], v[94:97]
	v_mfma_f32_16x16x32_bf16 v[90:93], v[142:145], v[198:201], v[90:93]
	s_waitcnt lgkmcnt(0)
	v_mfma_f32_16x16x32_bf16 v[86:89], v[134:137], v[206:209], v[86:89]
	v_mfma_f32_16x16x32_bf16 v[78:81], v[142:145], v[206:209], v[78:81]
	s_setprio 0
	s_setprio 1
	v_mfma_f32_16x16x32_bf16 v[110:113], v[146:149], v[166:169], v[110:113]
	v_mfma_f32_16x16x32_bf16 v[106:109], v[154:157], v[166:169], v[106:109]
	v_mfma_f32_16x16x32_bf16 v[102:105], v[146:149], v[186:189], v[102:105]
	v_mfma_f32_16x16x32_bf16 v[98:101], v[154:157], v[186:189], v[98:101]
	v_mfma_f32_16x16x32_bf16 v[82:85], v[146:149], v[194:197], v[82:85]
	v_mfma_f32_16x16x32_bf16 v[74:77], v[154:157], v[194:197], v[74:77]
	v_mfma_f32_16x16x32_bf16 v[70:73], v[146:149], v[202:205], v[70:73]
	v_mfma_f32_16x16x32_bf16 v[66:69], v[154:157], v[202:205], v[66:69]
	v_mfma_f32_16x16x32_bf16 v[110:113], v[150:153], v[170:173], v[110:113]
	v_mfma_f32_16x16x32_bf16 v[106:109], v[158:161], v[170:173], v[106:109]
	v_mfma_f32_16x16x32_bf16 v[102:105], v[150:153], v[190:193], v[102:105]
	v_mfma_f32_16x16x32_bf16 v[98:101], v[158:161], v[190:193], v[98:101]
	v_mfma_f32_16x16x32_bf16 v[82:85], v[150:153], v[198:201], v[82:85]
	v_mfma_f32_16x16x32_bf16 v[74:77], v[158:161], v[198:201], v[74:77]
	s_setprio 2
	s_barrier
	v_mfma_f32_16x16x32_bf16 v[70:73], v[150:153], v[206:209], v[70:73]
	v_mfma_f32_16x16x32_bf16 v[66:69], v[158:161], v[206:209], v[66:69]
	s_setprio 0
	ds_read_b128 v[166:169], v183 offset:16384
	ds_read_b128 v[170:173], v183 offset:17408
	ds_read_b128 v[186:189], v183 offset:18432
	ds_read_b128 v[190:193], v183 offset:19456
	ds_read_b128 v[194:197], v183 offset:20480
	ds_read_b128 v[198:201], v183 offset:21504
	ds_read_b128 v[202:205], v183 offset:22528
	ds_read_b128 v[206:209], v183 offset:23552
	s_mov_b32 s79, m0
	s_mov_b32 m0, s35
	s_nop 0
	global_load_lds_dwordx4 v176, s[22:23]
	s_mov_b32 m0, s79
	s_add_u32 s80, s22, 0x80000
	s_mov_b32 s79, m0
	s_mov_b32 m0, s36
	s_nop 0
	global_load_lds_dwordx4 v178, s[22:23]
	s_mov_b32 m0, s79
	s_addc_u32 s81, s23, 0
	s_mov_b32 s79, m0
	s_mov_b32 m0, s37
	s_nop 0
	global_load_lds_dwordx4 v176, s[80:81]
	s_mov_b32 m0, s79
	s_nop 0
	s_mov_b32 s79, m0
	s_mov_b32 m0, s40
	s_nop 0
	global_load_lds_dwordx4 v178, s[80:81]
	s_mov_b32 m0, s79
	s_waitcnt vmcnt(4)
	s_waitcnt lgkmcnt(0)
	s_barrier
	s_setprio 1
	s_waitcnt lgkmcnt(7)
	v_mfma_f32_16x16x32_bf16 v[62:65], v[130:133], v[166:169], v[62:65]
	v_mfma_f32_16x16x32_bf16 v[58:61], v[138:141], v[166:169], v[58:61]
	s_waitcnt lgkmcnt(5)
	v_mfma_f32_16x16x32_bf16 v[46:49], v[130:133], v[186:189], v[46:49]
	v_mfma_f32_16x16x32_bf16 v[42:45], v[138:141], v[186:189], v[42:45]
	s_waitcnt lgkmcnt(3)
	v_mfma_f32_16x16x32_bf16 v[30:33], v[130:133], v[194:197], v[30:33]
	v_mfma_f32_16x16x32_bf16 v[26:29], v[138:141], v[194:197], v[26:29]
	s_waitcnt lgkmcnt(1)
	v_mfma_f32_16x16x32_bf16 v[14:17], v[130:133], v[202:205], v[14:17]
	v_mfma_f32_16x16x32_bf16 v[10:13], v[138:141], v[202:205], v[10:13]
	v_mfma_f32_16x16x32_bf16 v[62:65], v[134:137], v[170:173], v[62:65]
	v_mfma_f32_16x16x32_bf16 v[58:61], v[142:145], v[170:173], v[58:61]
	v_mfma_f32_16x16x32_bf16 v[46:49], v[134:137], v[190:193], v[46:49]
	v_mfma_f32_16x16x32_bf16 v[42:45], v[142:145], v[190:193], v[42:45]
	v_mfma_f32_16x16x32_bf16 v[30:33], v[134:137], v[198:201], v[30:33]
	v_mfma_f32_16x16x32_bf16 v[26:29], v[142:145], v[198:201], v[26:29]
	s_waitcnt lgkmcnt(0)
	v_mfma_f32_16x16x32_bf16 v[14:17], v[134:137], v[206:209], v[14:17]
	v_mfma_f32_16x16x32_bf16 v[10:13], v[142:145], v[206:209], v[10:13]
	s_setprio 0
	s_setprio 1
	v_mfma_f32_16x16x32_bf16 v[54:57], v[146:149], v[166:169], v[54:57]
	v_mfma_f32_16x16x32_bf16 v[50:53], v[154:157], v[166:169], v[50:53]
	v_mfma_f32_16x16x32_bf16 v[38:41], v[146:149], v[186:189], v[38:41]
	v_mfma_f32_16x16x32_bf16 v[34:37], v[154:157], v[186:189], v[34:37]
	v_mfma_f32_16x16x32_bf16 v[22:25], v[146:149], v[194:197], v[22:25]
	v_mfma_f32_16x16x32_bf16 v[18:21], v[154:157], v[194:197], v[18:21]
	v_mfma_f32_16x16x32_bf16 v[6:9], v[146:149], v[202:205], v[6:9]
	v_mfma_f32_16x16x32_bf16 v[2:5], v[154:157], v[202:205], v[2:5]
	v_mfma_f32_16x16x32_bf16 v[54:57], v[150:153], v[170:173], v[54:57]
	v_mfma_f32_16x16x32_bf16 v[50:53], v[158:161], v[170:173], v[50:53]
	v_mfma_f32_16x16x32_bf16 v[38:41], v[150:153], v[190:193], v[38:41]
	v_mfma_f32_16x16x32_bf16 v[34:37], v[158:161], v[190:193], v[34:37]
	v_mfma_f32_16x16x32_bf16 v[22:25], v[150:153], v[198:201], v[22:25]
	v_mfma_f32_16x16x32_bf16 v[18:21], v[158:161], v[198:201], v[18:21]
	s_setprio 2
	s_barrier
	v_mfma_f32_16x16x32_bf16 v[6:9], v[150:153], v[206:209], v[6:9]
	v_mfma_f32_16x16x32_bf16 v[2:5], v[158:161], v[206:209], v[2:5]
	s_setprio 0
	ds_read_b128 v[130:133], v184
	ds_read_b128 v[134:137], v184 offset:1024
	ds_read_b128 v[138:141], v184 offset:2048
	ds_read_b128 v[142:145], v184 offset:3072
	ds_read_b128 v[146:149], v185
	ds_read_b128 v[150:153], v185 offset:1024
	ds_read_b128 v[154:157], v185 offset:2048
	ds_read_b128 v[158:161], v185 offset:3072
	ds_read_b128 v[166:169], v183 offset:32768
	ds_read_b128 v[170:173], v183 offset:33792
	ds_read_b128 v[186:189], v183 offset:34816
	ds_read_b128 v[190:193], v183 offset:35840
	ds_read_b128 v[194:197], v183 offset:36864
	ds_read_b128 v[198:201], v183 offset:37888
	ds_read_b128 v[202:205], v183 offset:38912
	ds_read_b128 v[206:209], v183 offset:39936
	s_mov_b32 s79, m0
	s_mov_b32 m0, s34
	s_nop 0
	global_load_lds_dwordx4 v1, s[24:25]
	s_mov_b32 m0, s79
	s_nop 0
	s_mov_b32 s79, m0
	s_mov_b32 m0, s41
	s_nop 0
	global_load_lds_dwordx4 v177, s[24:25]
	s_mov_b32 m0, s79
	s_add_u32 s24, s24, 0x80000
	s_addc_u32 s25, s25, 0
	s_mov_b32 s79, m0
	s_mov_b32 m0, s42
	s_nop 0
	global_load_lds_dwordx4 v1, s[24:25]
	s_mov_b32 m0, s79
	s_nop 0
	s_mov_b32 s79, m0
	s_mov_b32 m0, s43
	s_nop 0
	global_load_lds_dwordx4 v177, s[24:25]
	s_mov_b32 m0, s79
	s_waitcnt vmcnt(8)
	s_waitcnt lgkmcnt(0)
	s_barrier
	s_setprio 1
	s_waitcnt lgkmcnt(7)
	v_mfma_f32_16x16x32_bf16 v[126:129], v[130:133], v[166:169], v[126:129]
	v_mfma_f32_16x16x32_bf16 v[122:125], v[138:141], v[166:169], v[122:125]
	s_waitcnt lgkmcnt(5)
	v_mfma_f32_16x16x32_bf16 v[118:121], v[130:133], v[186:189], v[118:121]
	v_mfma_f32_16x16x32_bf16 v[114:117], v[138:141], v[186:189], v[114:117]
	s_waitcnt lgkmcnt(3)
	v_mfma_f32_16x16x32_bf16 v[94:97], v[130:133], v[194:197], v[94:97]
	v_mfma_f32_16x16x32_bf16 v[90:93], v[138:141], v[194:197], v[90:93]
	s_waitcnt lgkmcnt(1)
	v_mfma_f32_16x16x32_bf16 v[86:89], v[130:133], v[202:205], v[86:89]
	v_mfma_f32_16x16x32_bf16 v[78:81], v[138:141], v[202:205], v[78:81]
	v_mfma_f32_16x16x32_bf16 v[126:129], v[134:137], v[170:173], v[126:129]
	v_mfma_f32_16x16x32_bf16 v[122:125], v[142:145], v[170:173], v[122:125]
	v_mfma_f32_16x16x32_bf16 v[118:121], v[134:137], v[190:193], v[118:121]
	v_mfma_f32_16x16x32_bf16 v[114:117], v[142:145], v[190:193], v[114:117]
	v_mfma_f32_16x16x32_bf16 v[94:97], v[134:137], v[198:201], v[94:97]
	v_mfma_f32_16x16x32_bf16 v[90:93], v[142:145], v[198:201], v[90:93]
	s_waitcnt lgkmcnt(0)
	v_mfma_f32_16x16x32_bf16 v[86:89], v[134:137], v[206:209], v[86:89]
	v_mfma_f32_16x16x32_bf16 v[78:81], v[142:145], v[206:209], v[78:81]
	s_setprio 0
	s_setprio 1
	v_mfma_f32_16x16x32_bf16 v[110:113], v[146:149], v[166:169], v[110:113]
	v_mfma_f32_16x16x32_bf16 v[106:109], v[154:157], v[166:169], v[106:109]
	v_mfma_f32_16x16x32_bf16 v[102:105], v[146:149], v[186:189], v[102:105]
	v_mfma_f32_16x16x32_bf16 v[98:101], v[154:157], v[186:189], v[98:101]
	v_mfma_f32_16x16x32_bf16 v[82:85], v[146:149], v[194:197], v[82:85]
	v_mfma_f32_16x16x32_bf16 v[74:77], v[154:157], v[194:197], v[74:77]
	v_mfma_f32_16x16x32_bf16 v[70:73], v[146:149], v[202:205], v[70:73]
	v_mfma_f32_16x16x32_bf16 v[66:69], v[154:157], v[202:205], v[66:69]
	v_mfma_f32_16x16x32_bf16 v[110:113], v[150:153], v[170:173], v[110:113]
	v_mfma_f32_16x16x32_bf16 v[106:109], v[158:161], v[170:173], v[106:109]
	v_mfma_f32_16x16x32_bf16 v[102:105], v[150:153], v[190:193], v[102:105]
	v_mfma_f32_16x16x32_bf16 v[98:101], v[158:161], v[190:193], v[98:101]
	v_mfma_f32_16x16x32_bf16 v[82:85], v[150:153], v[198:201], v[82:85]
	v_mfma_f32_16x16x32_bf16 v[74:77], v[158:161], v[198:201], v[74:77]
	s_setprio 2
	s_barrier
	v_mfma_f32_16x16x32_bf16 v[70:73], v[150:153], v[206:209], v[70:73]
	v_mfma_f32_16x16x32_bf16 v[66:69], v[158:161], v[206:209], v[66:69]
	s_setprio 0
	ds_read_b128 v[166:169], v183 offset:49152
	ds_read_b128 v[170:173], v183 offset:50176
	ds_read_b128 v[186:189], v183 offset:51200
	ds_read_b128 v[190:193], v183 offset:52224
	ds_read_b128 v[194:197], v183 offset:53248
	ds_read_b128 v[198:201], v183 offset:54272
	ds_read_b128 v[202:205], v183 offset:55296
	ds_read_b128 v[206:209], v183 offset:56320
	s_add_u32 s24, s22, 0x80
	s_addc_u32 s25, s23, 0
	s_mov_b32 s79, m0
	s_mov_b32 m0, s46
	s_nop 0
	global_load_lds_dwordx4 v176, s[24:25]
	s_mov_b32 m0, s79
	s_add_u32 s22, s22, 0x80080
	s_mov_b32 s79, m0
	s_mov_b32 m0, s47
	s_nop 0
	global_load_lds_dwordx4 v178, s[24:25]
	s_mov_b32 m0, s79
	s_addc_u32 s23, s23, 0
	s_mov_b32 s24, m0
	s_mov_b32 m0, s48
	s_nop 0
	global_load_lds_dwordx4 v176, s[22:23]
	s_mov_b32 m0, s24
	s_nop 0
	s_mov_b32 s24, m0
	s_mov_b32 m0, s49
	s_nop 0
	global_load_lds_dwordx4 v178, s[22:23]
	s_mov_b32 m0, s24
	s_waitcnt vmcnt(4)
	s_waitcnt lgkmcnt(0)
	s_barrier
	s_setprio 1
	s_waitcnt lgkmcnt(7)
	v_mfma_f32_16x16x32_bf16 v[62:65], v[130:133], v[166:169], v[62:65]
	v_mfma_f32_16x16x32_bf16 v[58:61], v[138:141], v[166:169], v[58:61]
	s_waitcnt lgkmcnt(5)
	v_mfma_f32_16x16x32_bf16 v[46:49], v[130:133], v[186:189], v[46:49]
	v_mfma_f32_16x16x32_bf16 v[42:45], v[138:141], v[186:189], v[42:45]
	s_waitcnt lgkmcnt(3)
	v_mfma_f32_16x16x32_bf16 v[30:33], v[130:133], v[194:197], v[30:33]
	v_mfma_f32_16x16x32_bf16 v[26:29], v[138:141], v[194:197], v[26:29]
	s_waitcnt lgkmcnt(1)
	v_mfma_f32_16x16x32_bf16 v[14:17], v[130:133], v[202:205], v[14:17]
	v_mfma_f32_16x16x32_bf16 v[10:13], v[138:141], v[202:205], v[10:13]
	v_mfma_f32_16x16x32_bf16 v[62:65], v[134:137], v[170:173], v[62:65]
	v_mfma_f32_16x16x32_bf16 v[58:61], v[142:145], v[170:173], v[58:61]
	v_mfma_f32_16x16x32_bf16 v[46:49], v[134:137], v[190:193], v[46:49]
	v_mfma_f32_16x16x32_bf16 v[42:45], v[142:145], v[190:193], v[42:45]
	v_mfma_f32_16x16x32_bf16 v[30:33], v[134:137], v[198:201], v[30:33]
	v_mfma_f32_16x16x32_bf16 v[26:29], v[142:145], v[198:201], v[26:29]
	s_waitcnt lgkmcnt(0)
	v_mfma_f32_16x16x32_bf16 v[14:17], v[134:137], v[206:209], v[14:17]
	v_mfma_f32_16x16x32_bf16 v[10:13], v[142:145], v[206:209], v[10:13]
	s_setprio 0
	s_setprio 1
	v_mfma_f32_16x16x32_bf16 v[54:57], v[146:149], v[166:169], v[54:57]
	v_mfma_f32_16x16x32_bf16 v[50:53], v[154:157], v[166:169], v[50:53]
	v_mfma_f32_16x16x32_bf16 v[38:41], v[146:149], v[186:189], v[38:41]
	v_mfma_f32_16x16x32_bf16 v[34:37], v[154:157], v[186:189], v[34:37]
	v_mfma_f32_16x16x32_bf16 v[22:25], v[146:149], v[194:197], v[22:25]
	v_mfma_f32_16x16x32_bf16 v[18:21], v[154:157], v[194:197], v[18:21]
	v_mfma_f32_16x16x32_bf16 v[6:9], v[146:149], v[202:205], v[6:9]
	v_mfma_f32_16x16x32_bf16 v[2:5], v[154:157], v[202:205], v[2:5]
	v_mfma_f32_16x16x32_bf16 v[54:57], v[150:153], v[170:173], v[54:57]
	v_mfma_f32_16x16x32_bf16 v[50:53], v[158:161], v[170:173], v[50:53]
	v_mfma_f32_16x16x32_bf16 v[38:41], v[150:153], v[190:193], v[38:41]
	v_mfma_f32_16x16x32_bf16 v[34:37], v[158:161], v[190:193], v[34:37]
	v_mfma_f32_16x16x32_bf16 v[22:25], v[150:153], v[198:201], v[22:25]
	v_mfma_f32_16x16x32_bf16 v[18:21], v[158:161], v[198:201], v[18:21]
	s_setprio 2
	s_barrier
	v_mfma_f32_16x16x32_bf16 v[6:9], v[150:153], v[206:209], v[6:9]
	v_mfma_f32_16x16x32_bf16 v[2:5], v[158:161], v[206:209], v[2:5]
	s_setprio 0
	s_add_i32 s78, s78, 2
	s_add_u32 s74, s74, 0x100
	s_addc_u32 s75, s75, 0
	s_add_u32 s20, s20, 0x100
	s_addc_u32 s21, s21, 0
	s_add_u32 s76, s76, 0x100
	s_addc_u32 s77, s77, 0
	s_cmp_gt_u32 s78, 29
	s_cbranch_scc0 .LBB0_1053
	s_and_b64 vcc, exec, s[8:9]
	s_cbranch_vccz .LBB0_1056
	s_barrier

.LBB0_1224:
	ds_read_b128 v[148:151], v143
	ds_read_b128 v[152:155], v143 offset:1024
	ds_read_b128 v[156:159], v143 offset:2048
	ds_read_b128 v[160:163], v143 offset:3072
	ds_read_b128 v[164:167], v144
	ds_read_b128 v[168:171], v144 offset:1024
	ds_read_b128 v[172:175], v144 offset:2048
	ds_read_b128 v[176:179], v144 offset:3072
	s_cmp_eq_u32 s77, 28
	s_cselect_b32 s21, s9, s74
	s_cselect_b32 s20, s67, s73
	s_cselect_b32 s23, s11, s76
	s_cselect_b32 s22, s66, s75
	ds_read_b128 v[180:183], v145
	ds_read_b128 v[184:187], v145 offset:1024
	ds_read_b128 v[188:191], v145 offset:2048
	ds_read_b128 v[192:195], v145 offset:3072
	ds_read_b128 v[196:199], v145 offset:4096
	ds_read_b128 v[200:203], v145 offset:5120
	ds_read_b128 v[204:207], v145 offset:6144
	ds_read_b128 v[208:211], v145 offset:7168
	s_add_u32 s78, s18, 0xfff80000
	s_addc_u32 s79, s19, -1
	s_mov_b32 s80, m0
	s_mov_b32 m0, s56
	s_nop 0
	global_load_lds_dwordx4 v138, s[78:79]
	s_mov_b32 m0, s80
	s_nop 0
	s_mov_b32 s80, m0
	s_mov_b32 m0, s59
	s_nop 0
	global_load_lds_dwordx4 v140, s[78:79]
	s_mov_b32 m0, s80
	s_mov_b32 s78, m0
	s_mov_b32 m0, s57
	s_nop 0
	global_load_lds_dwordx4 v138, s[18:19]
	s_mov_b32 m0, s78
	s_nop 0
	s_mov_b32 s78, m0
	s_mov_b32 m0, s64
	s_nop 0
	global_load_lds_dwordx4 v140, s[18:19]
	s_mov_b32 m0, s78
	s_waitcnt vmcnt(8)
	s_waitcnt lgkmcnt(0)
	s_barrier
	s_setprio 1
	s_waitcnt lgkmcnt(7)
	v_mfma_f32_16x16x32_bf16 v[126:129], v[148:151], v[180:183], v[126:129]
	v_mfma_f32_16x16x32_bf16 v[122:125], v[156:159], v[180:183], v[122:125]
	s_waitcnt lgkmcnt(5)
	v_mfma_f32_16x16x32_bf16 v[110:113], v[148:151], v[188:191], v[110:113]
	v_mfma_f32_16x16x32_bf16 v[106:109], v[156:159], v[188:191], v[106:109]
	s_waitcnt lgkmcnt(3)
	v_mfma_f32_16x16x32_bf16 v[94:97], v[148:151], v[196:199], v[94:97]
	v_mfma_f32_16x16x32_bf16 v[90:93], v[156:159], v[196:199], v[90:93]
	s_waitcnt lgkmcnt(1)
	v_mfma_f32_16x16x32_bf16 v[78:81], v[148:151], v[204:207], v[78:81]
	v_mfma_f32_16x16x32_bf16 v[74:77], v[156:159], v[204:207], v[74:77]
	v_mfma_f32_16x16x32_bf16 v[126:129], v[152:155], v[184:187], v[126:129]
	v_mfma_f32_16x16x32_bf16 v[122:125], v[160:163], v[184:187], v[122:125]
	v_mfma_f32_16x16x32_bf16 v[110:113], v[152:155], v[192:195], v[110:113]
	v_mfma_f32_16x16x32_bf16 v[106:109], v[160:163], v[192:195], v[106:109]
	v_mfma_f32_16x16x32_bf16 v[94:97], v[152:155], v[200:203], v[94:97]
	v_mfma_f32_16x16x32_bf16 v[90:93], v[160:163], v[200:203], v[90:93]
	s_waitcnt lgkmcnt(0)
	v_mfma_f32_16x16x32_bf16 v[78:81], v[152:155], v[208:211], v[78:81]
	v_mfma_f32_16x16x32_bf16 v[74:77], v[160:163], v[208:211], v[74:77]
	s_setprio 0
	s_setprio 1
	v_mfma_f32_16x16x32_bf16 v[118:121], v[164:167], v[180:183], v[118:121]
	v_mfma_f32_16x16x32_bf16 v[114:117], v[172:175], v[180:183], v[114:117]
	v_mfma_f32_16x16x32_bf16 v[102:105], v[164:167], v[188:191], v[102:105]
	v_mfma_f32_16x16x32_bf16 v[98:101], v[172:175], v[188:191], v[98:101]
	v_mfma_f32_16x16x32_bf16 v[86:89], v[164:167], v[196:199], v[86:89]
	v_mfma_f32_16x16x32_bf16 v[82:85], v[172:175], v[196:199], v[82:85]
	v_mfma_f32_16x16x32_bf16 v[70:73], v[164:167], v[204:207], v[70:73]
	v_mfma_f32_16x16x32_bf16 v[66:69], v[172:175], v[204:207], v[66:69]
	v_mfma_f32_16x16x32_bf16 v[118:121], v[168:171], v[184:187], v[118:121]
	v_mfma_f32_16x16x32_bf16 v[114:117], v[176:179], v[184:187], v[114:117]
	v_mfma_f32_16x16x32_bf16 v[102:105], v[168:171], v[192:195], v[102:105]
	v_mfma_f32_16x16x32_bf16 v[98:101], v[176:179], v[192:195], v[98:101]
	v_mfma_f32_16x16x32_bf16 v[86:89], v[168:171], v[200:203], v[86:89]
	v_mfma_f32_16x16x32_bf16 v[82:85], v[176:179], v[200:203], v[82:85]
	s_setprio 2
	s_barrier
	v_mfma_f32_16x16x32_bf16 v[70:73], v[168:171], v[208:211], v[70:73]
	v_mfma_f32_16x16x32_bf16 v[66:69], v[176:179], v[208:211], v[66:69]
	s_setprio 0
	ds_read_b128 v[180:183], v145 offset:16384
	ds_read_b128 v[184:187], v145 offset:17408
	ds_read_b128 v[188:191], v145 offset:18432
	ds_read_b128 v[192:195], v145 offset:19456
	ds_read_b128 v[196:199], v145 offset:20480
	ds_read_b128 v[200:203], v145 offset:21504
	ds_read_b128 v[204:207], v145 offset:22528
	ds_read_b128 v[208:211], v145 offset:23552
	s_mov_b32 s78, m0
	s_mov_b32 m0, s35
	s_nop 0
	global_load_lds_dwordx4 v139, s[20:21]
	s_mov_b32 m0, s78
	s_nop 0
	s_mov_b32 s78, m0
	s_mov_b32 m0, s36
	s_nop 0
	global_load_lds_dwordx4 v141, s[20:21]
	s_mov_b32 m0, s78
	s_add_u32 s78, s20, 0x80000
	s_addc_u32 s79, s21, 0
	s_mov_b32 s80, m0
	s_mov_b32 m0, s37
	s_nop 0
	global_load_lds_dwordx4 v139, s[78:79]
	s_mov_b32 m0, s80
	s_nop 0
	s_mov_b32 s80, m0
	s_mov_b32 m0, s40
	s_nop 0
	global_load_lds_dwordx4 v141, s[78:79]
	s_mov_b32 m0, s80
	s_waitcnt vmcnt(4)
	s_waitcnt lgkmcnt(0)
	s_barrier
	s_setprio 1
	s_waitcnt lgkmcnt(7)
	v_mfma_f32_16x16x32_bf16 v[62:65], v[148:151], v[180:183], v[62:65]
	v_mfma_f32_16x16x32_bf16 v[58:61], v[156:159], v[180:183], v[58:61]
	s_waitcnt lgkmcnt(5)
	v_mfma_f32_16x16x32_bf16 v[46:49], v[148:151], v[188:191], v[46:49]
	v_mfma_f32_16x16x32_bf16 v[42:45], v[156:159], v[188:191], v[42:45]
	s_waitcnt lgkmcnt(3)
	v_mfma_f32_16x16x32_bf16 v[30:33], v[148:151], v[196:199], v[30:33]
	v_mfma_f32_16x16x32_bf16 v[26:29], v[156:159], v[196:199], v[26:29]
	s_waitcnt lgkmcnt(1)
	v_mfma_f32_16x16x32_bf16 v[14:17], v[148:151], v[204:207], v[14:17]
	v_mfma_f32_16x16x32_bf16 v[10:13], v[156:159], v[204:207], v[10:13]
	v_mfma_f32_16x16x32_bf16 v[62:65], v[152:155], v[184:187], v[62:65]
	v_mfma_f32_16x16x32_bf16 v[58:61], v[160:163], v[184:187], v[58:61]
	v_mfma_f32_16x16x32_bf16 v[46:49], v[152:155], v[192:195], v[46:49]
	v_mfma_f32_16x16x32_bf16 v[42:45], v[160:163], v[192:195], v[42:45]
	v_mfma_f32_16x16x32_bf16 v[30:33], v[152:155], v[200:203], v[30:33]
	v_mfma_f32_16x16x32_bf16 v[26:29], v[160:163], v[200:203], v[26:29]
	s_waitcnt lgkmcnt(0)
	v_mfma_f32_16x16x32_bf16 v[14:17], v[152:155], v[208:211], v[14:17]
	v_mfma_f32_16x16x32_bf16 v[10:13], v[160:163], v[208:211], v[10:13]
	s_setprio 0
	s_setprio 1
	v_mfma_f32_16x16x32_bf16 v[54:57], v[164:167], v[180:183], v[54:57]
	v_mfma_f32_16x16x32_bf16 v[50:53], v[172:175], v[180:183], v[50:53]
	v_mfma_f32_16x16x32_bf16 v[38:41], v[164:167], v[188:191], v[38:41]
	v_mfma_f32_16x16x32_bf16 v[34:37], v[172:175], v[188:191], v[34:37]
	v_mfma_f32_16x16x32_bf16 v[22:25], v[164:167], v[196:199], v[22:25]
	v_mfma_f32_16x16x32_bf16 v[18:21], v[172:175], v[196:199], v[18:21]
	v_mfma_f32_16x16x32_bf16 v[6:9], v[164:167], v[204:207], v[6:9]
	v_mfma_f32_16x16x32_bf16 v[2:5], v[172:175], v[204:207], v[2:5]
	v_mfma_f32_16x16x32_bf16 v[54:57], v[168:171], v[184:187], v[54:57]
	v_mfma_f32_16x16x32_bf16 v[50:53], v[176:179], v[184:187], v[50:53]
	v_mfma_f32_16x16x32_bf16 v[38:41], v[168:171], v[192:195], v[38:41]
	v_mfma_f32_16x16x32_bf16 v[34:37], v[176:179], v[192:195], v[34:37]
	v_mfma_f32_16x16x32_bf16 v[22:25], v[168:171], v[200:203], v[22:25]
	v_mfma_f32_16x16x32_bf16 v[18:21], v[176:179], v[200:203], v[18:21]
	s_setprio 2
	s_barrier
	v_mfma_f32_16x16x32_bf16 v[6:9], v[168:171], v[208:211], v[6:9]
	v_mfma_f32_16x16x32_bf16 v[2:5], v[176:179], v[208:211], v[2:5]
	s_setprio 0
	ds_read_b128 v[148:151], v146
	ds_read_b128 v[152:155], v146 offset:1024
	ds_read_b128 v[156:159], v146 offset:2048
	ds_read_b128 v[160:163], v146 offset:3072
	ds_read_b128 v[164:167], v147
	ds_read_b128 v[168:171], v147 offset:1024
	ds_read_b128 v[172:175], v147 offset:2048
	ds_read_b128 v[176:179], v147 offset:3072
	ds_read_b128 v[180:183], v145 offset:32768
	ds_read_b128 v[184:187], v145 offset:33792
	ds_read_b128 v[188:191], v145 offset:34816
	ds_read_b128 v[192:195], v145 offset:35840
	ds_read_b128 v[196:199], v145 offset:36864
	ds_read_b128 v[200:203], v145 offset:37888
	ds_read_b128 v[204:207], v145 offset:38912
	ds_read_b128 v[208:211], v145 offset:39936
	s_mov_b32 s78, m0
	s_mov_b32 m0, s31
	s_nop 0
	global_load_lds_dwordx4 v138, s[22:23]
	s_mov_b32 m0, s78
	s_nop 0
	s_mov_b32 s78, m0
	s_mov_b32 m0, s41
	s_nop 0
	global_load_lds_dwordx4 v140, s[22:23]
	s_mov_b32 m0, s78
	s_add_u32 s22, s22, 0x80000
	s_addc_u32 s23, s23, 0
	s_mov_b32 s78, m0
	s_mov_b32 m0, s42
	s_nop 0
	global_load_lds_dwordx4 v138, s[22:23]
	s_mov_b32 m0, s78
	s_nop 0
	s_mov_b32 s78, m0
	s_mov_b32 m0, s43
	s_nop 0
	global_load_lds_dwordx4 v140, s[22:23]
	s_mov_b32 m0, s78
	s_waitcnt vmcnt(8)
	s_waitcnt lgkmcnt(0)
	s_barrier
	s_setprio 1
	s_waitcnt lgkmcnt(7)
	v_mfma_f32_16x16x32_bf16 v[126:129], v[148:151], v[180:183], v[126:129]
	v_mfma_f32_16x16x32_bf16 v[122:125], v[156:159], v[180:183], v[122:125]
	s_waitcnt lgkmcnt(5)
	v_mfma_f32_16x16x32_bf16 v[110:113], v[148:151], v[188:191], v[110:113]
	v_mfma_f32_16x16x32_bf16 v[106:109], v[156:159], v[188:191], v[106:109]
	s_waitcnt lgkmcnt(3)
	v_mfma_f32_16x16x32_bf16 v[94:97], v[148:151], v[196:199], v[94:97]
	v_mfma_f32_16x16x32_bf16 v[90:93], v[156:159], v[196:199], v[90:93]
	s_waitcnt lgkmcnt(1)
	v_mfma_f32_16x16x32_bf16 v[78:81], v[148:151], v[204:207], v[78:81]
	v_mfma_f32_16x16x32_bf16 v[74:77], v[156:159], v[204:207], v[74:77]
	v_mfma_f32_16x16x32_bf16 v[126:129], v[152:155], v[184:187], v[126:129]
	v_mfma_f32_16x16x32_bf16 v[122:125], v[160:163], v[184:187], v[122:125]
	v_mfma_f32_16x16x32_bf16 v[110:113], v[152:155], v[192:195], v[110:113]
	v_mfma_f32_16x16x32_bf16 v[106:109], v[160:163], v[192:195], v[106:109]
	v_mfma_f32_16x16x32_bf16 v[94:97], v[152:155], v[200:203], v[94:97]
	v_mfma_f32_16x16x32_bf16 v[90:93], v[160:163], v[200:203], v[90:93]
	s_waitcnt lgkmcnt(0)
	v_mfma_f32_16x16x32_bf16 v[78:81], v[152:155], v[208:211], v[78:81]
	v_mfma_f32_16x16x32_bf16 v[74:77], v[160:163], v[208:211], v[74:77]
	s_setprio 0
	s_setprio 1
	v_mfma_f32_16x16x32_bf16 v[118:121], v[164:167], v[180:183], v[118:121]
	v_mfma_f32_16x16x32_bf16 v[114:117], v[172:175], v[180:183], v[114:117]
	v_mfma_f32_16x16x32_bf16 v[102:105], v[164:167], v[188:191], v[102:105]
	v_mfma_f32_16x16x32_bf16 v[98:101], v[172:175], v[188:191], v[98:101]
	v_mfma_f32_16x16x32_bf16 v[86:89], v[164:167], v[196:199], v[86:89]
	v_mfma_f32_16x16x32_bf16 v[82:85], v[172:175], v[196:199], v[82:85]
	v_mfma_f32_16x16x32_bf16 v[70:73], v[164:167], v[204:207], v[70:73]
	v_mfma_f32_16x16x32_bf16 v[66:69], v[172:175], v[204:207], v[66:69]
	v_mfma_f32_16x16x32_bf16 v[118:121], v[168:171], v[184:187], v[118:121]
	v_mfma_f32_16x16x32_bf16 v[114:117], v[176:179], v[184:187], v[114:117]
	v_mfma_f32_16x16x32_bf16 v[102:105], v[168:171], v[192:195], v[102:105]
	v_mfma_f32_16x16x32_bf16 v[98:101], v[176:179], v[192:195], v[98:101]
	v_mfma_f32_16x16x32_bf16 v[86:89], v[168:171], v[200:203], v[86:89]
	v_mfma_f32_16x16x32_bf16 v[82:85], v[176:179], v[200:203], v[82:85]
	s_setprio 2
	s_barrier
	v_mfma_f32_16x16x32_bf16 v[70:73], v[168:171], v[208:211], v[70:73]
	v_mfma_f32_16x16x32_bf16 v[66:69], v[176:179], v[208:211], v[66:69]
	s_setprio 0
	ds_read_b128 v[180:183], v145 offset:49152
	ds_read_b128 v[184:187], v145 offset:50176
	ds_read_b128 v[188:191], v145 offset:51200
	ds_read_b128 v[192:195], v145 offset:52224
	ds_read_b128 v[196:199], v145 offset:53248
	ds_read_b128 v[200:203], v145 offset:54272
	ds_read_b128 v[204:207], v145 offset:55296
	ds_read_b128 v[208:211], v145 offset:56320
	s_add_u32 s22, s20, 0x80
	s_addc_u32 s23, s21, 0
	s_mov_b32 s78, m0
	s_mov_b32 m0, s46
	s_nop 0
	global_load_lds_dwordx4 v139, s[22:23]
	s_mov_b32 m0, s78
	s_add_u32 s20, s20, 0x80080
	s_mov_b32 s78, m0
	s_mov_b32 m0, s47
	s_nop 0
	global_load_lds_dwordx4 v141, s[22:23]
	s_mov_b32 m0, s78
	s_addc_u32 s21, s21, 0
	s_mov_b32 s22, m0
	s_mov_b32 m0, s48
	s_nop 0
	global_load_lds_dwordx4 v139, s[20:21]
	s_mov_b32 m0, s22
	s_nop 0
	s_mov_b32 s22, m0
	s_mov_b32 m0, s49
	s_nop 0
	global_load_lds_dwordx4 v141, s[20:21]
	s_mov_b32 m0, s22
	s_waitcnt vmcnt(4)
	s_waitcnt lgkmcnt(0)
	s_barrier
	s_setprio 1
	s_waitcnt lgkmcnt(7)
	v_mfma_f32_16x16x32_bf16 v[62:65], v[148:151], v[180:183], v[62:65]
	v_mfma_f32_16x16x32_bf16 v[58:61], v[156:159], v[180:183], v[58:61]
	s_waitcnt lgkmcnt(5)
	v_mfma_f32_16x16x32_bf16 v[46:49], v[148:151], v[188:191], v[46:49]
	v_mfma_f32_16x16x32_bf16 v[42:45], v[156:159], v[188:191], v[42:45]
	s_waitcnt lgkmcnt(3)
	v_mfma_f32_16x16x32_bf16 v[30:33], v[148:151], v[196:199], v[30:33]
	v_mfma_f32_16x16x32_bf16 v[26:29], v[156:159], v[196:199], v[26:29]
	s_waitcnt lgkmcnt(1)
	v_mfma_f32_16x16x32_bf16 v[14:17], v[148:151], v[204:207], v[14:17]
	v_mfma_f32_16x16x32_bf16 v[10:13], v[156:159], v[204:207], v[10:13]
	v_mfma_f32_16x16x32_bf16 v[62:65], v[152:155], v[184:187], v[62:65]
	v_mfma_f32_16x16x32_bf16 v[58:61], v[160:163], v[184:187], v[58:61]
	v_mfma_f32_16x16x32_bf16 v[46:49], v[152:155], v[192:195], v[46:49]
	v_mfma_f32_16x16x32_bf16 v[42:45], v[160:163], v[192:195], v[42:45]
	v_mfma_f32_16x16x32_bf16 v[30:33], v[152:155], v[200:203], v[30:33]
	v_mfma_f32_16x16x32_bf16 v[26:29], v[160:163], v[200:203], v[26:29]
	s_waitcnt lgkmcnt(0)
	v_mfma_f32_16x16x32_bf16 v[14:17], v[152:155], v[208:211], v[14:17]
	v_mfma_f32_16x16x32_bf16 v[10:13], v[160:163], v[208:211], v[10:13]
	s_setprio 0
	s_setprio 1
	v_mfma_f32_16x16x32_bf16 v[54:57], v[164:167], v[180:183], v[54:57]
	v_mfma_f32_16x16x32_bf16 v[50:53], v[172:175], v[180:183], v[50:53]
	v_mfma_f32_16x16x32_bf16 v[38:41], v[164:167], v[188:191], v[38:41]
	v_mfma_f32_16x16x32_bf16 v[34:37], v[172:175], v[188:191], v[34:37]
	v_mfma_f32_16x16x32_bf16 v[22:25], v[164:167], v[196:199], v[22:25]
	v_mfma_f32_16x16x32_bf16 v[18:21], v[172:175], v[196:199], v[18:21]
	v_mfma_f32_16x16x32_bf16 v[6:9], v[164:167], v[204:207], v[6:9]
	v_mfma_f32_16x16x32_bf16 v[2:5], v[172:175], v[204:207], v[2:5]
	v_mfma_f32_16x16x32_bf16 v[54:57], v[168:171], v[184:187], v[54:57]
	v_mfma_f32_16x16x32_bf16 v[50:53], v[176:179], v[184:187], v[50:53]
	v_mfma_f32_16x16x32_bf16 v[38:41], v[168:171], v[192:195], v[38:41]
	v_mfma_f32_16x16x32_bf16 v[34:37], v[176:179], v[192:195], v[34:37]
	v_mfma_f32_16x16x32_bf16 v[22:25], v[168:171], v[200:203], v[22:25]
	v_mfma_f32_16x16x32_bf16 v[18:21], v[176:179], v[200:203], v[18:21]
	s_setprio 2
	s_barrier
	v_mfma_f32_16x16x32_bf16 v[6:9], v[168:171], v[208:211], v[6:9]
	v_mfma_f32_16x16x32_bf16 v[2:5], v[176:179], v[208:211], v[2:5]
	s_setprio 0
	s_add_i32 s77, s77, 2
	s_add_u32 s73, s73, 0x100
	s_addc_u32 s74, s74, 0
	s_add_u32 s18, s18, 0x100
	s_addc_u32 s19, s19, 0
	s_add_u32 s75, s75, 0x100
	s_addc_u32 s76, s76, 0
	s_cmp_gt_u32 s77, 29
	s_cbranch_scc0 .LBB0_1224
	s_and_b64 vcc, exec, s[6:7]
	s_cbranch_vccz .LBB0_1227
	s_barrier

.LBB0_1357:
	ds_read_b128 v[130:133], v181
	ds_read_b128 v[134:137], v181 offset:1024
	ds_read_b128 v[138:141], v181 offset:2048
	ds_read_b128 v[142:145], v181 offset:3072
	ds_read_b128 v[150:153], v182
	ds_read_b128 v[154:157], v182 offset:1024
	ds_read_b128 v[158:161], v182 offset:2048
	ds_read_b128 v[162:165], v182 offset:3072
	s_cmpk_eq_i32 s78, 0x52
	s_cselect_b32 s23, s11, s75
	s_cselect_b32 s22, s73, s74
	s_cselect_b32 s25, s13, s77
	s_cselect_b32 s24, s67, s76
	ds_read_b128 v[166:169], v183
	ds_read_b128 v[170:173], v183 offset:1024
	ds_read_b128 v[186:189], v183 offset:2048
	ds_read_b128 v[190:193], v183 offset:3072
	ds_read_b128 v[194:197], v183 offset:4096
	ds_read_b128 v[198:201], v183 offset:5120
	ds_read_b128 v[202:205], v183 offset:6144
	ds_read_b128 v[206:209], v183 offset:7168
	s_add_u32 s80, s20, 0xffffc000
	s_addc_u32 s81, s21, -1
	s_mov_b32 s79, m0
	s_mov_b32 m0, s58
	s_nop 0
	global_load_lds_dwordx4 v1, s[80:81]
	s_mov_b32 m0, s79
	s_nop 0
	s_mov_b32 s79, m0
	s_mov_b32 m0, s64
	s_nop 0
	global_load_lds_dwordx4 v177, s[80:81]
	s_mov_b32 m0, s79
	s_nop 0
	s_mov_b32 s79, m0
	s_mov_b32 m0, s59
	s_nop 0
	global_load_lds_dwordx4 v1, s[20:21]
	s_mov_b32 m0, s79
	s_nop 0
	s_mov_b32 s79, m0
	s_mov_b32 m0, s65
	s_nop 0
	global_load_lds_dwordx4 v177, s[20:21]
	s_mov_b32 m0, s79
	s_waitcnt vmcnt(8)
	s_waitcnt lgkmcnt(0)
	s_barrier
	s_setprio 1
	s_waitcnt lgkmcnt(7)
	v_mfma_f32_16x16x32_bf16 v[126:129], v[130:133], v[166:169], v[126:129]
	v_mfma_f32_16x16x32_bf16 v[122:125], v[138:141], v[166:169], v[122:125]
	s_waitcnt lgkmcnt(5)
	v_mfma_f32_16x16x32_bf16 v[118:121], v[130:133], v[186:189], v[118:121]
	v_mfma_f32_16x16x32_bf16 v[110:113], v[138:141], v[186:189], v[110:113]
	s_waitcnt lgkmcnt(3)
	v_mfma_f32_16x16x32_bf16 v[94:97], v[130:133], v[194:197], v[94:97]
	v_mfma_f32_16x16x32_bf16 v[90:93], v[138:141], v[194:197], v[90:93]
	s_waitcnt lgkmcnt(1)
	v_mfma_f32_16x16x32_bf16 v[86:89], v[130:133], v[202:205], v[86:89]
	v_mfma_f32_16x16x32_bf16 v[78:81], v[138:141], v[202:205], v[78:81]
	v_mfma_f32_16x16x32_bf16 v[126:129], v[134:137], v[170:173], v[126:129]
	v_mfma_f32_16x16x32_bf16 v[122:125], v[142:145], v[170:173], v[122:125]
	v_mfma_f32_16x16x32_bf16 v[118:121], v[134:137], v[190:193], v[118:121]
	v_mfma_f32_16x16x32_bf16 v[110:113], v[142:145], v[190:193], v[110:113]
	v_mfma_f32_16x16x32_bf16 v[94:97], v[134:137], v[198:201], v[94:97]
	v_mfma_f32_16x16x32_bf16 v[90:93], v[142:145], v[198:201], v[90:93]
	s_waitcnt lgkmcnt(0)
	v_mfma_f32_16x16x32_bf16 v[86:89], v[134:137], v[206:209], v[86:89]
	v_mfma_f32_16x16x32_bf16 v[78:81], v[142:145], v[206:209], v[78:81]
	s_setprio 0
	s_setprio 1
	v_mfma_f32_16x16x32_bf16 v[114:117], v[150:153], v[166:169], v[114:117]
	v_mfma_f32_16x16x32_bf16 v[106:109], v[158:161], v[166:169], v[106:109]
	v_mfma_f32_16x16x32_bf16 v[102:105], v[150:153], v[186:189], v[102:105]
	v_mfma_f32_16x16x32_bf16 v[98:101], v[158:161], v[186:189], v[98:101]
	v_mfma_f32_16x16x32_bf16 v[82:85], v[150:153], v[194:197], v[82:85]
	v_mfma_f32_16x16x32_bf16 v[74:77], v[158:161], v[194:197], v[74:77]
	v_mfma_f32_16x16x32_bf16 v[70:73], v[150:153], v[202:205], v[70:73]
	v_mfma_f32_16x16x32_bf16 v[66:69], v[158:161], v[202:205], v[66:69]
	v_mfma_f32_16x16x32_bf16 v[114:117], v[154:157], v[170:173], v[114:117]
	v_mfma_f32_16x16x32_bf16 v[106:109], v[162:165], v[170:173], v[106:109]
	v_mfma_f32_16x16x32_bf16 v[102:105], v[154:157], v[190:193], v[102:105]
	v_mfma_f32_16x16x32_bf16 v[98:101], v[162:165], v[190:193], v[98:101]
	v_mfma_f32_16x16x32_bf16 v[82:85], v[154:157], v[198:201], v[82:85]
	v_mfma_f32_16x16x32_bf16 v[74:77], v[162:165], v[198:201], v[74:77]
	s_setprio 2
	s_barrier
	v_mfma_f32_16x16x32_bf16 v[70:73], v[154:157], v[206:209], v[70:73]
	v_mfma_f32_16x16x32_bf16 v[66:69], v[162:165], v[206:209], v[66:69]
	s_setprio 0
	ds_read_b128 v[166:169], v183 offset:16384
	ds_read_b128 v[170:173], v183 offset:17408
	ds_read_b128 v[186:189], v183 offset:18432
	ds_read_b128 v[190:193], v183 offset:19456
	ds_read_b128 v[194:197], v183 offset:20480
	ds_read_b128 v[198:201], v183 offset:21504
	ds_read_b128 v[202:205], v183 offset:22528
	ds_read_b128 v[206:209], v183 offset:23552
	s_mov_b32 s79, m0
	s_mov_b32 m0, s35
	s_nop 0
	global_load_lds_dwordx4 v176, s[22:23]
	s_mov_b32 m0, s79
	s_add_u32 s80, s22, 0x4000
	s_mov_b32 s79, m0
	s_mov_b32 m0, s36
	s_nop 0
	global_load_lds_dwordx4 v178, s[22:23]
	s_mov_b32 m0, s79
	s_addc_u32 s81, s23, 0
	s_mov_b32 s79, m0
	s_mov_b32 m0, s37
	s_nop 0
	global_load_lds_dwordx4 v176, s[80:81]
	s_mov_b32 m0, s79
	s_nop 0
	s_mov_b32 s79, m0
	s_mov_b32 m0, s40
	s_nop 0
	global_load_lds_dwordx4 v178, s[80:81]
	s_mov_b32 m0, s79
	s_waitcnt vmcnt(4)
	s_waitcnt lgkmcnt(0)
	s_barrier
	s_setprio 1
	s_waitcnt lgkmcnt(7)
	v_mfma_f32_16x16x32_bf16 v[62:65], v[130:133], v[166:169], v[62:65]
	v_mfma_f32_16x16x32_bf16 v[58:61], v[138:141], v[166:169], v[58:61]
	s_waitcnt lgkmcnt(5)
	v_mfma_f32_16x16x32_bf16 v[46:49], v[130:133], v[186:189], v[46:49]
	v_mfma_f32_16x16x32_bf16 v[42:45], v[138:141], v[186:189], v[42:45]
	s_waitcnt lgkmcnt(3)
	v_mfma_f32_16x16x32_bf16 v[30:33], v[130:133], v[194:197], v[30:33]
	v_mfma_f32_16x16x32_bf16 v[26:29], v[138:141], v[194:197], v[26:29]
	s_waitcnt lgkmcnt(1)
	v_mfma_f32_16x16x32_bf16 v[14:17], v[130:133], v[202:205], v[14:17]
	v_mfma_f32_16x16x32_bf16 v[10:13], v[138:141], v[202:205], v[10:13]
	v_mfma_f32_16x16x32_bf16 v[62:65], v[134:137], v[170:173], v[62:65]
	v_mfma_f32_16x16x32_bf16 v[58:61], v[142:145], v[170:173], v[58:61]
	v_mfma_f32_16x16x32_bf16 v[46:49], v[134:137], v[190:193], v[46:49]
	v_mfma_f32_16x16x32_bf16 v[42:45], v[142:145], v[190:193], v[42:45]
	v_mfma_f32_16x16x32_bf16 v[30:33], v[134:137], v[198:201], v[30:33]
	v_mfma_f32_16x16x32_bf16 v[26:29], v[142:145], v[198:201], v[26:29]
	s_waitcnt lgkmcnt(0)
	v_mfma_f32_16x16x32_bf16 v[14:17], v[134:137], v[206:209], v[14:17]
	v_mfma_f32_16x16x32_bf16 v[10:13], v[142:145], v[206:209], v[10:13]
	s_setprio 0
	s_setprio 1
	v_mfma_f32_16x16x32_bf16 v[54:57], v[150:153], v[166:169], v[54:57]
	v_mfma_f32_16x16x32_bf16 v[50:53], v[158:161], v[166:169], v[50:53]
	v_mfma_f32_16x16x32_bf16 v[38:41], v[150:153], v[186:189], v[38:41]
	v_mfma_f32_16x16x32_bf16 v[34:37], v[158:161], v[186:189], v[34:37]
	v_mfma_f32_16x16x32_bf16 v[22:25], v[150:153], v[194:197], v[22:25]
	v_mfma_f32_16x16x32_bf16 v[18:21], v[158:161], v[194:197], v[18:21]
	v_mfma_f32_16x16x32_bf16 v[6:9], v[150:153], v[202:205], v[6:9]
	v_mfma_f32_16x16x32_bf16 v[2:5], v[158:161], v[202:205], v[2:5]
	v_mfma_f32_16x16x32_bf16 v[54:57], v[154:157], v[170:173], v[54:57]
	v_mfma_f32_16x16x32_bf16 v[50:53], v[162:165], v[170:173], v[50:53]
	v_mfma_f32_16x16x32_bf16 v[38:41], v[154:157], v[190:193], v[38:41]
	v_mfma_f32_16x16x32_bf16 v[34:37], v[162:165], v[190:193], v[34:37]
	v_mfma_f32_16x16x32_bf16 v[22:25], v[154:157], v[198:201], v[22:25]
	v_mfma_f32_16x16x32_bf16 v[18:21], v[162:165], v[198:201], v[18:21]
	s_setprio 2
	s_barrier
	v_mfma_f32_16x16x32_bf16 v[6:9], v[154:157], v[206:209], v[6:9]
	v_mfma_f32_16x16x32_bf16 v[2:5], v[162:165], v[206:209], v[2:5]
	s_setprio 0
	ds_read_b128 v[130:133], v184
	ds_read_b128 v[134:137], v184 offset:1024
	ds_read_b128 v[138:141], v184 offset:2048
	ds_read_b128 v[142:145], v184 offset:3072
	ds_read_b128 v[150:153], v185
	ds_read_b128 v[154:157], v185 offset:1024
	ds_read_b128 v[158:161], v185 offset:2048
	ds_read_b128 v[162:165], v185 offset:3072
	ds_read_b128 v[166:169], v183 offset:32768
	ds_read_b128 v[170:173], v183 offset:33792
	ds_read_b128 v[186:189], v183 offset:34816
	ds_read_b128 v[190:193], v183 offset:35840
	ds_read_b128 v[194:197], v183 offset:36864
	ds_read_b128 v[198:201], v183 offset:37888
	ds_read_b128 v[202:205], v183 offset:38912
	ds_read_b128 v[206:209], v183 offset:39936
	s_mov_b32 s79, m0
	s_mov_b32 m0, s34
	s_nop 0
	global_load_lds_dwordx4 v1, s[24:25]
	s_mov_b32 m0, s79
	s_nop 0
	s_mov_b32 s79, m0
	s_mov_b32 m0, s41
	s_nop 0
	global_load_lds_dwordx4 v177, s[24:25]
	s_mov_b32 m0, s79
	s_add_u32 s24, s24, 0x4000
	s_addc_u32 s25, s25, 0
	s_mov_b32 s79, m0
	s_mov_b32 m0, s42
	s_nop 0
	global_load_lds_dwordx4 v1, s[24:25]
	s_mov_b32 m0, s79
	s_nop 0
	s_mov_b32 s79, m0
	s_mov_b32 m0, s43
	s_nop 0
	global_load_lds_dwordx4 v177, s[24:25]
	s_mov_b32 m0, s79
	s_waitcnt vmcnt(8)
	s_waitcnt lgkmcnt(0)
	s_barrier
	s_setprio 1
	s_waitcnt lgkmcnt(7)
	v_mfma_f32_16x16x32_bf16 v[126:129], v[130:133], v[166:169], v[126:129]
	v_mfma_f32_16x16x32_bf16 v[122:125], v[138:141], v[166:169], v[122:125]
	s_waitcnt lgkmcnt(5)
	v_mfma_f32_16x16x32_bf16 v[118:121], v[130:133], v[186:189], v[118:121]
	v_mfma_f32_16x16x32_bf16 v[110:113], v[138:141], v[186:189], v[110:113]
	s_waitcnt lgkmcnt(3)
	v_mfma_f32_16x16x32_bf16 v[94:97], v[130:133], v[194:197], v[94:97]
	v_mfma_f32_16x16x32_bf16 v[90:93], v[138:141], v[194:197], v[90:93]
	s_waitcnt lgkmcnt(1)
	v_mfma_f32_16x16x32_bf16 v[86:89], v[130:133], v[202:205], v[86:89]
	v_mfma_f32_16x16x32_bf16 v[78:81], v[138:141], v[202:205], v[78:81]
	v_mfma_f32_16x16x32_bf16 v[126:129], v[134:137], v[170:173], v[126:129]
	v_mfma_f32_16x16x32_bf16 v[122:125], v[142:145], v[170:173], v[122:125]
	v_mfma_f32_16x16x32_bf16 v[118:121], v[134:137], v[190:193], v[118:121]
	v_mfma_f32_16x16x32_bf16 v[110:113], v[142:145], v[190:193], v[110:113]
	v_mfma_f32_16x16x32_bf16 v[94:97], v[134:137], v[198:201], v[94:97]
	v_mfma_f32_16x16x32_bf16 v[90:93], v[142:145], v[198:201], v[90:93]
	s_waitcnt lgkmcnt(0)
	v_mfma_f32_16x16x32_bf16 v[86:89], v[134:137], v[206:209], v[86:89]
	v_mfma_f32_16x16x32_bf16 v[78:81], v[142:145], v[206:209], v[78:81]
	s_setprio 0
	s_setprio 1
	v_mfma_f32_16x16x32_bf16 v[114:117], v[150:153], v[166:169], v[114:117]
	v_mfma_f32_16x16x32_bf16 v[106:109], v[158:161], v[166:169], v[106:109]
	v_mfma_f32_16x16x32_bf16 v[102:105], v[150:153], v[186:189], v[102:105]
	v_mfma_f32_16x16x32_bf16 v[98:101], v[158:161], v[186:189], v[98:101]
	v_mfma_f32_16x16x32_bf16 v[82:85], v[150:153], v[194:197], v[82:85]
	v_mfma_f32_16x16x32_bf16 v[74:77], v[158:161], v[194:197], v[74:77]
	v_mfma_f32_16x16x32_bf16 v[70:73], v[150:153], v[202:205], v[70:73]
	v_mfma_f32_16x16x32_bf16 v[66:69], v[158:161], v[202:205], v[66:69]
	v_mfma_f32_16x16x32_bf16 v[114:117], v[154:157], v[170:173], v[114:117]
	v_mfma_f32_16x16x32_bf16 v[106:109], v[162:165], v[170:173], v[106:109]
	v_mfma_f32_16x16x32_bf16 v[102:105], v[154:157], v[190:193], v[102:105]
	v_mfma_f32_16x16x32_bf16 v[98:101], v[162:165], v[190:193], v[98:101]
	v_mfma_f32_16x16x32_bf16 v[82:85], v[154:157], v[198:201], v[82:85]
	v_mfma_f32_16x16x32_bf16 v[74:77], v[162:165], v[198:201], v[74:77]
	s_setprio 2
	s_barrier
	v_mfma_f32_16x16x32_bf16 v[70:73], v[154:157], v[206:209], v[70:73]
	v_mfma_f32_16x16x32_bf16 v[66:69], v[162:165], v[206:209], v[66:69]
	s_setprio 0
	ds_read_b128 v[166:169], v183 offset:49152
	ds_read_b128 v[170:173], v183 offset:50176
	ds_read_b128 v[186:189], v183 offset:51200
	ds_read_b128 v[190:193], v183 offset:52224
	ds_read_b128 v[194:197], v183 offset:53248
	ds_read_b128 v[198:201], v183 offset:54272
	ds_read_b128 v[202:205], v183 offset:55296
	ds_read_b128 v[206:209], v183 offset:56320
	s_add_u32 s24, s22, 0x40000
	s_addc_u32 s25, s23, 0
	s_mov_b32 s79, m0
	s_mov_b32 m0, s46
	s_nop 0
	global_load_lds_dwordx4 v176, s[24:25]
	s_mov_b32 m0, s79
	s_add_u32 s22, s22, 0x44000
	s_mov_b32 s79, m0
	s_mov_b32 m0, s47
	s_nop 0
	global_load_lds_dwordx4 v178, s[24:25]
	s_mov_b32 m0, s79
	s_addc_u32 s23, s23, 0
	s_mov_b32 s24, m0
	s_mov_b32 m0, s48
	s_nop 0
	global_load_lds_dwordx4 v176, s[22:23]
	s_mov_b32 m0, s24
	s_nop 0
	s_mov_b32 s24, m0
	s_mov_b32 m0, s49
	s_nop 0
	global_load_lds_dwordx4 v178, s[22:23]
	s_mov_b32 m0, s24
	s_waitcnt vmcnt(4)
	s_waitcnt lgkmcnt(0)
	s_barrier
	s_setprio 1
	s_waitcnt lgkmcnt(7)
	v_mfma_f32_16x16x32_bf16 v[62:65], v[130:133], v[166:169], v[62:65]
	v_mfma_f32_16x16x32_bf16 v[58:61], v[138:141], v[166:169], v[58:61]
	s_waitcnt lgkmcnt(5)
	v_mfma_f32_16x16x32_bf16 v[46:49], v[130:133], v[186:189], v[46:49]
	v_mfma_f32_16x16x32_bf16 v[42:45], v[138:141], v[186:189], v[42:45]
	s_waitcnt lgkmcnt(3)
	v_mfma_f32_16x16x32_bf16 v[30:33], v[130:133], v[194:197], v[30:33]
	v_mfma_f32_16x16x32_bf16 v[26:29], v[138:141], v[194:197], v[26:29]
	s_waitcnt lgkmcnt(1)
	v_mfma_f32_16x16x32_bf16 v[14:17], v[130:133], v[202:205], v[14:17]
	v_mfma_f32_16x16x32_bf16 v[10:13], v[138:141], v[202:205], v[10:13]
	v_mfma_f32_16x16x32_bf16 v[62:65], v[134:137], v[170:173], v[62:65]
	v_mfma_f32_16x16x32_bf16 v[58:61], v[142:145], v[170:173], v[58:61]
	v_mfma_f32_16x16x32_bf16 v[46:49], v[134:137], v[190:193], v[46:49]
	v_mfma_f32_16x16x32_bf16 v[42:45], v[142:145], v[190:193], v[42:45]
	v_mfma_f32_16x16x32_bf16 v[30:33], v[134:137], v[198:201], v[30:33]
	v_mfma_f32_16x16x32_bf16 v[26:29], v[142:145], v[198:201], v[26:29]
	s_waitcnt lgkmcnt(0)
	v_mfma_f32_16x16x32_bf16 v[14:17], v[134:137], v[206:209], v[14:17]
	v_mfma_f32_16x16x32_bf16 v[10:13], v[142:145], v[206:209], v[10:13]
	s_setprio 0
	s_setprio 1
	v_mfma_f32_16x16x32_bf16 v[54:57], v[150:153], v[166:169], v[54:57]
	v_mfma_f32_16x16x32_bf16 v[50:53], v[158:161], v[166:169], v[50:53]
	v_mfma_f32_16x16x32_bf16 v[38:41], v[150:153], v[186:189], v[38:41]
	v_mfma_f32_16x16x32_bf16 v[34:37], v[158:161], v[186:189], v[34:37]
	v_mfma_f32_16x16x32_bf16 v[22:25], v[150:153], v[194:197], v[22:25]
	v_mfma_f32_16x16x32_bf16 v[18:21], v[158:161], v[194:197], v[18:21]
	v_mfma_f32_16x16x32_bf16 v[6:9], v[150:153], v[202:205], v[6:9]
	v_mfma_f32_16x16x32_bf16 v[2:5], v[158:161], v[202:205], v[2:5]
	v_mfma_f32_16x16x32_bf16 v[54:57], v[154:157], v[170:173], v[54:57]
	v_mfma_f32_16x16x32_bf16 v[50:53], v[162:165], v[170:173], v[50:53]
	v_mfma_f32_16x16x32_bf16 v[38:41], v[154:157], v[190:193], v[38:41]
	v_mfma_f32_16x16x32_bf16 v[34:37], v[162:165], v[190:193], v[34:37]
	v_mfma_f32_16x16x32_bf16 v[22:25], v[154:157], v[198:201], v[22:25]
	v_mfma_f32_16x16x32_bf16 v[18:21], v[162:165], v[198:201], v[18:21]
	s_setprio 2
	s_barrier
	v_mfma_f32_16x16x32_bf16 v[6:9], v[154:157], v[206:209], v[6:9]
	v_mfma_f32_16x16x32_bf16 v[2:5], v[162:165], v[206:209], v[2:5]
	s_setprio 0
	s_add_i32 s78, s78, 2
	s_add_u32 s74, s74, 0x80000
	s_addc_u32 s75, s75, 0
	s_add_u32 s20, s20, 0x400000
	s_addc_u32 s21, s21, 0
	s_add_u32 s76, s76, 0x400000
	s_addc_u32 s77, s77, 0
	s_cmpk_gt_u32 s78, 0x53
	s_cbranch_scc0 .LBB0_1357
	s_and_b64 vcc, exec, s[8:9]
	s_cbranch_vccz .LBB0_1360
	s_barrier

.LBB0_1538:
	ds_read_b128 v[46:49], v182
	ds_read_b128 v[54:57], v182 offset:1024
	ds_read_b128 v[58:61], v182 offset:2048
	ds_read_b128 v[62:65], v182 offset:3072
	ds_read_b128 v[146:149], v183
	ds_read_b128 v[150:153], v183 offset:1024
	ds_read_b128 v[154:157], v183 offset:2048
	ds_read_b128 v[158:161], v183 offset:3072
	s_cmp_eq_u32 s83, 28
	s_cselect_b32 s35, s21, s80
	s_cselect_b32 s34, s29, s79
	s_cselect_b32 s37, s7, s82
	s_cselect_b32 s36, s23, s81
	ds_read_b128 v[170:173], v184
	ds_read_b128 v[188:191], v184 offset:1024
	ds_read_b128 v[192:195], v184 offset:2048
	ds_read_b128 v[196:199], v184 offset:3072
	ds_read_b128 v[200:203], v184 offset:4096
	ds_read_b128 v[204:207], v184 offset:5120
	ds_read_b128 v[208:211], v184 offset:6144
	ds_read_b128 v[212:215], v184 offset:7168
	s_add_u32 s86, s30, 0xfff80000
	s_addc_u32 s87, s31, -1
	s_mov_b32 s92, m0
	s_mov_b32 m0, s73
	s_nop 0
	global_load_lds_dwordx4 v176, s[86:87]
	s_mov_b32 m0, s92
	s_nop 0
	s_mov_b32 s92, m0
	s_mov_b32 m0, s75
	s_nop 0
	global_load_lds_dwordx4 v178, s[86:87]
	s_mov_b32 m0, s92
	s_mov_b32 s86, m0
	s_mov_b32 m0, s74
	s_nop 0
	global_load_lds_dwordx4 v176, s[30:31]
	s_mov_b32 m0, s86
	s_nop 0
	s_mov_b32 s86, m0
	s_mov_b32 m0, s76
	s_nop 0
	global_load_lds_dwordx4 v178, s[30:31]
	s_mov_b32 m0, s86
	s_waitcnt vmcnt(8)
	s_waitcnt lgkmcnt(0)
	s_barrier
	s_setprio 1
	s_waitcnt lgkmcnt(7)
	v_mfma_f32_16x16x32_bf16 v[142:145], v[46:49], v[170:173], v[142:145]
	v_mfma_f32_16x16x32_bf16 v[138:141], v[58:61], v[170:173], v[138:141]
	s_waitcnt lgkmcnt(5)
	v_mfma_f32_16x16x32_bf16 v[126:129], v[46:49], v[192:195], v[126:129]
	v_mfma_f32_16x16x32_bf16 v[122:125], v[58:61], v[192:195], v[122:125]
	s_waitcnt lgkmcnt(3)
	v_mfma_f32_16x16x32_bf16 v[110:113], v[46:49], v[200:203], v[110:113]
	v_mfma_f32_16x16x32_bf16 v[106:109], v[58:61], v[200:203], v[106:109]
	s_waitcnt lgkmcnt(1)
	v_mfma_f32_16x16x32_bf16 v[94:97], v[46:49], v[208:211], v[94:97]
	v_mfma_f32_16x16x32_bf16 v[90:93], v[58:61], v[208:211], v[90:93]
	v_mfma_f32_16x16x32_bf16 v[142:145], v[54:57], v[188:191], v[142:145]
	v_mfma_f32_16x16x32_bf16 v[138:141], v[62:65], v[188:191], v[138:141]
	v_mfma_f32_16x16x32_bf16 v[126:129], v[54:57], v[196:199], v[126:129]
	v_mfma_f32_16x16x32_bf16 v[122:125], v[62:65], v[196:199], v[122:125]
	v_mfma_f32_16x16x32_bf16 v[110:113], v[54:57], v[204:207], v[110:113]
	v_mfma_f32_16x16x32_bf16 v[106:109], v[62:65], v[204:207], v[106:109]
	s_waitcnt lgkmcnt(0)
	v_mfma_f32_16x16x32_bf16 v[94:97], v[54:57], v[212:215], v[94:97]
	v_mfma_f32_16x16x32_bf16 v[90:93], v[62:65], v[212:215], v[90:93]
	s_setprio 0
	s_setprio 1
	v_mfma_f32_16x16x32_bf16 v[134:137], v[146:149], v[170:173], v[134:137]
	v_mfma_f32_16x16x32_bf16 v[130:133], v[154:157], v[170:173], v[130:133]
	v_mfma_f32_16x16x32_bf16 v[118:121], v[146:149], v[192:195], v[118:121]
	v_mfma_f32_16x16x32_bf16 v[114:117], v[154:157], v[192:195], v[114:117]
	v_mfma_f32_16x16x32_bf16 v[102:105], v[146:149], v[200:203], v[102:105]
	v_mfma_f32_16x16x32_bf16 v[98:101], v[154:157], v[200:203], v[98:101]
	v_mfma_f32_16x16x32_bf16 v[86:89], v[146:149], v[208:211], v[86:89]
	v_mfma_f32_16x16x32_bf16 v[82:85], v[154:157], v[208:211], v[82:85]
	v_mfma_f32_16x16x32_bf16 v[134:137], v[150:153], v[188:191], v[134:137]
	v_mfma_f32_16x16x32_bf16 v[130:133], v[158:161], v[188:191], v[130:133]
	v_mfma_f32_16x16x32_bf16 v[118:121], v[150:153], v[196:199], v[118:121]
	v_mfma_f32_16x16x32_bf16 v[114:117], v[158:161], v[196:199], v[114:117]
	v_mfma_f32_16x16x32_bf16 v[102:105], v[150:153], v[204:207], v[102:105]
	v_mfma_f32_16x16x32_bf16 v[98:101], v[158:161], v[204:207], v[98:101]
	s_setprio 2
	s_barrier
	v_mfma_f32_16x16x32_bf16 v[86:89], v[150:153], v[212:215], v[86:89]
	v_mfma_f32_16x16x32_bf16 v[82:85], v[158:161], v[212:215], v[82:85]
	s_setprio 0
	ds_read_b128 v[170:173], v184 offset:16384
	ds_read_b128 v[188:191], v184 offset:17408
	ds_read_b128 v[192:195], v184 offset:18432
	ds_read_b128 v[196:199], v184 offset:19456
	ds_read_b128 v[200:203], v184 offset:20480
	ds_read_b128 v[204:207], v184 offset:21504
	ds_read_b128 v[208:211], v184 offset:22528
	ds_read_b128 v[212:215], v184 offset:23552
	s_mov_b32 s86, m0
	s_mov_b32 m0, s49
	s_nop 0
	global_load_lds_dwordx4 v177, s[34:35]
	s_mov_b32 m0, s86
	s_nop 0
	s_mov_b32 s86, m0
	s_mov_b32 m0, s56
	s_nop 0
	global_load_lds_dwordx4 v179, s[34:35]
	s_mov_b32 m0, s86
	s_add_u32 s86, s34, 0x80000
	s_addc_u32 s87, s35, 0
	s_mov_b32 s92, m0
	s_mov_b32 m0, s57
	s_nop 0
	global_load_lds_dwordx4 v177, s[86:87]
	s_mov_b32 m0, s92
	s_nop 0
	s_mov_b32 s92, m0
	s_mov_b32 m0, s58
	s_nop 0
	global_load_lds_dwordx4 v179, s[86:87]
	s_mov_b32 m0, s92
	s_waitcnt vmcnt(4)
	s_waitcnt lgkmcnt(0)
	s_barrier
	s_setprio 1
	s_waitcnt lgkmcnt(7)
	v_mfma_f32_16x16x32_bf16 v[78:81], v[46:49], v[170:173], v[78:81]
	v_mfma_f32_16x16x32_bf16 v[74:77], v[58:61], v[170:173], v[74:77]
	s_waitcnt lgkmcnt(5)
	v_mfma_f32_16x16x32_bf16 v[50:53], v[46:49], v[192:195], v[50:53]
	v_mfma_f32_16x16x32_bf16 v[42:45], v[58:61], v[192:195], v[42:45]
	s_waitcnt lgkmcnt(3)
	v_mfma_f32_16x16x32_bf16 v[30:33], v[46:49], v[200:203], v[30:33]
	v_mfma_f32_16x16x32_bf16 v[26:29], v[58:61], v[200:203], v[26:29]
	s_waitcnt lgkmcnt(1)
	v_mfma_f32_16x16x32_bf16 v[14:17], v[46:49], v[208:211], v[14:17]
	v_mfma_f32_16x16x32_bf16 v[10:13], v[58:61], v[208:211], v[10:13]
	v_mfma_f32_16x16x32_bf16 v[78:81], v[54:57], v[188:191], v[78:81]
	v_mfma_f32_16x16x32_bf16 v[74:77], v[62:65], v[188:191], v[74:77]
	v_mfma_f32_16x16x32_bf16 v[50:53], v[54:57], v[196:199], v[50:53]
	v_mfma_f32_16x16x32_bf16 v[42:45], v[62:65], v[196:199], v[42:45]
	v_mfma_f32_16x16x32_bf16 v[30:33], v[54:57], v[204:207], v[30:33]
	v_mfma_f32_16x16x32_bf16 v[26:29], v[62:65], v[204:207], v[26:29]
	s_waitcnt lgkmcnt(0)
	v_mfma_f32_16x16x32_bf16 v[14:17], v[54:57], v[212:215], v[14:17]
	v_mfma_f32_16x16x32_bf16 v[10:13], v[62:65], v[212:215], v[10:13]
	s_setprio 0
	s_setprio 1
	v_mfma_f32_16x16x32_bf16 v[38:41], v[146:149], v[192:195], v[38:41]
	v_mfma_f32_16x16x32_bf16 v[34:37], v[154:157], v[192:195], v[34:37]
	v_mfma_f32_16x16x32_bf16 v[22:25], v[146:149], v[200:203], v[22:25]
	v_mfma_f32_16x16x32_bf16 v[18:21], v[154:157], v[200:203], v[18:21]
	v_mfma_f32_16x16x32_bf16 v[6:9], v[146:149], v[208:211], v[6:9]
	v_mfma_f32_16x16x32_bf16 v[2:5], v[154:157], v[208:211], v[2:5]
	v_mfma_f32_16x16x32_bf16 v[46:49], v[146:149], v[170:173], v[70:73]
	v_mfma_f32_16x16x32_bf16 v[54:57], v[154:157], v[170:173], v[66:69]
	v_mfma_f32_16x16x32_bf16 v[38:41], v[150:153], v[196:199], v[38:41]
	v_mfma_f32_16x16x32_bf16 v[34:37], v[158:161], v[196:199], v[34:37]
	v_mfma_f32_16x16x32_bf16 v[22:25], v[150:153], v[204:207], v[22:25]
	v_mfma_f32_16x16x32_bf16 v[18:21], v[158:161], v[204:207], v[18:21]
	v_mfma_f32_16x16x32_bf16 v[6:9], v[150:153], v[212:215], v[6:9]
	v_mfma_f32_16x16x32_bf16 v[2:5], v[158:161], v[212:215], v[2:5]
	s_setprio 2
	s_barrier
	v_mfma_f32_16x16x32_bf16 v[46:49], v[150:153], v[188:191], v[46:49]
	v_mfma_f32_16x16x32_bf16 v[54:57], v[158:161], v[188:191], v[54:57]
	s_setprio 0
	ds_read_b128 v[58:61], v185
	ds_read_b128 v[62:65], v185 offset:1024
	ds_read_b128 v[66:69], v185 offset:2048
	ds_read_b128 v[70:73], v185 offset:3072
	ds_read_b128 v[146:149], v186
	ds_read_b128 v[150:153], v186 offset:1024
	ds_read_b128 v[154:157], v186 offset:2048
	ds_read_b128 v[158:161], v186 offset:3072
	ds_read_b128 v[170:173], v184 offset:32768
	ds_read_b128 v[188:191], v184 offset:33792
	ds_read_b128 v[192:195], v184 offset:34816
	ds_read_b128 v[196:199], v184 offset:35840
	ds_read_b128 v[200:203], v184 offset:36864
	ds_read_b128 v[204:207], v184 offset:37888
	ds_read_b128 v[208:211], v184 offset:38912
	ds_read_b128 v[212:215], v184 offset:39936
	s_mov_b32 s86, m0
	s_mov_b32 m0, s48
	s_nop 0
	global_load_lds_dwordx4 v176, s[36:37]
	s_mov_b32 m0, s86
	s_nop 0
	s_mov_b32 s86, m0
	s_mov_b32 m0, s59
	s_nop 0
	global_load_lds_dwordx4 v178, s[36:37]
	s_mov_b32 m0, s86
	s_add_u32 s36, s36, 0x80000
	s_addc_u32 s37, s37, 0
	s_mov_b32 s86, m0
	s_mov_b32 m0, s62
	s_nop 0
	global_load_lds_dwordx4 v176, s[36:37]
	s_mov_b32 m0, s86
	s_nop 0
	s_mov_b32 s86, m0
	s_mov_b32 m0, s63
	s_nop 0
	global_load_lds_dwordx4 v178, s[36:37]
	s_mov_b32 m0, s86
	s_waitcnt vmcnt(8)
	s_waitcnt lgkmcnt(0)
	s_barrier
	s_setprio 1
	s_waitcnt lgkmcnt(7)
	v_mfma_f32_16x16x32_bf16 v[142:145], v[58:61], v[170:173], v[142:145]
	v_mfma_f32_16x16x32_bf16 v[138:141], v[66:69], v[170:173], v[138:141]
	s_waitcnt lgkmcnt(5)
	v_mfma_f32_16x16x32_bf16 v[126:129], v[58:61], v[192:195], v[126:129]
	v_mfma_f32_16x16x32_bf16 v[122:125], v[66:69], v[192:195], v[122:125]
	s_waitcnt lgkmcnt(3)
	v_mfma_f32_16x16x32_bf16 v[110:113], v[58:61], v[200:203], v[110:113]
	v_mfma_f32_16x16x32_bf16 v[106:109], v[66:69], v[200:203], v[106:109]
	s_waitcnt lgkmcnt(1)
	v_mfma_f32_16x16x32_bf16 v[94:97], v[58:61], v[208:211], v[94:97]
	v_mfma_f32_16x16x32_bf16 v[90:93], v[66:69], v[208:211], v[90:93]
	v_mfma_f32_16x16x32_bf16 v[142:145], v[62:65], v[188:191], v[142:145]
	v_mfma_f32_16x16x32_bf16 v[138:141], v[70:73], v[188:191], v[138:141]
	v_mfma_f32_16x16x32_bf16 v[126:129], v[62:65], v[196:199], v[126:129]
	v_mfma_f32_16x16x32_bf16 v[122:125], v[70:73], v[196:199], v[122:125]
	v_mfma_f32_16x16x32_bf16 v[110:113], v[62:65], v[204:207], v[110:113]
	v_mfma_f32_16x16x32_bf16 v[106:109], v[70:73], v[204:207], v[106:109]
	s_waitcnt lgkmcnt(0)
	v_mfma_f32_16x16x32_bf16 v[94:97], v[62:65], v[212:215], v[94:97]
	v_mfma_f32_16x16x32_bf16 v[90:93], v[70:73], v[212:215], v[90:93]
	s_setprio 0
	s_setprio 1
	v_mfma_f32_16x16x32_bf16 v[134:137], v[146:149], v[170:173], v[134:137]
	v_mfma_f32_16x16x32_bf16 v[130:133], v[154:157], v[170:173], v[130:133]
	v_mfma_f32_16x16x32_bf16 v[118:121], v[146:149], v[192:195], v[118:121]
	v_mfma_f32_16x16x32_bf16 v[114:117], v[154:157], v[192:195], v[114:117]
	v_mfma_f32_16x16x32_bf16 v[102:105], v[146:149], v[200:203], v[102:105]
	v_mfma_f32_16x16x32_bf16 v[98:101], v[154:157], v[200:203], v[98:101]
	v_mfma_f32_16x16x32_bf16 v[86:89], v[146:149], v[208:211], v[86:89]
	v_mfma_f32_16x16x32_bf16 v[82:85], v[154:157], v[208:211], v[82:85]
	v_mfma_f32_16x16x32_bf16 v[134:137], v[150:153], v[188:191], v[134:137]
	v_mfma_f32_16x16x32_bf16 v[130:133], v[158:161], v[188:191], v[130:133]
	v_mfma_f32_16x16x32_bf16 v[118:121], v[150:153], v[196:199], v[118:121]
	v_mfma_f32_16x16x32_bf16 v[114:117], v[158:161], v[196:199], v[114:117]
	v_mfma_f32_16x16x32_bf16 v[102:105], v[150:153], v[204:207], v[102:105]
	v_mfma_f32_16x16x32_bf16 v[98:101], v[158:161], v[204:207], v[98:101]
	s_setprio 2
	s_barrier
	v_mfma_f32_16x16x32_bf16 v[86:89], v[150:153], v[212:215], v[86:89]
	v_mfma_f32_16x16x32_bf16 v[82:85], v[158:161], v[212:215], v[82:85]
	s_setprio 0
	ds_read_b128 v[170:173], v184 offset:49152
	ds_read_b128 v[188:191], v184 offset:50176
	ds_read_b128 v[192:195], v184 offset:51200
	ds_read_b128 v[196:199], v184 offset:52224
	ds_read_b128 v[200:203], v184 offset:53248
	ds_read_b128 v[204:207], v184 offset:54272
	ds_read_b128 v[208:211], v184 offset:55296
	ds_read_b128 v[212:215], v184 offset:56320
	s_add_u32 s36, s34, 0x80
	s_addc_u32 s37, s35, 0
	s_mov_b32 s86, m0
	s_mov_b32 m0, s64
	s_nop 0
	global_load_lds_dwordx4 v177, s[36:37]
	s_mov_b32 m0, s86
	s_add_u32 s34, s34, 0x80080
	s_mov_b32 s86, m0
	s_mov_b32 m0, s65
	s_nop 0
	global_load_lds_dwordx4 v179, s[36:37]
	s_mov_b32 m0, s86
	s_addc_u32 s35, s35, 0
	s_mov_b32 s36, m0
	s_mov_b32 m0, s66
	s_nop 0
	global_load_lds_dwordx4 v177, s[34:35]
	s_mov_b32 m0, s36
	s_nop 0
	s_mov_b32 s36, m0
	s_mov_b32 m0, s67
	s_nop 0
	global_load_lds_dwordx4 v179, s[34:35]
	s_mov_b32 m0, s36
	s_waitcnt vmcnt(4)
	s_waitcnt lgkmcnt(0)
	s_barrier
	s_setprio 1
	s_waitcnt lgkmcnt(7)
	v_mfma_f32_16x16x32_bf16 v[78:81], v[58:61], v[170:173], v[78:81]
	v_mfma_f32_16x16x32_bf16 v[74:77], v[66:69], v[170:173], v[74:77]
	s_waitcnt lgkmcnt(5)
	v_mfma_f32_16x16x32_bf16 v[50:53], v[58:61], v[192:195], v[50:53]
	v_mfma_f32_16x16x32_bf16 v[42:45], v[66:69], v[192:195], v[42:45]
	s_waitcnt lgkmcnt(3)
	v_mfma_f32_16x16x32_bf16 v[30:33], v[58:61], v[200:203], v[30:33]
	v_mfma_f32_16x16x32_bf16 v[26:29], v[66:69], v[200:203], v[26:29]
	s_waitcnt lgkmcnt(1)
	v_mfma_f32_16x16x32_bf16 v[14:17], v[58:61], v[208:211], v[14:17]
	v_mfma_f32_16x16x32_bf16 v[10:13], v[66:69], v[208:211], v[10:13]
	v_mfma_f32_16x16x32_bf16 v[78:81], v[62:65], v[188:191], v[78:81]
	v_mfma_f32_16x16x32_bf16 v[74:77], v[70:73], v[188:191], v[74:77]
	v_mfma_f32_16x16x32_bf16 v[50:53], v[62:65], v[196:199], v[50:53]
	v_mfma_f32_16x16x32_bf16 v[42:45], v[70:73], v[196:199], v[42:45]
	v_mfma_f32_16x16x32_bf16 v[30:33], v[62:65], v[204:207], v[30:33]
	v_mfma_f32_16x16x32_bf16 v[26:29], v[70:73], v[204:207], v[26:29]
	s_waitcnt lgkmcnt(0)
	v_mfma_f32_16x16x32_bf16 v[14:17], v[62:65], v[212:215], v[14:17]
	v_mfma_f32_16x16x32_bf16 v[10:13], v[70:73], v[212:215], v[10:13]
	s_setprio 0
	s_setprio 1
	v_mfma_f32_16x16x32_bf16 v[46:49], v[146:149], v[170:173], v[46:49]
	v_mfma_f32_16x16x32_bf16 v[70:73], v[150:153], v[188:191], v[46:49]
	v_mfma_f32_16x16x32_bf16 v[46:49], v[154:157], v[170:173], v[54:57]
	v_mfma_f32_16x16x32_bf16 v[38:41], v[146:149], v[192:195], v[38:41]
	v_mfma_f32_16x16x32_bf16 v[34:37], v[154:157], v[192:195], v[34:37]
	v_mfma_f32_16x16x32_bf16 v[22:25], v[146:149], v[200:203], v[22:25]
	v_mfma_f32_16x16x32_bf16 v[18:21], v[154:157], v[200:203], v[18:21]
	v_mfma_f32_16x16x32_bf16 v[6:9], v[146:149], v[208:211], v[6:9]
	v_mfma_f32_16x16x32_bf16 v[2:5], v[154:157], v[208:211], v[2:5]
	v_mfma_f32_16x16x32_bf16 v[66:69], v[158:161], v[188:191], v[46:49]
	v_mfma_f32_16x16x32_bf16 v[38:41], v[150:153], v[196:199], v[38:41]
	v_mfma_f32_16x16x32_bf16 v[34:37], v[158:161], v[196:199], v[34:37]
	v_mfma_f32_16x16x32_bf16 v[22:25], v[150:153], v[204:207], v[22:25]
	v_mfma_f32_16x16x32_bf16 v[18:21], v[158:161], v[204:207], v[18:21]
	s_setprio 2
	s_barrier
	v_mfma_f32_16x16x32_bf16 v[6:9], v[150:153], v[212:215], v[6:9]
	v_mfma_f32_16x16x32_bf16 v[2:5], v[158:161], v[212:215], v[2:5]
	s_setprio 0
	s_add_i32 s83, s83, 2
	s_add_u32 s79, s79, 0x100
	s_addc_u32 s80, s80, 0
	s_add_u32 s30, s30, 0x100
	s_addc_u32 s31, s31, 0
	s_add_u32 s81, s81, 0x100
	s_addc_u32 s82, s82, 0
	s_cmp_gt_u32 s83, 29
	s_cbranch_scc0 .LBB0_1538
	s_and_b64 vcc, exec, s[16:17]
	s_cbranch_vccz .LBB0_1541
	s_barrier

.LBB0_1785:
	ds_read_b128 v[148:151], v143
	ds_read_b128 v[152:155], v143 offset:1024
	ds_read_b128 v[156:159], v143 offset:2048
	ds_read_b128 v[160:163], v143 offset:3072
	ds_read_b128 v[164:167], v144
	ds_read_b128 v[168:171], v144 offset:1024
	ds_read_b128 v[172:175], v144 offset:2048
	ds_read_b128 v[176:179], v144 offset:3072
	s_cmp_eq_u32 s73, 28
	s_cselect_b32 s21, s9, s67
	s_cselect_b32 s20, s65, s66
	s_cselect_b32 s23, s11, s71
	s_cselect_b32 s22, s64, s70
	ds_read_b128 v[180:183], v145
	ds_read_b128 v[184:187], v145 offset:1024
	ds_read_b128 v[188:191], v145 offset:2048
	ds_read_b128 v[192:195], v145 offset:3072
	ds_read_b128 v[196:199], v145 offset:4096
	ds_read_b128 v[200:203], v145 offset:5120
	ds_read_b128 v[204:207], v145 offset:6144
	ds_read_b128 v[208:211], v145 offset:7168
	s_add_u32 s74, s18, 0xfff80000
	s_addc_u32 s75, s19, -1
	s_mov_b32 s76, m0
	s_mov_b32 m0, s56
	s_nop 0
	global_load_lds_dwordx4 v138, s[74:75]
	s_mov_b32 m0, s76
	s_nop 0
	s_mov_b32 s76, m0
	s_mov_b32 m0, s59
	s_nop 0
	global_load_lds_dwordx4 v140, s[74:75]
	s_mov_b32 m0, s76
	s_mov_b32 s74, m0
	s_mov_b32 m0, s57
	s_nop 0
	global_load_lds_dwordx4 v138, s[18:19]
	s_mov_b32 m0, s74
	s_nop 0
	s_mov_b32 s74, m0
	s_mov_b32 m0, s62
	s_nop 0
	global_load_lds_dwordx4 v140, s[18:19]
	s_mov_b32 m0, s74
	s_waitcnt vmcnt(8)
	s_waitcnt lgkmcnt(0)
	s_barrier
	s_setprio 1
	s_waitcnt lgkmcnt(7)
	v_mfma_f32_16x16x32_bf16 v[126:129], v[148:151], v[180:183], v[126:129]
	v_mfma_f32_16x16x32_bf16 v[122:125], v[156:159], v[180:183], v[122:125]
	s_waitcnt lgkmcnt(5)
	v_mfma_f32_16x16x32_bf16 v[110:113], v[148:151], v[188:191], v[110:113]
	v_mfma_f32_16x16x32_bf16 v[106:109], v[156:159], v[188:191], v[106:109]
	s_waitcnt lgkmcnt(3)
	v_mfma_f32_16x16x32_bf16 v[94:97], v[148:151], v[196:199], v[94:97]
	v_mfma_f32_16x16x32_bf16 v[90:93], v[156:159], v[196:199], v[90:93]
	s_waitcnt lgkmcnt(1)
	v_mfma_f32_16x16x32_bf16 v[78:81], v[148:151], v[204:207], v[78:81]
	v_mfma_f32_16x16x32_bf16 v[74:77], v[156:159], v[204:207], v[74:77]
	v_mfma_f32_16x16x32_bf16 v[126:129], v[152:155], v[184:187], v[126:129]
	v_mfma_f32_16x16x32_bf16 v[122:125], v[160:163], v[184:187], v[122:125]
	v_mfma_f32_16x16x32_bf16 v[110:113], v[152:155], v[192:195], v[110:113]
	v_mfma_f32_16x16x32_bf16 v[106:109], v[160:163], v[192:195], v[106:109]
	v_mfma_f32_16x16x32_bf16 v[94:97], v[152:155], v[200:203], v[94:97]
	v_mfma_f32_16x16x32_bf16 v[90:93], v[160:163], v[200:203], v[90:93]
	s_waitcnt lgkmcnt(0)
	v_mfma_f32_16x16x32_bf16 v[78:81], v[152:155], v[208:211], v[78:81]
	v_mfma_f32_16x16x32_bf16 v[74:77], v[160:163], v[208:211], v[74:77]
	s_setprio 0
	s_setprio 1
	v_mfma_f32_16x16x32_bf16 v[118:121], v[164:167], v[180:183], v[118:121]
	v_mfma_f32_16x16x32_bf16 v[114:117], v[172:175], v[180:183], v[114:117]
	v_mfma_f32_16x16x32_bf16 v[102:105], v[164:167], v[188:191], v[102:105]
	v_mfma_f32_16x16x32_bf16 v[98:101], v[172:175], v[188:191], v[98:101]
	v_mfma_f32_16x16x32_bf16 v[86:89], v[164:167], v[196:199], v[86:89]
	v_mfma_f32_16x16x32_bf16 v[82:85], v[172:175], v[196:199], v[82:85]
	v_mfma_f32_16x16x32_bf16 v[70:73], v[164:167], v[204:207], v[70:73]
	v_mfma_f32_16x16x32_bf16 v[66:69], v[172:175], v[204:207], v[66:69]
	v_mfma_f32_16x16x32_bf16 v[118:121], v[168:171], v[184:187], v[118:121]
	v_mfma_f32_16x16x32_bf16 v[114:117], v[176:179], v[184:187], v[114:117]
	v_mfma_f32_16x16x32_bf16 v[102:105], v[168:171], v[192:195], v[102:105]
	v_mfma_f32_16x16x32_bf16 v[98:101], v[176:179], v[192:195], v[98:101]
	v_mfma_f32_16x16x32_bf16 v[86:89], v[168:171], v[200:203], v[86:89]
	v_mfma_f32_16x16x32_bf16 v[82:85], v[176:179], v[200:203], v[82:85]
	s_setprio 2
	s_barrier
	v_mfma_f32_16x16x32_bf16 v[70:73], v[168:171], v[208:211], v[70:73]
	v_mfma_f32_16x16x32_bf16 v[66:69], v[176:179], v[208:211], v[66:69]
	s_setprio 0
	ds_read_b128 v[180:183], v145 offset:16384
	ds_read_b128 v[184:187], v145 offset:17408
	ds_read_b128 v[188:191], v145 offset:18432
	ds_read_b128 v[192:195], v145 offset:19456
	ds_read_b128 v[196:199], v145 offset:20480
	ds_read_b128 v[200:203], v145 offset:21504
	ds_read_b128 v[204:207], v145 offset:22528
	ds_read_b128 v[208:211], v145 offset:23552
	s_mov_b32 s74, m0
	s_mov_b32 m0, s35
	s_nop 0
	global_load_lds_dwordx4 v139, s[20:21]
	s_mov_b32 m0, s74
	s_nop 0
	s_mov_b32 s74, m0
	s_mov_b32 m0, s36
	s_nop 0
	global_load_lds_dwordx4 v141, s[20:21]
	s_mov_b32 m0, s74
	s_add_u32 s74, s20, 0x80000
	s_addc_u32 s75, s21, 0
	s_mov_b32 s76, m0
	s_mov_b32 m0, s37
	s_nop 0
	global_load_lds_dwordx4 v139, s[74:75]
	s_mov_b32 m0, s76
	s_nop 0
	s_mov_b32 s76, m0
	s_mov_b32 m0, s40
	s_nop 0
	global_load_lds_dwordx4 v141, s[74:75]
	s_mov_b32 m0, s76
	s_waitcnt vmcnt(4)
	s_waitcnt lgkmcnt(0)
	s_barrier
	s_setprio 1
	s_waitcnt lgkmcnt(7)
	v_mfma_f32_16x16x32_bf16 v[62:65], v[148:151], v[180:183], v[62:65]
	v_mfma_f32_16x16x32_bf16 v[58:61], v[156:159], v[180:183], v[58:61]
	s_waitcnt lgkmcnt(5)
	v_mfma_f32_16x16x32_bf16 v[46:49], v[148:151], v[188:191], v[46:49]
	v_mfma_f32_16x16x32_bf16 v[42:45], v[156:159], v[188:191], v[42:45]
	s_waitcnt lgkmcnt(3)
	v_mfma_f32_16x16x32_bf16 v[30:33], v[148:151], v[196:199], v[30:33]
	v_mfma_f32_16x16x32_bf16 v[26:29], v[156:159], v[196:199], v[26:29]
	s_waitcnt lgkmcnt(1)
	v_mfma_f32_16x16x32_bf16 v[14:17], v[148:151], v[204:207], v[14:17]
	v_mfma_f32_16x16x32_bf16 v[10:13], v[156:159], v[204:207], v[10:13]
	v_mfma_f32_16x16x32_bf16 v[62:65], v[152:155], v[184:187], v[62:65]
	v_mfma_f32_16x16x32_bf16 v[58:61], v[160:163], v[184:187], v[58:61]
	v_mfma_f32_16x16x32_bf16 v[46:49], v[152:155], v[192:195], v[46:49]
	v_mfma_f32_16x16x32_bf16 v[42:45], v[160:163], v[192:195], v[42:45]
	v_mfma_f32_16x16x32_bf16 v[30:33], v[152:155], v[200:203], v[30:33]
	v_mfma_f32_16x16x32_bf16 v[26:29], v[160:163], v[200:203], v[26:29]
	s_waitcnt lgkmcnt(0)
	v_mfma_f32_16x16x32_bf16 v[14:17], v[152:155], v[208:211], v[14:17]
	v_mfma_f32_16x16x32_bf16 v[10:13], v[160:163], v[208:211], v[10:13]
	s_setprio 0
	s_setprio 1
	v_mfma_f32_16x16x32_bf16 v[54:57], v[164:167], v[180:183], v[54:57]
	v_mfma_f32_16x16x32_bf16 v[50:53], v[172:175], v[180:183], v[50:53]
	v_mfma_f32_16x16x32_bf16 v[38:41], v[164:167], v[188:191], v[38:41]
	v_mfma_f32_16x16x32_bf16 v[34:37], v[172:175], v[188:191], v[34:37]
	v_mfma_f32_16x16x32_bf16 v[22:25], v[164:167], v[196:199], v[22:25]
	v_mfma_f32_16x16x32_bf16 v[18:21], v[172:175], v[196:199], v[18:21]
	v_mfma_f32_16x16x32_bf16 v[6:9], v[164:167], v[204:207], v[6:9]
	v_mfma_f32_16x16x32_bf16 v[2:5], v[172:175], v[204:207], v[2:5]
	v_mfma_f32_16x16x32_bf16 v[54:57], v[168:171], v[184:187], v[54:57]
	v_mfma_f32_16x16x32_bf16 v[50:53], v[176:179], v[184:187], v[50:53]
	v_mfma_f32_16x16x32_bf16 v[38:41], v[168:171], v[192:195], v[38:41]
	v_mfma_f32_16x16x32_bf16 v[34:37], v[176:179], v[192:195], v[34:37]
	v_mfma_f32_16x16x32_bf16 v[22:25], v[168:171], v[200:203], v[22:25]
	v_mfma_f32_16x16x32_bf16 v[18:21], v[176:179], v[200:203], v[18:21]
	s_setprio 2
	s_barrier
	v_mfma_f32_16x16x32_bf16 v[6:9], v[168:171], v[208:211], v[6:9]
	v_mfma_f32_16x16x32_bf16 v[2:5], v[176:179], v[208:211], v[2:5]
	s_setprio 0
	ds_read_b128 v[148:151], v146
	ds_read_b128 v[152:155], v146 offset:1024
	ds_read_b128 v[156:159], v146 offset:2048
	ds_read_b128 v[160:163], v146 offset:3072
	ds_read_b128 v[164:167], v147
	ds_read_b128 v[168:171], v147 offset:1024
	ds_read_b128 v[172:175], v147 offset:2048
	ds_read_b128 v[176:179], v147 offset:3072
	ds_read_b128 v[180:183], v145 offset:32768
	ds_read_b128 v[184:187], v145 offset:33792
	ds_read_b128 v[188:191], v145 offset:34816
	ds_read_b128 v[192:195], v145 offset:35840
	ds_read_b128 v[196:199], v145 offset:36864
	ds_read_b128 v[200:203], v145 offset:37888
	ds_read_b128 v[204:207], v145 offset:38912
	ds_read_b128 v[208:211], v145 offset:39936
	s_mov_b32 s74, m0
	s_mov_b32 m0, s31
	s_nop 0
	global_load_lds_dwordx4 v138, s[22:23]
	s_mov_b32 m0, s74
	s_nop 0
	s_mov_b32 s74, m0
	s_mov_b32 m0, s41
	s_nop 0
	global_load_lds_dwordx4 v140, s[22:23]
	s_mov_b32 m0, s74
	s_add_u32 s22, s22, 0x80000
	s_addc_u32 s23, s23, 0
	s_mov_b32 s74, m0
	s_mov_b32 m0, s42
	s_nop 0
	global_load_lds_dwordx4 v138, s[22:23]
	s_mov_b32 m0, s74
	s_nop 0
	s_mov_b32 s74, m0
	s_mov_b32 m0, s43
	s_nop 0
	global_load_lds_dwordx4 v140, s[22:23]
	s_mov_b32 m0, s74
	s_waitcnt vmcnt(8)
	s_waitcnt lgkmcnt(0)
	s_barrier
	s_setprio 1
	s_waitcnt lgkmcnt(7)
	v_mfma_f32_16x16x32_bf16 v[126:129], v[148:151], v[180:183], v[126:129]
	v_mfma_f32_16x16x32_bf16 v[122:125], v[156:159], v[180:183], v[122:125]
	s_waitcnt lgkmcnt(5)
	v_mfma_f32_16x16x32_bf16 v[110:113], v[148:151], v[188:191], v[110:113]
	v_mfma_f32_16x16x32_bf16 v[106:109], v[156:159], v[188:191], v[106:109]
	s_waitcnt lgkmcnt(3)
	v_mfma_f32_16x16x32_bf16 v[94:97], v[148:151], v[196:199], v[94:97]
	v_mfma_f32_16x16x32_bf16 v[90:93], v[156:159], v[196:199], v[90:93]
	s_waitcnt lgkmcnt(1)
	v_mfma_f32_16x16x32_bf16 v[78:81], v[148:151], v[204:207], v[78:81]
	v_mfma_f32_16x16x32_bf16 v[74:77], v[156:159], v[204:207], v[74:77]
	v_mfma_f32_16x16x32_bf16 v[126:129], v[152:155], v[184:187], v[126:129]
	v_mfma_f32_16x16x32_bf16 v[122:125], v[160:163], v[184:187], v[122:125]
	v_mfma_f32_16x16x32_bf16 v[110:113], v[152:155], v[192:195], v[110:113]
	v_mfma_f32_16x16x32_bf16 v[106:109], v[160:163], v[192:195], v[106:109]
	v_mfma_f32_16x16x32_bf16 v[94:97], v[152:155], v[200:203], v[94:97]
	v_mfma_f32_16x16x32_bf16 v[90:93], v[160:163], v[200:203], v[90:93]
	s_waitcnt lgkmcnt(0)
	v_mfma_f32_16x16x32_bf16 v[78:81], v[152:155], v[208:211], v[78:81]
	v_mfma_f32_16x16x32_bf16 v[74:77], v[160:163], v[208:211], v[74:77]
	s_setprio 0
	s_setprio 1
	v_mfma_f32_16x16x32_bf16 v[118:121], v[164:167], v[180:183], v[118:121]
	v_mfma_f32_16x16x32_bf16 v[114:117], v[172:175], v[180:183], v[114:117]
	v_mfma_f32_16x16x32_bf16 v[102:105], v[164:167], v[188:191], v[102:105]
	v_mfma_f32_16x16x32_bf16 v[98:101], v[172:175], v[188:191], v[98:101]
	v_mfma_f32_16x16x32_bf16 v[86:89], v[164:167], v[196:199], v[86:89]
	v_mfma_f32_16x16x32_bf16 v[82:85], v[172:175], v[196:199], v[82:85]
	v_mfma_f32_16x16x32_bf16 v[70:73], v[164:167], v[204:207], v[70:73]
	v_mfma_f32_16x16x32_bf16 v[66:69], v[172:175], v[204:207], v[66:69]
	v_mfma_f32_16x16x32_bf16 v[118:121], v[168:171], v[184:187], v[118:121]
	v_mfma_f32_16x16x32_bf16 v[114:117], v[176:179], v[184:187], v[114:117]
	v_mfma_f32_16x16x32_bf16 v[102:105], v[168:171], v[192:195], v[102:105]
	v_mfma_f32_16x16x32_bf16 v[98:101], v[176:179], v[192:195], v[98:101]
	v_mfma_f32_16x16x32_bf16 v[86:89], v[168:171], v[200:203], v[86:89]
	v_mfma_f32_16x16x32_bf16 v[82:85], v[176:179], v[200:203], v[82:85]
	s_setprio 2
	s_barrier
	v_mfma_f32_16x16x32_bf16 v[70:73], v[168:171], v[208:211], v[70:73]
	v_mfma_f32_16x16x32_bf16 v[66:69], v[176:179], v[208:211], v[66:69]
	s_setprio 0
	ds_read_b128 v[180:183], v145 offset:49152
	ds_read_b128 v[184:187], v145 offset:50176
	ds_read_b128 v[188:191], v145 offset:51200
	ds_read_b128 v[192:195], v145 offset:52224
	ds_read_b128 v[196:199], v145 offset:53248
	ds_read_b128 v[200:203], v145 offset:54272
	ds_read_b128 v[204:207], v145 offset:55296
	ds_read_b128 v[208:211], v145 offset:56320
	s_add_u32 s22, s20, 0x80
	s_addc_u32 s23, s21, 0
	s_mov_b32 s74, m0
	s_mov_b32 m0, s46
	s_nop 0
	global_load_lds_dwordx4 v139, s[22:23]
	s_mov_b32 m0, s74
	s_add_u32 s20, s20, 0x80080
	s_mov_b32 s74, m0
	s_mov_b32 m0, s47
	s_nop 0
	global_load_lds_dwordx4 v141, s[22:23]
	s_mov_b32 m0, s74
	s_addc_u32 s21, s21, 0
	s_mov_b32 s22, m0
	s_mov_b32 m0, s48
	s_nop 0
	global_load_lds_dwordx4 v139, s[20:21]
	s_mov_b32 m0, s22
	s_nop 0
	s_mov_b32 s22, m0
	s_mov_b32 m0, s49
	s_nop 0
	global_load_lds_dwordx4 v141, s[20:21]
	s_mov_b32 m0, s22
	s_waitcnt vmcnt(4)
	s_waitcnt lgkmcnt(0)
	s_barrier
	s_setprio 1
	s_waitcnt lgkmcnt(7)
	v_mfma_f32_16x16x32_bf16 v[62:65], v[148:151], v[180:183], v[62:65]
	v_mfma_f32_16x16x32_bf16 v[58:61], v[156:159], v[180:183], v[58:61]
	s_waitcnt lgkmcnt(5)
	v_mfma_f32_16x16x32_bf16 v[46:49], v[148:151], v[188:191], v[46:49]
	v_mfma_f32_16x16x32_bf16 v[42:45], v[156:159], v[188:191], v[42:45]
	s_waitcnt lgkmcnt(3)
	v_mfma_f32_16x16x32_bf16 v[30:33], v[148:151], v[196:199], v[30:33]
	v_mfma_f32_16x16x32_bf16 v[26:29], v[156:159], v[196:199], v[26:29]
	s_waitcnt lgkmcnt(1)
	v_mfma_f32_16x16x32_bf16 v[14:17], v[148:151], v[204:207], v[14:17]
	v_mfma_f32_16x16x32_bf16 v[10:13], v[156:159], v[204:207], v[10:13]
	v_mfma_f32_16x16x32_bf16 v[62:65], v[152:155], v[184:187], v[62:65]
	v_mfma_f32_16x16x32_bf16 v[58:61], v[160:163], v[184:187], v[58:61]
	v_mfma_f32_16x16x32_bf16 v[46:49], v[152:155], v[192:195], v[46:49]
	v_mfma_f32_16x16x32_bf16 v[42:45], v[160:163], v[192:195], v[42:45]
	v_mfma_f32_16x16x32_bf16 v[30:33], v[152:155], v[200:203], v[30:33]
	v_mfma_f32_16x16x32_bf16 v[26:29], v[160:163], v[200:203], v[26:29]
	s_waitcnt lgkmcnt(0)
	v_mfma_f32_16x16x32_bf16 v[14:17], v[152:155], v[208:211], v[14:17]
	v_mfma_f32_16x16x32_bf16 v[10:13], v[160:163], v[208:211], v[10:13]
	s_setprio 0
	s_setprio 1
	v_mfma_f32_16x16x32_bf16 v[54:57], v[164:167], v[180:183], v[54:57]
	v_mfma_f32_16x16x32_bf16 v[50:53], v[172:175], v[180:183], v[50:53]
	v_mfma_f32_16x16x32_bf16 v[38:41], v[164:167], v[188:191], v[38:41]
	v_mfma_f32_16x16x32_bf16 v[34:37], v[172:175], v[188:191], v[34:37]
	v_mfma_f32_16x16x32_bf16 v[22:25], v[164:167], v[196:199], v[22:25]
	v_mfma_f32_16x16x32_bf16 v[18:21], v[172:175], v[196:199], v[18:21]
	v_mfma_f32_16x16x32_bf16 v[6:9], v[164:167], v[204:207], v[6:9]
	v_mfma_f32_16x16x32_bf16 v[2:5], v[172:175], v[204:207], v[2:5]
	v_mfma_f32_16x16x32_bf16 v[54:57], v[168:171], v[184:187], v[54:57]
	v_mfma_f32_16x16x32_bf16 v[50:53], v[176:179], v[184:187], v[50:53]
	v_mfma_f32_16x16x32_bf16 v[38:41], v[168:171], v[192:195], v[38:41]
	v_mfma_f32_16x16x32_bf16 v[34:37], v[176:179], v[192:195], v[34:37]
	v_mfma_f32_16x16x32_bf16 v[22:25], v[168:171], v[200:203], v[22:25]
	v_mfma_f32_16x16x32_bf16 v[18:21], v[176:179], v[200:203], v[18:21]
	s_setprio 2
	s_barrier
	v_mfma_f32_16x16x32_bf16 v[6:9], v[168:171], v[208:211], v[6:9]
	v_mfma_f32_16x16x32_bf16 v[2:5], v[176:179], v[208:211], v[2:5]
	s_setprio 0
	s_add_i32 s73, s73, 2
	s_add_u32 s66, s66, 0x100
	s_addc_u32 s67, s67, 0
	s_add_u32 s18, s18, 0x100
	s_addc_u32 s19, s19, 0
	s_add_u32 s70, s70, 0x100
	s_addc_u32 s71, s71, 0
	s_cmp_gt_u32 s73, 29
	s_cbranch_scc0 .LBB0_1785
	s_and_b64 vcc, exec, s[6:7]
	s_cbranch_vccz .LBB0_1788
	s_barrier

.LBB0_1952:
	ds_read_b128 v[130:133], v181
	ds_read_b128 v[134:137], v181 offset:1024
	ds_read_b128 v[138:141], v181 offset:2048
	ds_read_b128 v[142:145], v181 offset:3072
	ds_read_b128 v[150:153], v182
	ds_read_b128 v[154:157], v182 offset:1024
	ds_read_b128 v[158:161], v182 offset:2048
	ds_read_b128 v[162:165], v182 offset:3072
	s_cmpk_eq_i32 s74, 0x52
	s_cselect_b32 s23, s11, s70
	s_cselect_b32 s22, s66, s67
	s_cselect_b32 s25, s13, s73
	s_cselect_b32 s24, s65, s71
	ds_read_b128 v[166:169], v183
	ds_read_b128 v[170:173], v183 offset:1024
	ds_read_b128 v[186:189], v183 offset:2048
	ds_read_b128 v[190:193], v183 offset:3072
	ds_read_b128 v[194:197], v183 offset:4096
	ds_read_b128 v[198:201], v183 offset:5120
	ds_read_b128 v[202:205], v183 offset:6144
	ds_read_b128 v[206:209], v183 offset:7168
	s_add_u32 s76, s20, 0xffffc000
	s_addc_u32 s77, s21, -1
	s_mov_b32 s75, m0
	s_mov_b32 m0, s58
	s_nop 0
	global_load_lds_dwordx4 v1, s[76:77]
	s_mov_b32 m0, s75
	s_nop 0
	s_mov_b32 s75, m0
	s_mov_b32 m0, s62
	s_nop 0
	global_load_lds_dwordx4 v177, s[76:77]
	s_mov_b32 m0, s75
	s_nop 0
	s_mov_b32 s75, m0
	s_mov_b32 m0, s59
	s_nop 0
	global_load_lds_dwordx4 v1, s[20:21]
	s_mov_b32 m0, s75
	s_nop 0
	s_mov_b32 s75, m0
	s_mov_b32 m0, s63
	s_nop 0
	global_load_lds_dwordx4 v177, s[20:21]
	s_mov_b32 m0, s75
	s_waitcnt vmcnt(8)
	s_waitcnt lgkmcnt(0)
	s_barrier
	s_setprio 1
	s_waitcnt lgkmcnt(7)
	v_mfma_f32_16x16x32_bf16 v[126:129], v[130:133], v[166:169], v[126:129]
	v_mfma_f32_16x16x32_bf16 v[122:125], v[138:141], v[166:169], v[122:125]
	s_waitcnt lgkmcnt(5)
	v_mfma_f32_16x16x32_bf16 v[118:121], v[130:133], v[186:189], v[118:121]
	v_mfma_f32_16x16x32_bf16 v[110:113], v[138:141], v[186:189], v[110:113]
	s_waitcnt lgkmcnt(3)
	v_mfma_f32_16x16x32_bf16 v[94:97], v[130:133], v[194:197], v[94:97]
	v_mfma_f32_16x16x32_bf16 v[90:93], v[138:141], v[194:197], v[90:93]
	s_waitcnt lgkmcnt(1)
	v_mfma_f32_16x16x32_bf16 v[86:89], v[130:133], v[202:205], v[86:89]
	v_mfma_f32_16x16x32_bf16 v[78:81], v[138:141], v[202:205], v[78:81]
	v_mfma_f32_16x16x32_bf16 v[126:129], v[134:137], v[170:173], v[126:129]
	v_mfma_f32_16x16x32_bf16 v[122:125], v[142:145], v[170:173], v[122:125]
	v_mfma_f32_16x16x32_bf16 v[118:121], v[134:137], v[190:193], v[118:121]
	v_mfma_f32_16x16x32_bf16 v[110:113], v[142:145], v[190:193], v[110:113]
	v_mfma_f32_16x16x32_bf16 v[94:97], v[134:137], v[198:201], v[94:97]
	v_mfma_f32_16x16x32_bf16 v[90:93], v[142:145], v[198:201], v[90:93]
	s_waitcnt lgkmcnt(0)
	v_mfma_f32_16x16x32_bf16 v[86:89], v[134:137], v[206:209], v[86:89]
	v_mfma_f32_16x16x32_bf16 v[78:81], v[142:145], v[206:209], v[78:81]
	s_setprio 0
	s_setprio 1
	v_mfma_f32_16x16x32_bf16 v[114:117], v[150:153], v[166:169], v[114:117]
	v_mfma_f32_16x16x32_bf16 v[106:109], v[158:161], v[166:169], v[106:109]
	v_mfma_f32_16x16x32_bf16 v[102:105], v[150:153], v[186:189], v[102:105]
	v_mfma_f32_16x16x32_bf16 v[98:101], v[158:161], v[186:189], v[98:101]
	v_mfma_f32_16x16x32_bf16 v[82:85], v[150:153], v[194:197], v[82:85]
	v_mfma_f32_16x16x32_bf16 v[74:77], v[158:161], v[194:197], v[74:77]
	v_mfma_f32_16x16x32_bf16 v[70:73], v[150:153], v[202:205], v[70:73]
	v_mfma_f32_16x16x32_bf16 v[66:69], v[158:161], v[202:205], v[66:69]
	v_mfma_f32_16x16x32_bf16 v[114:117], v[154:157], v[170:173], v[114:117]
	v_mfma_f32_16x16x32_bf16 v[106:109], v[162:165], v[170:173], v[106:109]
	v_mfma_f32_16x16x32_bf16 v[102:105], v[154:157], v[190:193], v[102:105]
	v_mfma_f32_16x16x32_bf16 v[98:101], v[162:165], v[190:193], v[98:101]
	v_mfma_f32_16x16x32_bf16 v[82:85], v[154:157], v[198:201], v[82:85]
	v_mfma_f32_16x16x32_bf16 v[74:77], v[162:165], v[198:201], v[74:77]
	s_setprio 2
	s_barrier
	v_mfma_f32_16x16x32_bf16 v[70:73], v[154:157], v[206:209], v[70:73]
	v_mfma_f32_16x16x32_bf16 v[66:69], v[162:165], v[206:209], v[66:69]
	s_setprio 0
	ds_read_b128 v[166:169], v183 offset:16384
	ds_read_b128 v[170:173], v183 offset:17408
	ds_read_b128 v[186:189], v183 offset:18432
	ds_read_b128 v[190:193], v183 offset:19456
	ds_read_b128 v[194:197], v183 offset:20480
	ds_read_b128 v[198:201], v183 offset:21504
	ds_read_b128 v[202:205], v183 offset:22528
	ds_read_b128 v[206:209], v183 offset:23552
	s_mov_b32 s75, m0
	s_mov_b32 m0, s35
	s_nop 0
	global_load_lds_dwordx4 v176, s[22:23]
	s_mov_b32 m0, s75
	s_add_u32 s76, s22, 0x4000
	s_mov_b32 s75, m0
	s_mov_b32 m0, s36
	s_nop 0
	global_load_lds_dwordx4 v178, s[22:23]
	s_mov_b32 m0, s75
	s_addc_u32 s77, s23, 0
	s_mov_b32 s75, m0
	s_mov_b32 m0, s37
	s_nop 0
	global_load_lds_dwordx4 v176, s[76:77]
	s_mov_b32 m0, s75
	s_nop 0
	s_mov_b32 s75, m0
	s_mov_b32 m0, s40
	s_nop 0
	global_load_lds_dwordx4 v178, s[76:77]
	s_mov_b32 m0, s75
	s_waitcnt vmcnt(4)
	s_waitcnt lgkmcnt(0)
	s_barrier
	s_setprio 1
	s_waitcnt lgkmcnt(7)
	v_mfma_f32_16x16x32_bf16 v[62:65], v[130:133], v[166:169], v[62:65]
	v_mfma_f32_16x16x32_bf16 v[58:61], v[138:141], v[166:169], v[58:61]
	s_waitcnt lgkmcnt(5)
	v_mfma_f32_16x16x32_bf16 v[46:49], v[130:133], v[186:189], v[46:49]
	v_mfma_f32_16x16x32_bf16 v[42:45], v[138:141], v[186:189], v[42:45]
	s_waitcnt lgkmcnt(3)
	v_mfma_f32_16x16x32_bf16 v[30:33], v[130:133], v[194:197], v[30:33]
	v_mfma_f32_16x16x32_bf16 v[26:29], v[138:141], v[194:197], v[26:29]
	s_waitcnt lgkmcnt(1)
	v_mfma_f32_16x16x32_bf16 v[14:17], v[130:133], v[202:205], v[14:17]
	v_mfma_f32_16x16x32_bf16 v[10:13], v[138:141], v[202:205], v[10:13]
	v_mfma_f32_16x16x32_bf16 v[62:65], v[134:137], v[170:173], v[62:65]
	v_mfma_f32_16x16x32_bf16 v[58:61], v[142:145], v[170:173], v[58:61]
	v_mfma_f32_16x16x32_bf16 v[46:49], v[134:137], v[190:193], v[46:49]
	v_mfma_f32_16x16x32_bf16 v[42:45], v[142:145], v[190:193], v[42:45]
	v_mfma_f32_16x16x32_bf16 v[30:33], v[134:137], v[198:201], v[30:33]
	v_mfma_f32_16x16x32_bf16 v[26:29], v[142:145], v[198:201], v[26:29]
	s_waitcnt lgkmcnt(0)
	v_mfma_f32_16x16x32_bf16 v[14:17], v[134:137], v[206:209], v[14:17]
	v_mfma_f32_16x16x32_bf16 v[10:13], v[142:145], v[206:209], v[10:13]
	s_setprio 0
	s_setprio 1
	v_mfma_f32_16x16x32_bf16 v[54:57], v[150:153], v[166:169], v[54:57]
	v_mfma_f32_16x16x32_bf16 v[50:53], v[158:161], v[166:169], v[50:53]
	v_mfma_f32_16x16x32_bf16 v[38:41], v[150:153], v[186:189], v[38:41]
	v_mfma_f32_16x16x32_bf16 v[34:37], v[158:161], v[186:189], v[34:37]
	v_mfma_f32_16x16x32_bf16 v[22:25], v[150:153], v[194:197], v[22:25]
	v_mfma_f32_16x16x32_bf16 v[18:21], v[158:161], v[194:197], v[18:21]
	v_mfma_f32_16x16x32_bf16 v[6:9], v[150:153], v[202:205], v[6:9]
	v_mfma_f32_16x16x32_bf16 v[2:5], v[158:161], v[202:205], v[2:5]
	v_mfma_f32_16x16x32_bf16 v[54:57], v[154:157], v[170:173], v[54:57]
	v_mfma_f32_16x16x32_bf16 v[50:53], v[162:165], v[170:173], v[50:53]
	v_mfma_f32_16x16x32_bf16 v[38:41], v[154:157], v[190:193], v[38:41]
	v_mfma_f32_16x16x32_bf16 v[34:37], v[162:165], v[190:193], v[34:37]
	v_mfma_f32_16x16x32_bf16 v[22:25], v[154:157], v[198:201], v[22:25]
	v_mfma_f32_16x16x32_bf16 v[18:21], v[162:165], v[198:201], v[18:21]
	s_setprio 2
	s_barrier
	v_mfma_f32_16x16x32_bf16 v[6:9], v[154:157], v[206:209], v[6:9]
	v_mfma_f32_16x16x32_bf16 v[2:5], v[162:165], v[206:209], v[2:5]
	s_setprio 0
	ds_read_b128 v[130:133], v184
	ds_read_b128 v[134:137], v184 offset:1024
	ds_read_b128 v[138:141], v184 offset:2048
	ds_read_b128 v[142:145], v184 offset:3072
	ds_read_b128 v[150:153], v185
	ds_read_b128 v[154:157], v185 offset:1024
	ds_read_b128 v[158:161], v185 offset:2048
	ds_read_b128 v[162:165], v185 offset:3072
	ds_read_b128 v[166:169], v183 offset:32768
	ds_read_b128 v[170:173], v183 offset:33792
	ds_read_b128 v[186:189], v183 offset:34816
	ds_read_b128 v[190:193], v183 offset:35840
	ds_read_b128 v[194:197], v183 offset:36864
	ds_read_b128 v[198:201], v183 offset:37888
	ds_read_b128 v[202:205], v183 offset:38912
	ds_read_b128 v[206:209], v183 offset:39936
	s_mov_b32 s75, m0
	s_mov_b32 m0, s34
	s_nop 0
	global_load_lds_dwordx4 v1, s[24:25]
	s_mov_b32 m0, s75
	s_nop 0
	s_mov_b32 s75, m0
	s_mov_b32 m0, s41
	s_nop 0
	global_load_lds_dwordx4 v177, s[24:25]
	s_mov_b32 m0, s75
	s_add_u32 s24, s24, 0x4000
	s_addc_u32 s25, s25, 0
	s_mov_b32 s75, m0
	s_mov_b32 m0, s42
	s_nop 0
	global_load_lds_dwordx4 v1, s[24:25]
	s_mov_b32 m0, s75
	s_nop 0
	s_mov_b32 s75, m0
	s_mov_b32 m0, s43
	s_nop 0
	global_load_lds_dwordx4 v177, s[24:25]
	s_mov_b32 m0, s75
	s_waitcnt vmcnt(8)
	s_waitcnt lgkmcnt(0)
	s_barrier
	s_setprio 1
	s_waitcnt lgkmcnt(7)
	v_mfma_f32_16x16x32_bf16 v[126:129], v[130:133], v[166:169], v[126:129]
	v_mfma_f32_16x16x32_bf16 v[122:125], v[138:141], v[166:169], v[122:125]
	s_waitcnt lgkmcnt(5)
	v_mfma_f32_16x16x32_bf16 v[118:121], v[130:133], v[186:189], v[118:121]
	v_mfma_f32_16x16x32_bf16 v[110:113], v[138:141], v[186:189], v[110:113]
	s_waitcnt lgkmcnt(3)
	v_mfma_f32_16x16x32_bf16 v[94:97], v[130:133], v[194:197], v[94:97]
	v_mfma_f32_16x16x32_bf16 v[90:93], v[138:141], v[194:197], v[90:93]
	s_waitcnt lgkmcnt(1)
	v_mfma_f32_16x16x32_bf16 v[86:89], v[130:133], v[202:205], v[86:89]
	v_mfma_f32_16x16x32_bf16 v[78:81], v[138:141], v[202:205], v[78:81]
	v_mfma_f32_16x16x32_bf16 v[126:129], v[134:137], v[170:173], v[126:129]
	v_mfma_f32_16x16x32_bf16 v[122:125], v[142:145], v[170:173], v[122:125]
	v_mfma_f32_16x16x32_bf16 v[118:121], v[134:137], v[190:193], v[118:121]
	v_mfma_f32_16x16x32_bf16 v[110:113], v[142:145], v[190:193], v[110:113]
	v_mfma_f32_16x16x32_bf16 v[94:97], v[134:137], v[198:201], v[94:97]
	v_mfma_f32_16x16x32_bf16 v[90:93], v[142:145], v[198:201], v[90:93]
	s_waitcnt lgkmcnt(0)
	v_mfma_f32_16x16x32_bf16 v[86:89], v[134:137], v[206:209], v[86:89]
	v_mfma_f32_16x16x32_bf16 v[78:81], v[142:145], v[206:209], v[78:81]
	s_setprio 0
	s_setprio 1
	v_mfma_f32_16x16x32_bf16 v[114:117], v[150:153], v[166:169], v[114:117]
	v_mfma_f32_16x16x32_bf16 v[106:109], v[158:161], v[166:169], v[106:109]
	v_mfma_f32_16x16x32_bf16 v[102:105], v[150:153], v[186:189], v[102:105]
	v_mfma_f32_16x16x32_bf16 v[98:101], v[158:161], v[186:189], v[98:101]
	v_mfma_f32_16x16x32_bf16 v[82:85], v[150:153], v[194:197], v[82:85]
	v_mfma_f32_16x16x32_bf16 v[74:77], v[158:161], v[194:197], v[74:77]
	v_mfma_f32_16x16x32_bf16 v[70:73], v[150:153], v[202:205], v[70:73]
	v_mfma_f32_16x16x32_bf16 v[66:69], v[158:161], v[202:205], v[66:69]
	v_mfma_f32_16x16x32_bf16 v[114:117], v[154:157], v[170:173], v[114:117]
	v_mfma_f32_16x16x32_bf16 v[106:109], v[162:165], v[170:173], v[106:109]
	v_mfma_f32_16x16x32_bf16 v[102:105], v[154:157], v[190:193], v[102:105]
	v_mfma_f32_16x16x32_bf16 v[98:101], v[162:165], v[190:193], v[98:101]
	v_mfma_f32_16x16x32_bf16 v[82:85], v[154:157], v[198:201], v[82:85]
	v_mfma_f32_16x16x32_bf16 v[74:77], v[162:165], v[198:201], v[74:77]
	s_setprio 2
	s_barrier
	v_mfma_f32_16x16x32_bf16 v[70:73], v[154:157], v[206:209], v[70:73]
	v_mfma_f32_16x16x32_bf16 v[66:69], v[162:165], v[206:209], v[66:69]
	s_setprio 0
	ds_read_b128 v[166:169], v183 offset:49152
	ds_read_b128 v[170:173], v183 offset:50176
	ds_read_b128 v[186:189], v183 offset:51200
	ds_read_b128 v[190:193], v183 offset:52224
	ds_read_b128 v[194:197], v183 offset:53248
	ds_read_b128 v[198:201], v183 offset:54272
	ds_read_b128 v[202:205], v183 offset:55296
	ds_read_b128 v[206:209], v183 offset:56320
	s_add_u32 s24, s22, 0x40000
	s_addc_u32 s25, s23, 0
	s_mov_b32 s75, m0
	s_mov_b32 m0, s46
	s_nop 0
	global_load_lds_dwordx4 v176, s[24:25]
	s_mov_b32 m0, s75
	s_add_u32 s22, s22, 0x44000
	s_mov_b32 s75, m0
	s_mov_b32 m0, s47
	s_nop 0
	global_load_lds_dwordx4 v178, s[24:25]
	s_mov_b32 m0, s75
	s_addc_u32 s23, s23, 0
	s_mov_b32 s24, m0
	s_mov_b32 m0, s48
	s_nop 0
	global_load_lds_dwordx4 v176, s[22:23]
	s_mov_b32 m0, s24
	s_nop 0
	s_mov_b32 s24, m0
	s_mov_b32 m0, s49
	s_nop 0
	global_load_lds_dwordx4 v178, s[22:23]
	s_mov_b32 m0, s24
	s_waitcnt vmcnt(4)
	s_waitcnt lgkmcnt(0)
	s_barrier
	s_setprio 1
	s_waitcnt lgkmcnt(7)
	v_mfma_f32_16x16x32_bf16 v[62:65], v[130:133], v[166:169], v[62:65]
	v_mfma_f32_16x16x32_bf16 v[58:61], v[138:141], v[166:169], v[58:61]
	s_waitcnt lgkmcnt(5)
	v_mfma_f32_16x16x32_bf16 v[46:49], v[130:133], v[186:189], v[46:49]
	v_mfma_f32_16x16x32_bf16 v[42:45], v[138:141], v[186:189], v[42:45]
	s_waitcnt lgkmcnt(3)
	v_mfma_f32_16x16x32_bf16 v[30:33], v[130:133], v[194:197], v[30:33]
	v_mfma_f32_16x16x32_bf16 v[26:29], v[138:141], v[194:197], v[26:29]
	s_waitcnt lgkmcnt(1)
	v_mfma_f32_16x16x32_bf16 v[14:17], v[130:133], v[202:205], v[14:17]
	v_mfma_f32_16x16x32_bf16 v[10:13], v[138:141], v[202:205], v[10:13]
	v_mfma_f32_16x16x32_bf16 v[62:65], v[134:137], v[170:173], v[62:65]
	v_mfma_f32_16x16x32_bf16 v[58:61], v[142:145], v[170:173], v[58:61]
	v_mfma_f32_16x16x32_bf16 v[46:49], v[134:137], v[190:193], v[46:49]
	v_mfma_f32_16x16x32_bf16 v[42:45], v[142:145], v[190:193], v[42:45]
	v_mfma_f32_16x16x32_bf16 v[30:33], v[134:137], v[198:201], v[30:33]
	v_mfma_f32_16x16x32_bf16 v[26:29], v[142:145], v[198:201], v[26:29]
	s_waitcnt lgkmcnt(0)
	v_mfma_f32_16x16x32_bf16 v[14:17], v[134:137], v[206:209], v[14:17]
	v_mfma_f32_16x16x32_bf16 v[10:13], v[142:145], v[206:209], v[10:13]
	s_setprio 0
	s_setprio 1
	v_mfma_f32_16x16x32_bf16 v[54:57], v[150:153], v[166:169], v[54:57]
	v_mfma_f32_16x16x32_bf16 v[50:53], v[158:161], v[166:169], v[50:53]
	v_mfma_f32_16x16x32_bf16 v[38:41], v[150:153], v[186:189], v[38:41]
	v_mfma_f32_16x16x32_bf16 v[34:37], v[158:161], v[186:189], v[34:37]
	v_mfma_f32_16x16x32_bf16 v[22:25], v[150:153], v[194:197], v[22:25]
	v_mfma_f32_16x16x32_bf16 v[18:21], v[158:161], v[194:197], v[18:21]
	v_mfma_f32_16x16x32_bf16 v[6:9], v[150:153], v[202:205], v[6:9]
	v_mfma_f32_16x16x32_bf16 v[2:5], v[158:161], v[202:205], v[2:5]
	v_mfma_f32_16x16x32_bf16 v[54:57], v[154:157], v[170:173], v[54:57]
	v_mfma_f32_16x16x32_bf16 v[50:53], v[162:165], v[170:173], v[50:53]
	v_mfma_f32_16x16x32_bf16 v[38:41], v[154:157], v[190:193], v[38:41]
	v_mfma_f32_16x16x32_bf16 v[34:37], v[162:165], v[190:193], v[34:37]
	v_mfma_f32_16x16x32_bf16 v[22:25], v[154:157], v[198:201], v[22:25]
	v_mfma_f32_16x16x32_bf16 v[18:21], v[162:165], v[198:201], v[18:21]
	s_setprio 2
	s_barrier
	v_mfma_f32_16x16x32_bf16 v[6:9], v[154:157], v[206:209], v[6:9]
	v_mfma_f32_16x16x32_bf16 v[2:5], v[162:165], v[206:209], v[2:5]
	s_setprio 0
	s_add_i32 s74, s74, 2
	s_add_u32 s67, s67, 0x80000
	s_addc_u32 s70, s70, 0
	s_add_u32 s20, s20, 0x400000
	s_addc_u32 s21, s21, 0
	s_add_u32 s71, s71, 0x400000
	s_addc_u32 s73, s73, 0
	s_cmpk_gt_u32 s74, 0x53
	s_cbranch_scc0 .LBB0_1952
	s_and_b64 vcc, exec, s[8:9]
	s_cbranch_vccz .LBB0_1955
	s_barrier

.LBB0_2146:
	ds_read_b128 v[42:45], v181
	ds_read_b128 v[46:49], v181 offset:1024
	ds_read_b128 v[58:61], v181 offset:2048
	ds_read_b128 v[62:65], v181 offset:3072
	ds_read_b128 v[146:149], v182
	ds_read_b128 v[150:153], v182 offset:1024
	ds_read_b128 v[154:157], v182 offset:2048
	ds_read_b128 v[158:161], v182 offset:3072
	s_cmp_eq_u32 s81, 28
	s_cselect_b32 s37, s23, s78
	s_cselect_b32 s36, s31, s77
	s_cselect_b32 s41, s5, s80
	s_cselect_b32 s40, s25, s79
	ds_read_b128 v[170:173], v183
	ds_read_b128 v[188:191], v183 offset:1024
	ds_read_b128 v[192:195], v183 offset:2048
	ds_read_b128 v[196:199], v183 offset:3072
	ds_read_b128 v[200:203], v183 offset:4096
	ds_read_b128 v[204:207], v183 offset:5120
	ds_read_b128 v[208:211], v183 offset:6144
	ds_read_b128 v[212:215], v183 offset:7168
	s_add_u32 s82, s34, 0xfff80000
	s_addc_u32 s83, s35, -1
	s_mov_b32 s86, m0
	s_mov_b32 m0, s70
	s_nop 0
	global_load_lds_dwordx4 v1, s[82:83]
	s_mov_b32 m0, s86
	s_nop 0
	s_mov_b32 s86, m0
	s_mov_b32 m0, s73
	s_nop 0
	global_load_lds_dwordx4 v177, s[82:83]
	s_mov_b32 m0, s86
	s_mov_b32 s82, m0
	s_mov_b32 m0, s71
	s_nop 0
	global_load_lds_dwordx4 v1, s[34:35]
	s_mov_b32 m0, s82
	s_nop 0
	s_mov_b32 s82, m0
	s_mov_b32 m0, s74
	s_nop 0
	global_load_lds_dwordx4 v177, s[34:35]
	s_mov_b32 m0, s82
	s_waitcnt vmcnt(8)
	s_waitcnt lgkmcnt(0)
	s_barrier
	s_setprio 1
	s_waitcnt lgkmcnt(7)
	v_mfma_f32_16x16x32_bf16 v[142:145], v[42:45], v[170:173], v[142:145]
	v_mfma_f32_16x16x32_bf16 v[138:141], v[58:61], v[170:173], v[138:141]
	s_waitcnt lgkmcnt(5)
	v_mfma_f32_16x16x32_bf16 v[126:129], v[42:45], v[192:195], v[126:129]
	v_mfma_f32_16x16x32_bf16 v[122:125], v[58:61], v[192:195], v[122:125]
	s_waitcnt lgkmcnt(3)
	v_mfma_f32_16x16x32_bf16 v[110:113], v[42:45], v[200:203], v[110:113]
	v_mfma_f32_16x16x32_bf16 v[106:109], v[58:61], v[200:203], v[106:109]
	s_waitcnt lgkmcnt(1)
	v_mfma_f32_16x16x32_bf16 v[94:97], v[42:45], v[208:211], v[94:97]
	v_mfma_f32_16x16x32_bf16 v[90:93], v[58:61], v[208:211], v[90:93]
	v_mfma_f32_16x16x32_bf16 v[142:145], v[46:49], v[188:191], v[142:145]
	v_mfma_f32_16x16x32_bf16 v[138:141], v[62:65], v[188:191], v[138:141]
	v_mfma_f32_16x16x32_bf16 v[126:129], v[46:49], v[196:199], v[126:129]
	v_mfma_f32_16x16x32_bf16 v[122:125], v[62:65], v[196:199], v[122:125]
	v_mfma_f32_16x16x32_bf16 v[110:113], v[46:49], v[204:207], v[110:113]
	v_mfma_f32_16x16x32_bf16 v[106:109], v[62:65], v[204:207], v[106:109]
	s_waitcnt lgkmcnt(0)
	v_mfma_f32_16x16x32_bf16 v[94:97], v[46:49], v[212:215], v[94:97]
	v_mfma_f32_16x16x32_bf16 v[90:93], v[62:65], v[212:215], v[90:93]
	s_setprio 0
	s_setprio 1
	v_mfma_f32_16x16x32_bf16 v[134:137], v[146:149], v[170:173], v[134:137]
	v_mfma_f32_16x16x32_bf16 v[130:133], v[154:157], v[170:173], v[130:133]
	v_mfma_f32_16x16x32_bf16 v[118:121], v[146:149], v[192:195], v[118:121]
	v_mfma_f32_16x16x32_bf16 v[114:117], v[154:157], v[192:195], v[114:117]
	v_mfma_f32_16x16x32_bf16 v[102:105], v[146:149], v[200:203], v[102:105]
	v_mfma_f32_16x16x32_bf16 v[98:101], v[154:157], v[200:203], v[98:101]
	v_mfma_f32_16x16x32_bf16 v[86:89], v[146:149], v[208:211], v[86:89]
	v_mfma_f32_16x16x32_bf16 v[82:85], v[154:157], v[208:211], v[82:85]
	v_mfma_f32_16x16x32_bf16 v[134:137], v[150:153], v[188:191], v[134:137]
	v_mfma_f32_16x16x32_bf16 v[130:133], v[158:161], v[188:191], v[130:133]
	v_mfma_f32_16x16x32_bf16 v[118:121], v[150:153], v[196:199], v[118:121]
	v_mfma_f32_16x16x32_bf16 v[114:117], v[158:161], v[196:199], v[114:117]
	v_mfma_f32_16x16x32_bf16 v[102:105], v[150:153], v[204:207], v[102:105]
	v_mfma_f32_16x16x32_bf16 v[98:101], v[158:161], v[204:207], v[98:101]
	s_setprio 2
	s_barrier
	v_mfma_f32_16x16x32_bf16 v[86:89], v[150:153], v[212:215], v[86:89]
	v_mfma_f32_16x16x32_bf16 v[82:85], v[158:161], v[212:215], v[82:85]
	s_setprio 0
	ds_read_b128 v[170:173], v183 offset:16384
	ds_read_b128 v[188:191], v183 offset:17408
	ds_read_b128 v[192:195], v183 offset:18432
	ds_read_b128 v[196:199], v183 offset:19456
	ds_read_b128 v[200:203], v183 offset:20480
	ds_read_b128 v[204:207], v183 offset:21504
	ds_read_b128 v[208:211], v183 offset:22528
	ds_read_b128 v[212:215], v183 offset:23552
	s_mov_b32 s82, m0
	s_mov_b32 m0, s49
	s_nop 0
	global_load_lds_dwordx4 v176, s[36:37]
	s_mov_b32 m0, s82
	s_nop 0
	s_mov_b32 s82, m0
	s_mov_b32 m0, s56
	s_nop 0
	global_load_lds_dwordx4 v178, s[36:37]
	s_mov_b32 m0, s82
	s_add_u32 s82, s36, 0x80000
	s_addc_u32 s83, s37, 0
	s_mov_b32 s86, m0
	s_mov_b32 m0, s57
	s_nop 0
	global_load_lds_dwordx4 v176, s[82:83]
	s_mov_b32 m0, s86
	s_nop 0
	s_mov_b32 s86, m0
	s_mov_b32 m0, s58
	s_nop 0
	global_load_lds_dwordx4 v178, s[82:83]
	s_mov_b32 m0, s86
	s_waitcnt vmcnt(4)
	s_waitcnt lgkmcnt(0)
	s_barrier
	s_setprio 1
	s_waitcnt lgkmcnt(7)
	v_mfma_f32_16x16x32_bf16 v[78:81], v[42:45], v[170:173], v[78:81]
	v_mfma_f32_16x16x32_bf16 v[74:77], v[58:61], v[170:173], v[74:77]
	s_waitcnt lgkmcnt(5)
	v_mfma_f32_16x16x32_bf16 v[54:57], v[42:45], v[192:195], v[54:57]
	v_mfma_f32_16x16x32_bf16 v[50:53], v[58:61], v[192:195], v[50:53]
	s_waitcnt lgkmcnt(3)
	v_mfma_f32_16x16x32_bf16 v[30:33], v[42:45], v[200:203], v[30:33]
	v_mfma_f32_16x16x32_bf16 v[26:29], v[58:61], v[200:203], v[26:29]
	s_waitcnt lgkmcnt(1)
	v_mfma_f32_16x16x32_bf16 v[14:17], v[42:45], v[208:211], v[14:17]
	v_mfma_f32_16x16x32_bf16 v[10:13], v[58:61], v[208:211], v[10:13]
	v_mfma_f32_16x16x32_bf16 v[78:81], v[46:49], v[188:191], v[78:81]
	v_mfma_f32_16x16x32_bf16 v[74:77], v[62:65], v[188:191], v[74:77]
	v_mfma_f32_16x16x32_bf16 v[54:57], v[46:49], v[196:199], v[54:57]
	v_mfma_f32_16x16x32_bf16 v[50:53], v[62:65], v[196:199], v[50:53]
	v_mfma_f32_16x16x32_bf16 v[30:33], v[46:49], v[204:207], v[30:33]
	v_mfma_f32_16x16x32_bf16 v[26:29], v[62:65], v[204:207], v[26:29]
	s_waitcnt lgkmcnt(0)
	v_mfma_f32_16x16x32_bf16 v[14:17], v[46:49], v[212:215], v[14:17]
	v_mfma_f32_16x16x32_bf16 v[10:13], v[62:65], v[212:215], v[10:13]
	s_setprio 0
	s_setprio 1
	v_mfma_f32_16x16x32_bf16 v[38:41], v[146:149], v[192:195], v[38:41]
	v_mfma_f32_16x16x32_bf16 v[34:37], v[154:157], v[192:195], v[34:37]
	v_mfma_f32_16x16x32_bf16 v[22:25], v[146:149], v[200:203], v[22:25]
	v_mfma_f32_16x16x32_bf16 v[18:21], v[154:157], v[200:203], v[18:21]
	v_mfma_f32_16x16x32_bf16 v[6:9], v[146:149], v[208:211], v[6:9]
	v_mfma_f32_16x16x32_bf16 v[2:5], v[154:157], v[208:211], v[2:5]
	v_mfma_f32_16x16x32_bf16 v[42:45], v[146:149], v[170:173], v[70:73]
	v_mfma_f32_16x16x32_bf16 v[46:49], v[154:157], v[170:173], v[66:69]
	v_mfma_f32_16x16x32_bf16 v[38:41], v[150:153], v[196:199], v[38:41]
	v_mfma_f32_16x16x32_bf16 v[34:37], v[158:161], v[196:199], v[34:37]
	v_mfma_f32_16x16x32_bf16 v[22:25], v[150:153], v[204:207], v[22:25]
	v_mfma_f32_16x16x32_bf16 v[18:21], v[158:161], v[204:207], v[18:21]
	v_mfma_f32_16x16x32_bf16 v[6:9], v[150:153], v[212:215], v[6:9]
	v_mfma_f32_16x16x32_bf16 v[2:5], v[158:161], v[212:215], v[2:5]
	s_setprio 2
	s_barrier
	v_mfma_f32_16x16x32_bf16 v[42:45], v[150:153], v[188:191], v[42:45]
	v_mfma_f32_16x16x32_bf16 v[46:49], v[158:161], v[188:191], v[46:49]
	s_setprio 0
	ds_read_b128 v[58:61], v184
	ds_read_b128 v[62:65], v184 offset:1024
	ds_read_b128 v[66:69], v184 offset:2048
	ds_read_b128 v[70:73], v184 offset:3072
	ds_read_b128 v[146:149], v185
	ds_read_b128 v[150:153], v185 offset:1024
	ds_read_b128 v[154:157], v185 offset:2048
	ds_read_b128 v[158:161], v185 offset:3072
	ds_read_b128 v[170:173], v183 offset:32768
	ds_read_b128 v[188:191], v183 offset:33792
	ds_read_b128 v[192:195], v183 offset:34816
	ds_read_b128 v[196:199], v183 offset:35840
	ds_read_b128 v[200:203], v183 offset:36864
	ds_read_b128 v[204:207], v183 offset:37888
	ds_read_b128 v[208:211], v183 offset:38912
	ds_read_b128 v[212:215], v183 offset:39936
	s_mov_b32 s82, m0
	s_mov_b32 m0, s48
	s_nop 0
	global_load_lds_dwordx4 v1, s[40:41]
	s_mov_b32 m0, s82
	s_nop 0
	s_mov_b32 s82, m0
	s_mov_b32 m0, s59
	s_nop 0
	global_load_lds_dwordx4 v177, s[40:41]
	s_mov_b32 m0, s82
	s_add_u32 s40, s40, 0x80000
	s_addc_u32 s41, s41, 0
	s_mov_b32 s82, m0
	s_mov_b32 m0, s62
	s_nop 0
	global_load_lds_dwordx4 v1, s[40:41]
	s_mov_b32 m0, s82
	s_nop 0
	s_mov_b32 s82, m0
	s_mov_b32 m0, s63
	s_nop 0
	global_load_lds_dwordx4 v177, s[40:41]
	s_mov_b32 m0, s82
	s_waitcnt vmcnt(8)
	s_waitcnt lgkmcnt(0)
	s_barrier
	s_setprio 1
	s_waitcnt lgkmcnt(7)
	v_mfma_f32_16x16x32_bf16 v[142:145], v[58:61], v[170:173], v[142:145]
	v_mfma_f32_16x16x32_bf16 v[138:141], v[66:69], v[170:173], v[138:141]
	s_waitcnt lgkmcnt(5)
	v_mfma_f32_16x16x32_bf16 v[126:129], v[58:61], v[192:195], v[126:129]
	v_mfma_f32_16x16x32_bf16 v[122:125], v[66:69], v[192:195], v[122:125]
	s_waitcnt lgkmcnt(3)
	v_mfma_f32_16x16x32_bf16 v[110:113], v[58:61], v[200:203], v[110:113]
	v_mfma_f32_16x16x32_bf16 v[106:109], v[66:69], v[200:203], v[106:109]
	s_waitcnt lgkmcnt(1)
	v_mfma_f32_16x16x32_bf16 v[94:97], v[58:61], v[208:211], v[94:97]
	v_mfma_f32_16x16x32_bf16 v[90:93], v[66:69], v[208:211], v[90:93]
	v_mfma_f32_16x16x32_bf16 v[142:145], v[62:65], v[188:191], v[142:145]
	v_mfma_f32_16x16x32_bf16 v[138:141], v[70:73], v[188:191], v[138:141]
	v_mfma_f32_16x16x32_bf16 v[126:129], v[62:65], v[196:199], v[126:129]
	v_mfma_f32_16x16x32_bf16 v[122:125], v[70:73], v[196:199], v[122:125]
	v_mfma_f32_16x16x32_bf16 v[110:113], v[62:65], v[204:207], v[110:113]
	v_mfma_f32_16x16x32_bf16 v[106:109], v[70:73], v[204:207], v[106:109]
	s_waitcnt lgkmcnt(0)
	v_mfma_f32_16x16x32_bf16 v[94:97], v[62:65], v[212:215], v[94:97]
	v_mfma_f32_16x16x32_bf16 v[90:93], v[70:73], v[212:215], v[90:93]
	s_setprio 0
	s_setprio 1
	v_mfma_f32_16x16x32_bf16 v[134:137], v[146:149], v[170:173], v[134:137]
	v_mfma_f32_16x16x32_bf16 v[130:133], v[154:157], v[170:173], v[130:133]
	v_mfma_f32_16x16x32_bf16 v[118:121], v[146:149], v[192:195], v[118:121]
	v_mfma_f32_16x16x32_bf16 v[114:117], v[154:157], v[192:195], v[114:117]
	v_mfma_f32_16x16x32_bf16 v[102:105], v[146:149], v[200:203], v[102:105]
	v_mfma_f32_16x16x32_bf16 v[98:101], v[154:157], v[200:203], v[98:101]
	v_mfma_f32_16x16x32_bf16 v[86:89], v[146:149], v[208:211], v[86:89]
	v_mfma_f32_16x16x32_bf16 v[82:85], v[154:157], v[208:211], v[82:85]
	v_mfma_f32_16x16x32_bf16 v[134:137], v[150:153], v[188:191], v[134:137]
	v_mfma_f32_16x16x32_bf16 v[130:133], v[158:161], v[188:191], v[130:133]
	v_mfma_f32_16x16x32_bf16 v[118:121], v[150:153], v[196:199], v[118:121]
	v_mfma_f32_16x16x32_bf16 v[114:117], v[158:161], v[196:199], v[114:117]
	v_mfma_f32_16x16x32_bf16 v[102:105], v[150:153], v[204:207], v[102:105]
	v_mfma_f32_16x16x32_bf16 v[98:101], v[158:161], v[204:207], v[98:101]
	s_setprio 2
	s_barrier
	v_mfma_f32_16x16x32_bf16 v[86:89], v[150:153], v[212:215], v[86:89]
	v_mfma_f32_16x16x32_bf16 v[82:85], v[158:161], v[212:215], v[82:85]
	s_setprio 0
	ds_read_b128 v[170:173], v183 offset:49152
	ds_read_b128 v[188:191], v183 offset:50176
	ds_read_b128 v[192:195], v183 offset:51200
	ds_read_b128 v[196:199], v183 offset:52224
	ds_read_b128 v[200:203], v183 offset:53248
	ds_read_b128 v[204:207], v183 offset:54272
	ds_read_b128 v[208:211], v183 offset:55296
	ds_read_b128 v[212:215], v183 offset:56320
	s_add_u32 s40, s36, 0x80
	s_addc_u32 s41, s37, 0
	s_mov_b32 s82, m0
	s_mov_b32 m0, s64
	s_nop 0
	global_load_lds_dwordx4 v176, s[40:41]
	s_mov_b32 m0, s82
	s_add_u32 s36, s36, 0x80080
	s_mov_b32 s82, m0
	s_mov_b32 m0, s65
	s_nop 0
	global_load_lds_dwordx4 v178, s[40:41]
	s_mov_b32 m0, s82
	s_addc_u32 s37, s37, 0
	s_mov_b32 s40, m0
	s_mov_b32 m0, s66
	s_nop 0
	global_load_lds_dwordx4 v176, s[36:37]
	s_mov_b32 m0, s40
	s_nop 0
	s_mov_b32 s40, m0
	s_mov_b32 m0, s67
	s_nop 0
	global_load_lds_dwordx4 v178, s[36:37]
	s_mov_b32 m0, s40
	s_waitcnt vmcnt(4)
	s_waitcnt lgkmcnt(0)
	s_barrier
	s_setprio 1
	s_waitcnt lgkmcnt(7)
	v_mfma_f32_16x16x32_bf16 v[78:81], v[58:61], v[170:173], v[78:81]
	v_mfma_f32_16x16x32_bf16 v[74:77], v[66:69], v[170:173], v[74:77]
	s_waitcnt lgkmcnt(5)
	v_mfma_f32_16x16x32_bf16 v[54:57], v[58:61], v[192:195], v[54:57]
	v_mfma_f32_16x16x32_bf16 v[50:53], v[66:69], v[192:195], v[50:53]
	s_waitcnt lgkmcnt(3)
	v_mfma_f32_16x16x32_bf16 v[30:33], v[58:61], v[200:203], v[30:33]
	v_mfma_f32_16x16x32_bf16 v[26:29], v[66:69], v[200:203], v[26:29]
	s_waitcnt lgkmcnt(1)
	v_mfma_f32_16x16x32_bf16 v[14:17], v[58:61], v[208:211], v[14:17]
	v_mfma_f32_16x16x32_bf16 v[10:13], v[66:69], v[208:211], v[10:13]
	v_mfma_f32_16x16x32_bf16 v[78:81], v[62:65], v[188:191], v[78:81]
	v_mfma_f32_16x16x32_bf16 v[74:77], v[70:73], v[188:191], v[74:77]
	v_mfma_f32_16x16x32_bf16 v[54:57], v[62:65], v[196:199], v[54:57]
	v_mfma_f32_16x16x32_bf16 v[50:53], v[70:73], v[196:199], v[50:53]
	v_mfma_f32_16x16x32_bf16 v[30:33], v[62:65], v[204:207], v[30:33]
	v_mfma_f32_16x16x32_bf16 v[26:29], v[70:73], v[204:207], v[26:29]
	s_waitcnt lgkmcnt(0)
	v_mfma_f32_16x16x32_bf16 v[14:17], v[62:65], v[212:215], v[14:17]
	v_mfma_f32_16x16x32_bf16 v[10:13], v[70:73], v[212:215], v[10:13]
	s_setprio 0
	s_setprio 1
	v_mfma_f32_16x16x32_bf16 v[42:45], v[146:149], v[170:173], v[42:45]
	v_mfma_f32_16x16x32_bf16 v[70:73], v[150:153], v[188:191], v[42:45]
	v_mfma_f32_16x16x32_bf16 v[42:45], v[154:157], v[170:173], v[46:49]
	v_mfma_f32_16x16x32_bf16 v[38:41], v[146:149], v[192:195], v[38:41]
	v_mfma_f32_16x16x32_bf16 v[34:37], v[154:157], v[192:195], v[34:37]
	v_mfma_f32_16x16x32_bf16 v[22:25], v[146:149], v[200:203], v[22:25]
	v_mfma_f32_16x16x32_bf16 v[18:21], v[154:157], v[200:203], v[18:21]
	v_mfma_f32_16x16x32_bf16 v[6:9], v[146:149], v[208:211], v[6:9]
	v_mfma_f32_16x16x32_bf16 v[2:5], v[154:157], v[208:211], v[2:5]
	v_mfma_f32_16x16x32_bf16 v[66:69], v[158:161], v[188:191], v[42:45]
	v_mfma_f32_16x16x32_bf16 v[38:41], v[150:153], v[196:199], v[38:41]
	v_mfma_f32_16x16x32_bf16 v[34:37], v[158:161], v[196:199], v[34:37]
	v_mfma_f32_16x16x32_bf16 v[22:25], v[150:153], v[204:207], v[22:25]
	v_mfma_f32_16x16x32_bf16 v[18:21], v[158:161], v[204:207], v[18:21]
	s_setprio 2
	s_barrier
	v_mfma_f32_16x16x32_bf16 v[6:9], v[150:153], v[212:215], v[6:9]
	v_mfma_f32_16x16x32_bf16 v[2:5], v[158:161], v[212:215], v[2:5]
	s_setprio 0
	s_add_i32 s81, s81, 2
	s_add_u32 s77, s77, 0x100
	s_addc_u32 s78, s78, 0
	s_add_u32 s34, s34, 0x100
	s_addc_u32 s35, s35, 0
	s_add_u32 s79, s79, 0x100
	s_addc_u32 s80, s80, 0
	s_cmp_gt_u32 s81, 29
	s_cbranch_scc0 .LBB0_2146
	s_and_b64 vcc, exec, s[14:15]
	s_cbranch_vccz .LBB0_2149
	s_barrier

.LBB0_2410:
	ds_read_b128 v[130:133], v181
	ds_read_b128 v[134:137], v181 offset:1024
	ds_read_b128 v[138:141], v181 offset:2048
	ds_read_b128 v[142:145], v181 offset:3072
	ds_read_b128 v[146:149], v182
	ds_read_b128 v[150:153], v182 offset:1024
	ds_read_b128 v[154:157], v182 offset:2048
	ds_read_b128 v[158:161], v182 offset:3072
	s_cmp_eq_u32 s78, 28
	s_cselect_b32 s27, s15, s75
	s_cselect_b32 s26, s73, s74
	s_cselect_b32 s29, s17, s77
	s_cselect_b32 s28, s71, s76
	ds_read_b128 v[166:169], v183
	ds_read_b128 v[170:173], v183 offset:1024
	ds_read_b128 v[186:189], v183 offset:2048
	ds_read_b128 v[190:193], v183 offset:3072
	ds_read_b128 v[194:197], v183 offset:4096
	ds_read_b128 v[198:201], v183 offset:5120
	ds_read_b128 v[202:205], v183 offset:6144
	ds_read_b128 v[206:209], v183 offset:7168
	s_add_u32 s80, s24, 0xfff80000
	s_addc_u32 s81, s25, -1
	s_mov_b32 s79, m0
	s_mov_b32 m0, s64
	s_nop 0
	global_load_lds_dwordx4 v1, s[80:81]
	s_mov_b32 m0, s79
	s_nop 0
	s_mov_b32 s79, m0
	s_mov_b32 m0, s66
	s_nop 0
	global_load_lds_dwordx4 v177, s[80:81]
	s_mov_b32 m0, s79
	s_nop 0
	s_mov_b32 s79, m0
	s_mov_b32 m0, s65
	s_nop 0
	global_load_lds_dwordx4 v1, s[24:25]
	s_mov_b32 m0, s79
	s_nop 0
	s_mov_b32 s79, m0
	s_mov_b32 m0, s67
	s_nop 0
	global_load_lds_dwordx4 v177, s[24:25]
	s_mov_b32 m0, s79
	s_waitcnt vmcnt(8)
	s_waitcnt lgkmcnt(0)
	s_barrier
	s_setprio 1
	s_waitcnt lgkmcnt(7)
	v_mfma_f32_16x16x32_bf16 v[126:129], v[130:133], v[166:169], v[126:129]
	v_mfma_f32_16x16x32_bf16 v[122:125], v[138:141], v[166:169], v[122:125]
	s_waitcnt lgkmcnt(5)
	v_mfma_f32_16x16x32_bf16 v[118:121], v[130:133], v[186:189], v[118:121]
	v_mfma_f32_16x16x32_bf16 v[114:117], v[138:141], v[186:189], v[114:117]
	s_waitcnt lgkmcnt(3)
	v_mfma_f32_16x16x32_bf16 v[94:97], v[130:133], v[194:197], v[94:97]
	v_mfma_f32_16x16x32_bf16 v[90:93], v[138:141], v[194:197], v[90:93]
	s_waitcnt lgkmcnt(1)
	v_mfma_f32_16x16x32_bf16 v[86:89], v[130:133], v[202:205], v[86:89]
	v_mfma_f32_16x16x32_bf16 v[78:81], v[138:141], v[202:205], v[78:81]
	v_mfma_f32_16x16x32_bf16 v[126:129], v[134:137], v[170:173], v[126:129]
	v_mfma_f32_16x16x32_bf16 v[122:125], v[142:145], v[170:173], v[122:125]
	v_mfma_f32_16x16x32_bf16 v[118:121], v[134:137], v[190:193], v[118:121]
	v_mfma_f32_16x16x32_bf16 v[114:117], v[142:145], v[190:193], v[114:117]
	v_mfma_f32_16x16x32_bf16 v[94:97], v[134:137], v[198:201], v[94:97]
	v_mfma_f32_16x16x32_bf16 v[90:93], v[142:145], v[198:201], v[90:93]
	s_waitcnt lgkmcnt(0)
	v_mfma_f32_16x16x32_bf16 v[86:89], v[134:137], v[206:209], v[86:89]
	v_mfma_f32_16x16x32_bf16 v[78:81], v[142:145], v[206:209], v[78:81]
	s_setprio 0
	s_setprio 1
	v_mfma_f32_16x16x32_bf16 v[110:113], v[146:149], v[166:169], v[110:113]
	v_mfma_f32_16x16x32_bf16 v[106:109], v[154:157], v[166:169], v[106:109]
	v_mfma_f32_16x16x32_bf16 v[102:105], v[146:149], v[186:189], v[102:105]
	v_mfma_f32_16x16x32_bf16 v[98:101], v[154:157], v[186:189], v[98:101]
	v_mfma_f32_16x16x32_bf16 v[82:85], v[146:149], v[194:197], v[82:85]
	v_mfma_f32_16x16x32_bf16 v[74:77], v[154:157], v[194:197], v[74:77]
	v_mfma_f32_16x16x32_bf16 v[70:73], v[146:149], v[202:205], v[70:73]
	v_mfma_f32_16x16x32_bf16 v[66:69], v[154:157], v[202:205], v[66:69]
	v_mfma_f32_16x16x32_bf16 v[110:113], v[150:153], v[170:173], v[110:113]
	v_mfma_f32_16x16x32_bf16 v[106:109], v[158:161], v[170:173], v[106:109]
	v_mfma_f32_16x16x32_bf16 v[102:105], v[150:153], v[190:193], v[102:105]
	v_mfma_f32_16x16x32_bf16 v[98:101], v[158:161], v[190:193], v[98:101]
	v_mfma_f32_16x16x32_bf16 v[82:85], v[150:153], v[198:201], v[82:85]
	v_mfma_f32_16x16x32_bf16 v[74:77], v[158:161], v[198:201], v[74:77]
	s_setprio 2
	s_barrier
	v_mfma_f32_16x16x32_bf16 v[70:73], v[150:153], v[206:209], v[70:73]
	v_mfma_f32_16x16x32_bf16 v[66:69], v[158:161], v[206:209], v[66:69]
	s_setprio 0
	ds_read_b128 v[166:169], v183 offset:16384
	ds_read_b128 v[170:173], v183 offset:17408
	ds_read_b128 v[186:189], v183 offset:18432
	ds_read_b128 v[190:193], v183 offset:19456
	ds_read_b128 v[194:197], v183 offset:20480
	ds_read_b128 v[198:201], v183 offset:21504
	ds_read_b128 v[202:205], v183 offset:22528
	ds_read_b128 v[206:209], v183 offset:23552
	s_mov_b32 s79, m0
	s_mov_b32 m0, s41
	s_nop 0
	global_load_lds_dwordx4 v176, s[26:27]
	s_mov_b32 m0, s79
	s_add_u32 s80, s26, 0x80000
	s_mov_b32 s79, m0
	s_mov_b32 m0, s42
	s_nop 0
	global_load_lds_dwordx4 v178, s[26:27]
	s_mov_b32 m0, s79
	s_addc_u32 s81, s27, 0
	s_mov_b32 s79, m0
	s_mov_b32 m0, s43
	s_nop 0
	global_load_lds_dwordx4 v176, s[80:81]
	s_mov_b32 m0, s79
	s_nop 0
	s_mov_b32 s79, m0
	s_mov_b32 m0, s46
	s_nop 0
	global_load_lds_dwordx4 v178, s[80:81]
	s_mov_b32 m0, s79
	s_waitcnt vmcnt(4)
	s_waitcnt lgkmcnt(0)
	s_barrier
	s_setprio 1
	s_waitcnt lgkmcnt(7)
	v_mfma_f32_16x16x32_bf16 v[62:65], v[130:133], v[166:169], v[62:65]
	v_mfma_f32_16x16x32_bf16 v[58:61], v[138:141], v[166:169], v[58:61]
	s_waitcnt lgkmcnt(5)
	v_mfma_f32_16x16x32_bf16 v[46:49], v[130:133], v[186:189], v[46:49]
	v_mfma_f32_16x16x32_bf16 v[42:45], v[138:141], v[186:189], v[42:45]
	s_waitcnt lgkmcnt(3)
	v_mfma_f32_16x16x32_bf16 v[30:33], v[130:133], v[194:197], v[30:33]
	v_mfma_f32_16x16x32_bf16 v[26:29], v[138:141], v[194:197], v[26:29]
	s_waitcnt lgkmcnt(1)
	v_mfma_f32_16x16x32_bf16 v[14:17], v[130:133], v[202:205], v[14:17]
	v_mfma_f32_16x16x32_bf16 v[10:13], v[138:141], v[202:205], v[10:13]
	v_mfma_f32_16x16x32_bf16 v[62:65], v[134:137], v[170:173], v[62:65]
	v_mfma_f32_16x16x32_bf16 v[58:61], v[142:145], v[170:173], v[58:61]
	v_mfma_f32_16x16x32_bf16 v[46:49], v[134:137], v[190:193], v[46:49]
	v_mfma_f32_16x16x32_bf16 v[42:45], v[142:145], v[190:193], v[42:45]
	v_mfma_f32_16x16x32_bf16 v[30:33], v[134:137], v[198:201], v[30:33]
	v_mfma_f32_16x16x32_bf16 v[26:29], v[142:145], v[198:201], v[26:29]
	s_waitcnt lgkmcnt(0)
	v_mfma_f32_16x16x32_bf16 v[14:17], v[134:137], v[206:209], v[14:17]
	v_mfma_f32_16x16x32_bf16 v[10:13], v[142:145], v[206:209], v[10:13]
	s_setprio 0
	s_setprio 1
	v_mfma_f32_16x16x32_bf16 v[54:57], v[146:149], v[166:169], v[54:57]
	v_mfma_f32_16x16x32_bf16 v[50:53], v[154:157], v[166:169], v[50:53]
	v_mfma_f32_16x16x32_bf16 v[38:41], v[146:149], v[186:189], v[38:41]
	v_mfma_f32_16x16x32_bf16 v[34:37], v[154:157], v[186:189], v[34:37]
	v_mfma_f32_16x16x32_bf16 v[22:25], v[146:149], v[194:197], v[22:25]
	v_mfma_f32_16x16x32_bf16 v[18:21], v[154:157], v[194:197], v[18:21]
	v_mfma_f32_16x16x32_bf16 v[6:9], v[146:149], v[202:205], v[6:9]
	v_mfma_f32_16x16x32_bf16 v[2:5], v[154:157], v[202:205], v[2:5]
	v_mfma_f32_16x16x32_bf16 v[54:57], v[150:153], v[170:173], v[54:57]
	v_mfma_f32_16x16x32_bf16 v[50:53], v[158:161], v[170:173], v[50:53]
	v_mfma_f32_16x16x32_bf16 v[38:41], v[150:153], v[190:193], v[38:41]
	v_mfma_f32_16x16x32_bf16 v[34:37], v[158:161], v[190:193], v[34:37]
	v_mfma_f32_16x16x32_bf16 v[22:25], v[150:153], v[198:201], v[22:25]
	v_mfma_f32_16x16x32_bf16 v[18:21], v[158:161], v[198:201], v[18:21]
	s_setprio 2
	s_barrier
	v_mfma_f32_16x16x32_bf16 v[6:9], v[150:153], v[206:209], v[6:9]
	v_mfma_f32_16x16x32_bf16 v[2:5], v[158:161], v[206:209], v[2:5]
	s_setprio 0
	ds_read_b128 v[130:133], v184
	ds_read_b128 v[134:137], v184 offset:1024
	ds_read_b128 v[138:141], v184 offset:2048
	ds_read_b128 v[142:145], v184 offset:3072
	ds_read_b128 v[146:149], v185
	ds_read_b128 v[150:153], v185 offset:1024
	ds_read_b128 v[154:157], v185 offset:2048
	ds_read_b128 v[158:161], v185 offset:3072
	ds_read_b128 v[166:169], v183 offset:32768
	ds_read_b128 v[170:173], v183 offset:33792
	ds_read_b128 v[186:189], v183 offset:34816
	ds_read_b128 v[190:193], v183 offset:35840
	ds_read_b128 v[194:197], v183 offset:36864
	ds_read_b128 v[198:201], v183 offset:37888
	ds_read_b128 v[202:205], v183 offset:38912
	ds_read_b128 v[206:209], v183 offset:39936
	s_mov_b32 s79, m0
	s_mov_b32 m0, s40
	s_nop 0
	global_load_lds_dwordx4 v1, s[28:29]
	s_mov_b32 m0, s79
	s_nop 0
	s_mov_b32 s79, m0
	s_mov_b32 m0, s47
	s_nop 0
	global_load_lds_dwordx4 v177, s[28:29]
	s_mov_b32 m0, s79
	s_add_u32 s28, s28, 0x80000
	s_addc_u32 s29, s29, 0
	s_mov_b32 s79, m0
	s_mov_b32 m0, s48
	s_nop 0
	global_load_lds_dwordx4 v1, s[28:29]
	s_mov_b32 m0, s79
	s_nop 0
	s_mov_b32 s79, m0
	s_mov_b32 m0, s49
	s_nop 0
	global_load_lds_dwordx4 v177, s[28:29]
	s_mov_b32 m0, s79
	s_waitcnt vmcnt(8)
	s_waitcnt lgkmcnt(0)
	s_barrier
	s_setprio 1
	s_waitcnt lgkmcnt(7)
	v_mfma_f32_16x16x32_bf16 v[126:129], v[130:133], v[166:169], v[126:129]
	v_mfma_f32_16x16x32_bf16 v[122:125], v[138:141], v[166:169], v[122:125]
	s_waitcnt lgkmcnt(5)
	v_mfma_f32_16x16x32_bf16 v[118:121], v[130:133], v[186:189], v[118:121]
	v_mfma_f32_16x16x32_bf16 v[114:117], v[138:141], v[186:189], v[114:117]
	s_waitcnt lgkmcnt(3)
	v_mfma_f32_16x16x32_bf16 v[94:97], v[130:133], v[194:197], v[94:97]
	v_mfma_f32_16x16x32_bf16 v[90:93], v[138:141], v[194:197], v[90:93]
	s_waitcnt lgkmcnt(1)
	v_mfma_f32_16x16x32_bf16 v[86:89], v[130:133], v[202:205], v[86:89]
	v_mfma_f32_16x16x32_bf16 v[78:81], v[138:141], v[202:205], v[78:81]
	v_mfma_f32_16x16x32_bf16 v[126:129], v[134:137], v[170:173], v[126:129]
	v_mfma_f32_16x16x32_bf16 v[122:125], v[142:145], v[170:173], v[122:125]
	v_mfma_f32_16x16x32_bf16 v[118:121], v[134:137], v[190:193], v[118:121]
	v_mfma_f32_16x16x32_bf16 v[114:117], v[142:145], v[190:193], v[114:117]
	v_mfma_f32_16x16x32_bf16 v[94:97], v[134:137], v[198:201], v[94:97]
	v_mfma_f32_16x16x32_bf16 v[90:93], v[142:145], v[198:201], v[90:93]
	s_waitcnt lgkmcnt(0)
	v_mfma_f32_16x16x32_bf16 v[86:89], v[134:137], v[206:209], v[86:89]
	v_mfma_f32_16x16x32_bf16 v[78:81], v[142:145], v[206:209], v[78:81]
	s_setprio 0
	s_setprio 1
	v_mfma_f32_16x16x32_bf16 v[110:113], v[146:149], v[166:169], v[110:113]
	v_mfma_f32_16x16x32_bf16 v[106:109], v[154:157], v[166:169], v[106:109]
	v_mfma_f32_16x16x32_bf16 v[102:105], v[146:149], v[186:189], v[102:105]
	v_mfma_f32_16x16x32_bf16 v[98:101], v[154:157], v[186:189], v[98:101]
	v_mfma_f32_16x16x32_bf16 v[82:85], v[146:149], v[194:197], v[82:85]
	v_mfma_f32_16x16x32_bf16 v[74:77], v[154:157], v[194:197], v[74:77]
	v_mfma_f32_16x16x32_bf16 v[70:73], v[146:149], v[202:205], v[70:73]
	v_mfma_f32_16x16x32_bf16 v[66:69], v[154:157], v[202:205], v[66:69]
	v_mfma_f32_16x16x32_bf16 v[110:113], v[150:153], v[170:173], v[110:113]
	v_mfma_f32_16x16x32_bf16 v[106:109], v[158:161], v[170:173], v[106:109]
	v_mfma_f32_16x16x32_bf16 v[102:105], v[150:153], v[190:193], v[102:105]
	v_mfma_f32_16x16x32_bf16 v[98:101], v[158:161], v[190:193], v[98:101]
	v_mfma_f32_16x16x32_bf16 v[82:85], v[150:153], v[198:201], v[82:85]
	v_mfma_f32_16x16x32_bf16 v[74:77], v[158:161], v[198:201], v[74:77]
	s_setprio 2
	s_barrier
	v_mfma_f32_16x16x32_bf16 v[70:73], v[150:153], v[206:209], v[70:73]
	v_mfma_f32_16x16x32_bf16 v[66:69], v[158:161], v[206:209], v[66:69]
	s_setprio 0
	ds_read_b128 v[166:169], v183 offset:49152
	ds_read_b128 v[170:173], v183 offset:50176
	ds_read_b128 v[186:189], v183 offset:51200
	ds_read_b128 v[190:193], v183 offset:52224
	ds_read_b128 v[194:197], v183 offset:53248
	ds_read_b128 v[198:201], v183 offset:54272
	ds_read_b128 v[202:205], v183 offset:55296
	ds_read_b128 v[206:209], v183 offset:56320
	s_add_u32 s28, s26, 0x80
	s_addc_u32 s29, s27, 0
	s_mov_b32 s79, m0
	s_mov_b32 m0, s56
	s_nop 0
	global_load_lds_dwordx4 v176, s[28:29]
	s_mov_b32 m0, s79
	s_add_u32 s26, s26, 0x80080
	s_mov_b32 s79, m0
	s_mov_b32 m0, s57
	s_nop 0
	global_load_lds_dwordx4 v178, s[28:29]
	s_mov_b32 m0, s79
	s_addc_u32 s27, s27, 0
	s_mov_b32 s28, m0
	s_mov_b32 m0, s58
	s_nop 0
	global_load_lds_dwordx4 v176, s[26:27]
	s_mov_b32 m0, s28
	s_nop 0
	s_mov_b32 s28, m0
	s_mov_b32 m0, s59
	s_nop 0
	global_load_lds_dwordx4 v178, s[26:27]
	s_mov_b32 m0, s28
	s_waitcnt vmcnt(4)
	s_waitcnt lgkmcnt(0)
	s_barrier
	s_setprio 1
	s_waitcnt lgkmcnt(7)
	v_mfma_f32_16x16x32_bf16 v[62:65], v[130:133], v[166:169], v[62:65]
	v_mfma_f32_16x16x32_bf16 v[58:61], v[138:141], v[166:169], v[58:61]
	s_waitcnt lgkmcnt(5)
	v_mfma_f32_16x16x32_bf16 v[46:49], v[130:133], v[186:189], v[46:49]
	v_mfma_f32_16x16x32_bf16 v[42:45], v[138:141], v[186:189], v[42:45]
	s_waitcnt lgkmcnt(3)
	v_mfma_f32_16x16x32_bf16 v[30:33], v[130:133], v[194:197], v[30:33]
	v_mfma_f32_16x16x32_bf16 v[26:29], v[138:141], v[194:197], v[26:29]
	s_waitcnt lgkmcnt(1)
	v_mfma_f32_16x16x32_bf16 v[14:17], v[130:133], v[202:205], v[14:17]
	v_mfma_f32_16x16x32_bf16 v[10:13], v[138:141], v[202:205], v[10:13]
	v_mfma_f32_16x16x32_bf16 v[62:65], v[134:137], v[170:173], v[62:65]
	v_mfma_f32_16x16x32_bf16 v[58:61], v[142:145], v[170:173], v[58:61]
	v_mfma_f32_16x16x32_bf16 v[46:49], v[134:137], v[190:193], v[46:49]
	v_mfma_f32_16x16x32_bf16 v[42:45], v[142:145], v[190:193], v[42:45]
	v_mfma_f32_16x16x32_bf16 v[30:33], v[134:137], v[198:201], v[30:33]
	v_mfma_f32_16x16x32_bf16 v[26:29], v[142:145], v[198:201], v[26:29]
	s_waitcnt lgkmcnt(0)
	v_mfma_f32_16x16x32_bf16 v[14:17], v[134:137], v[206:209], v[14:17]
	v_mfma_f32_16x16x32_bf16 v[10:13], v[142:145], v[206:209], v[10:13]
	s_setprio 0
	s_setprio 1
	v_mfma_f32_16x16x32_bf16 v[54:57], v[146:149], v[166:169], v[54:57]
	v_mfma_f32_16x16x32_bf16 v[50:53], v[154:157], v[166:169], v[50:53]
	v_mfma_f32_16x16x32_bf16 v[38:41], v[146:149], v[186:189], v[38:41]
	v_mfma_f32_16x16x32_bf16 v[34:37], v[154:157], v[186:189], v[34:37]
	v_mfma_f32_16x16x32_bf16 v[22:25], v[146:149], v[194:197], v[22:25]
	v_mfma_f32_16x16x32_bf16 v[18:21], v[154:157], v[194:197], v[18:21]
	v_mfma_f32_16x16x32_bf16 v[6:9], v[146:149], v[202:205], v[6:9]
	v_mfma_f32_16x16x32_bf16 v[2:5], v[154:157], v[202:205], v[2:5]
	v_mfma_f32_16x16x32_bf16 v[54:57], v[150:153], v[170:173], v[54:57]
	v_mfma_f32_16x16x32_bf16 v[50:53], v[158:161], v[170:173], v[50:53]
	v_mfma_f32_16x16x32_bf16 v[38:41], v[150:153], v[190:193], v[38:41]
	v_mfma_f32_16x16x32_bf16 v[34:37], v[158:161], v[190:193], v[34:37]
	v_mfma_f32_16x16x32_bf16 v[22:25], v[150:153], v[198:201], v[22:25]
	v_mfma_f32_16x16x32_bf16 v[18:21], v[158:161], v[198:201], v[18:21]
	s_setprio 2
	s_barrier
	v_mfma_f32_16x16x32_bf16 v[6:9], v[150:153], v[206:209], v[6:9]
	v_mfma_f32_16x16x32_bf16 v[2:5], v[158:161], v[206:209], v[2:5]
	s_setprio 0
	s_add_i32 s78, s78, 2
	s_add_u32 s74, s74, 0x100
	s_addc_u32 s75, s75, 0
	s_add_u32 s24, s24, 0x100
	s_addc_u32 s25, s25, 0
	s_add_u32 s76, s76, 0x100
	s_addc_u32 s77, s77, 0
	s_cmp_gt_u32 s78, 29
	s_cbranch_scc0 .LBB0_2410
	s_and_b64 vcc, exec, s[8:9]
	s_cbranch_vccz .LBB0_2413
	s_barrier

.LBB0_2594:
	ds_read_b128 v[148:151], v143
	ds_read_b128 v[152:155], v143 offset:1024
	ds_read_b128 v[156:159], v143 offset:2048
	ds_read_b128 v[160:163], v143 offset:3072
	ds_read_b128 v[164:167], v144
	ds_read_b128 v[168:171], v144 offset:1024
	ds_read_b128 v[172:175], v144 offset:2048
	ds_read_b128 v[176:179], v144 offset:3072
	s_cmp_eq_u32 s70, 28
	s_cselect_b32 s21, s9, s65
	s_cselect_b32 s20, s63, s64
	s_cselect_b32 s23, s11, s67
	s_cselect_b32 s22, s62, s66
	ds_read_b128 v[180:183], v145
	ds_read_b128 v[184:187], v145 offset:1024
	ds_read_b128 v[188:191], v145 offset:2048
	ds_read_b128 v[192:195], v145 offset:3072
	ds_read_b128 v[196:199], v145 offset:4096
	ds_read_b128 v[200:203], v145 offset:5120
	ds_read_b128 v[204:207], v145 offset:6144
	ds_read_b128 v[208:211], v145 offset:7168
	s_add_u32 s74, s18, 0xfff80000
	s_addc_u32 s75, s19, -1
	s_mov_b32 s71, m0
	s_mov_b32 m0, s48
	s_nop 0
	global_load_lds_dwordx4 v138, s[74:75]
	s_mov_b32 m0, s71
	s_nop 0
	s_mov_b32 s71, m0
	s_mov_b32 m0, s57
	s_nop 0
	global_load_lds_dwordx4 v140, s[74:75]
	s_mov_b32 m0, s71
	s_nop 0
	s_mov_b32 s71, m0
	s_mov_b32 m0, s49
	s_nop 0
	global_load_lds_dwordx4 v138, s[18:19]
	s_mov_b32 m0, s71
	s_nop 0
	s_mov_b32 s71, m0
	s_mov_b32 m0, s58
	s_nop 0
	global_load_lds_dwordx4 v140, s[18:19]
	s_mov_b32 m0, s71
	s_waitcnt vmcnt(8)
	s_waitcnt lgkmcnt(0)
	s_barrier
	s_setprio 1
	s_waitcnt lgkmcnt(7)
	v_mfma_f32_16x16x32_bf16 v[126:129], v[148:151], v[180:183], v[126:129]
	v_mfma_f32_16x16x32_bf16 v[122:125], v[156:159], v[180:183], v[122:125]
	s_waitcnt lgkmcnt(5)
	v_mfma_f32_16x16x32_bf16 v[110:113], v[148:151], v[188:191], v[110:113]
	v_mfma_f32_16x16x32_bf16 v[106:109], v[156:159], v[188:191], v[106:109]
	s_waitcnt lgkmcnt(3)
	v_mfma_f32_16x16x32_bf16 v[94:97], v[148:151], v[196:199], v[94:97]
	v_mfma_f32_16x16x32_bf16 v[90:93], v[156:159], v[196:199], v[90:93]
	s_waitcnt lgkmcnt(1)
	v_mfma_f32_16x16x32_bf16 v[78:81], v[148:151], v[204:207], v[78:81]
	v_mfma_f32_16x16x32_bf16 v[74:77], v[156:159], v[204:207], v[74:77]
	v_mfma_f32_16x16x32_bf16 v[126:129], v[152:155], v[184:187], v[126:129]
	v_mfma_f32_16x16x32_bf16 v[122:125], v[160:163], v[184:187], v[122:125]
	v_mfma_f32_16x16x32_bf16 v[110:113], v[152:155], v[192:195], v[110:113]
	v_mfma_f32_16x16x32_bf16 v[106:109], v[160:163], v[192:195], v[106:109]
	v_mfma_f32_16x16x32_bf16 v[94:97], v[152:155], v[200:203], v[94:97]
	v_mfma_f32_16x16x32_bf16 v[90:93], v[160:163], v[200:203], v[90:93]
	s_waitcnt lgkmcnt(0)
	v_mfma_f32_16x16x32_bf16 v[78:81], v[152:155], v[208:211], v[78:81]
	v_mfma_f32_16x16x32_bf16 v[74:77], v[160:163], v[208:211], v[74:77]
	s_setprio 0
	s_setprio 1
	v_mfma_f32_16x16x32_bf16 v[118:121], v[164:167], v[180:183], v[118:121]
	v_mfma_f32_16x16x32_bf16 v[114:117], v[172:175], v[180:183], v[114:117]
	v_mfma_f32_16x16x32_bf16 v[102:105], v[164:167], v[188:191], v[102:105]
	v_mfma_f32_16x16x32_bf16 v[98:101], v[172:175], v[188:191], v[98:101]
	v_mfma_f32_16x16x32_bf16 v[86:89], v[164:167], v[196:199], v[86:89]
	v_mfma_f32_16x16x32_bf16 v[82:85], v[172:175], v[196:199], v[82:85]
	v_mfma_f32_16x16x32_bf16 v[70:73], v[164:167], v[204:207], v[70:73]
	v_mfma_f32_16x16x32_bf16 v[66:69], v[172:175], v[204:207], v[66:69]
	v_mfma_f32_16x16x32_bf16 v[118:121], v[168:171], v[184:187], v[118:121]
	v_mfma_f32_16x16x32_bf16 v[114:117], v[176:179], v[184:187], v[114:117]
	v_mfma_f32_16x16x32_bf16 v[102:105], v[168:171], v[192:195], v[102:105]
	v_mfma_f32_16x16x32_bf16 v[98:101], v[176:179], v[192:195], v[98:101]
	v_mfma_f32_16x16x32_bf16 v[86:89], v[168:171], v[200:203], v[86:89]
	v_mfma_f32_16x16x32_bf16 v[82:85], v[176:179], v[200:203], v[82:85]
	s_setprio 2
	s_barrier
	v_mfma_f32_16x16x32_bf16 v[70:73], v[168:171], v[208:211], v[70:73]
	v_mfma_f32_16x16x32_bf16 v[66:69], v[176:179], v[208:211], v[66:69]
	s_setprio 0
	ds_read_b128 v[180:183], v145 offset:16384
	ds_read_b128 v[184:187], v145 offset:17408
	ds_read_b128 v[188:191], v145 offset:18432
	ds_read_b128 v[192:195], v145 offset:19456
	ds_read_b128 v[196:199], v145 offset:20480
	ds_read_b128 v[200:203], v145 offset:21504
	ds_read_b128 v[204:207], v145 offset:22528
	ds_read_b128 v[208:211], v145 offset:23552
	s_mov_b32 s71, m0
	s_mov_b32 m0, s35
	s_nop 0
	global_load_lds_dwordx4 v139, s[20:21]
	s_mov_b32 m0, s71
	s_add_u32 s74, s20, 0x80000
	s_mov_b32 s71, m0
	s_mov_b32 m0, s36
	s_nop 0
	global_load_lds_dwordx4 v141, s[20:21]
	s_mov_b32 m0, s71
	s_addc_u32 s75, s21, 0
	s_mov_b32 s71, m0
	s_mov_b32 m0, s37
	s_nop 0
	global_load_lds_dwordx4 v139, s[74:75]
	s_mov_b32 m0, s71
	s_nop 0
	s_mov_b32 s71, m0
	s_mov_b32 m0, s40
	s_nop 0
	global_load_lds_dwordx4 v141, s[74:75]
	s_mov_b32 m0, s71
	s_waitcnt vmcnt(4)
	s_waitcnt lgkmcnt(0)
	s_barrier
	s_setprio 1
	s_waitcnt lgkmcnt(7)
	v_mfma_f32_16x16x32_bf16 v[62:65], v[148:151], v[180:183], v[62:65]
	v_mfma_f32_16x16x32_bf16 v[58:61], v[156:159], v[180:183], v[58:61]
	s_waitcnt lgkmcnt(5)
	v_mfma_f32_16x16x32_bf16 v[46:49], v[148:151], v[188:191], v[46:49]
	v_mfma_f32_16x16x32_bf16 v[42:45], v[156:159], v[188:191], v[42:45]
	s_waitcnt lgkmcnt(3)
	v_mfma_f32_16x16x32_bf16 v[30:33], v[148:151], v[196:199], v[30:33]
	v_mfma_f32_16x16x32_bf16 v[26:29], v[156:159], v[196:199], v[26:29]
	s_waitcnt lgkmcnt(1)
	v_mfma_f32_16x16x32_bf16 v[14:17], v[148:151], v[204:207], v[14:17]
	v_mfma_f32_16x16x32_bf16 v[10:13], v[156:159], v[204:207], v[10:13]
	v_mfma_f32_16x16x32_bf16 v[62:65], v[152:155], v[184:187], v[62:65]
	v_mfma_f32_16x16x32_bf16 v[58:61], v[160:163], v[184:187], v[58:61]
	v_mfma_f32_16x16x32_bf16 v[46:49], v[152:155], v[192:195], v[46:49]
	v_mfma_f32_16x16x32_bf16 v[42:45], v[160:163], v[192:195], v[42:45]
	v_mfma_f32_16x16x32_bf16 v[30:33], v[152:155], v[200:203], v[30:33]
	v_mfma_f32_16x16x32_bf16 v[26:29], v[160:163], v[200:203], v[26:29]
	s_waitcnt lgkmcnt(0)
	v_mfma_f32_16x16x32_bf16 v[14:17], v[152:155], v[208:211], v[14:17]
	v_mfma_f32_16x16x32_bf16 v[10:13], v[160:163], v[208:211], v[10:13]
	s_setprio 0
	s_setprio 1
	v_mfma_f32_16x16x32_bf16 v[54:57], v[164:167], v[180:183], v[54:57]
	v_mfma_f32_16x16x32_bf16 v[50:53], v[172:175], v[180:183], v[50:53]
	v_mfma_f32_16x16x32_bf16 v[38:41], v[164:167], v[188:191], v[38:41]
	v_mfma_f32_16x16x32_bf16 v[34:37], v[172:175], v[188:191], v[34:37]
	v_mfma_f32_16x16x32_bf16 v[22:25], v[164:167], v[196:199], v[22:25]
	v_mfma_f32_16x16x32_bf16 v[18:21], v[172:175], v[196:199], v[18:21]
	v_mfma_f32_16x16x32_bf16 v[6:9], v[164:167], v[204:207], v[6:9]
	v_mfma_f32_16x16x32_bf16 v[2:5], v[172:175], v[204:207], v[2:5]
	v_mfma_f32_16x16x32_bf16 v[54:57], v[168:171], v[184:187], v[54:57]
	v_mfma_f32_16x16x32_bf16 v[50:53], v[176:179], v[184:187], v[50:53]
	v_mfma_f32_16x16x32_bf16 v[38:41], v[168:171], v[192:195], v[38:41]
	v_mfma_f32_16x16x32_bf16 v[34:37], v[176:179], v[192:195], v[34:37]
	v_mfma_f32_16x16x32_bf16 v[22:25], v[168:171], v[200:203], v[22:25]
	v_mfma_f32_16x16x32_bf16 v[18:21], v[176:179], v[200:203], v[18:21]
	s_setprio 2
	s_barrier
	v_mfma_f32_16x16x32_bf16 v[6:9], v[168:171], v[208:211], v[6:9]
	v_mfma_f32_16x16x32_bf16 v[2:5], v[176:179], v[208:211], v[2:5]
	s_setprio 0
	ds_read_b128 v[148:151], v146
	ds_read_b128 v[152:155], v146 offset:1024
	ds_read_b128 v[156:159], v146 offset:2048
	ds_read_b128 v[160:163], v146 offset:3072
	ds_read_b128 v[164:167], v147
	ds_read_b128 v[168:171], v147 offset:1024
	ds_read_b128 v[172:175], v147 offset:2048
	ds_read_b128 v[176:179], v147 offset:3072
	ds_read_b128 v[180:183], v145 offset:32768
	ds_read_b128 v[184:187], v145 offset:33792
	ds_read_b128 v[188:191], v145 offset:34816
	ds_read_b128 v[192:195], v145 offset:35840
	ds_read_b128 v[196:199], v145 offset:36864
	ds_read_b128 v[200:203], v145 offset:37888
	ds_read_b128 v[204:207], v145 offset:38912
	ds_read_b128 v[208:211], v145 offset:39936
	s_mov_b32 s71, m0
	s_mov_b32 m0, s31
	s_nop 0
	global_load_lds_dwordx4 v138, s[22:23]
	s_mov_b32 m0, s71
	s_nop 0
	s_mov_b32 s71, m0
	s_mov_b32 m0, s41
	s_nop 0
	global_load_lds_dwordx4 v140, s[22:23]
	s_mov_b32 m0, s71
	s_add_u32 s22, s22, 0x80000
	s_addc_u32 s23, s23, 0
	s_mov_b32 s71, m0
	s_mov_b32 m0, s42
	s_nop 0
	global_load_lds_dwordx4 v138, s[22:23]
	s_mov_b32 m0, s71
	s_nop 0
	s_mov_b32 s71, m0
	s_mov_b32 m0, s43
	s_nop 0
	global_load_lds_dwordx4 v140, s[22:23]
	s_mov_b32 m0, s71
	s_waitcnt vmcnt(8)
	s_waitcnt lgkmcnt(0)
	s_barrier
	s_setprio 1
	s_waitcnt lgkmcnt(7)
	v_mfma_f32_16x16x32_bf16 v[126:129], v[148:151], v[180:183], v[126:129]
	v_mfma_f32_16x16x32_bf16 v[122:125], v[156:159], v[180:183], v[122:125]
	s_waitcnt lgkmcnt(5)
	v_mfma_f32_16x16x32_bf16 v[110:113], v[148:151], v[188:191], v[110:113]
	v_mfma_f32_16x16x32_bf16 v[106:109], v[156:159], v[188:191], v[106:109]
	s_waitcnt lgkmcnt(3)
	v_mfma_f32_16x16x32_bf16 v[94:97], v[148:151], v[196:199], v[94:97]
	v_mfma_f32_16x16x32_bf16 v[90:93], v[156:159], v[196:199], v[90:93]
	s_waitcnt lgkmcnt(1)
	v_mfma_f32_16x16x32_bf16 v[78:81], v[148:151], v[204:207], v[78:81]
	v_mfma_f32_16x16x32_bf16 v[74:77], v[156:159], v[204:207], v[74:77]
	v_mfma_f32_16x16x32_bf16 v[126:129], v[152:155], v[184:187], v[126:129]
	v_mfma_f32_16x16x32_bf16 v[122:125], v[160:163], v[184:187], v[122:125]
	v_mfma_f32_16x16x32_bf16 v[110:113], v[152:155], v[192:195], v[110:113]
	v_mfma_f32_16x16x32_bf16 v[106:109], v[160:163], v[192:195], v[106:109]
	v_mfma_f32_16x16x32_bf16 v[94:97], v[152:155], v[200:203], v[94:97]
	v_mfma_f32_16x16x32_bf16 v[90:93], v[160:163], v[200:203], v[90:93]
	s_waitcnt lgkmcnt(0)
	v_mfma_f32_16x16x32_bf16 v[78:81], v[152:155], v[208:211], v[78:81]
	v_mfma_f32_16x16x32_bf16 v[74:77], v[160:163], v[208:211], v[74:77]
	s_setprio 0
	s_setprio 1
	v_mfma_f32_16x16x32_bf16 v[118:121], v[164:167], v[180:183], v[118:121]
	v_mfma_f32_16x16x32_bf16 v[114:117], v[172:175], v[180:183], v[114:117]
	v_mfma_f32_16x16x32_bf16 v[102:105], v[164:167], v[188:191], v[102:105]
	v_mfma_f32_16x16x32_bf16 v[98:101], v[172:175], v[188:191], v[98:101]
	v_mfma_f32_16x16x32_bf16 v[86:89], v[164:167], v[196:199], v[86:89]
	v_mfma_f32_16x16x32_bf16 v[82:85], v[172:175], v[196:199], v[82:85]
	v_mfma_f32_16x16x32_bf16 v[70:73], v[164:167], v[204:207], v[70:73]
	v_mfma_f32_16x16x32_bf16 v[66:69], v[172:175], v[204:207], v[66:69]
	v_mfma_f32_16x16x32_bf16 v[118:121], v[168:171], v[184:187], v[118:121]
	v_mfma_f32_16x16x32_bf16 v[114:117], v[176:179], v[184:187], v[114:117]
	v_mfma_f32_16x16x32_bf16 v[102:105], v[168:171], v[192:195], v[102:105]
	v_mfma_f32_16x16x32_bf16 v[98:101], v[176:179], v[192:195], v[98:101]
	v_mfma_f32_16x16x32_bf16 v[86:89], v[168:171], v[200:203], v[86:89]
	v_mfma_f32_16x16x32_bf16 v[82:85], v[176:179], v[200:203], v[82:85]
	s_setprio 2
	s_barrier
	v_mfma_f32_16x16x32_bf16 v[70:73], v[168:171], v[208:211], v[70:73]
	v_mfma_f32_16x16x32_bf16 v[66:69], v[176:179], v[208:211], v[66:69]
	s_setprio 0
	ds_read_b128 v[180:183], v145 offset:49152
	ds_read_b128 v[184:187], v145 offset:50176
	ds_read_b128 v[188:191], v145 offset:51200
	ds_read_b128 v[192:195], v145 offset:52224
	ds_read_b128 v[196:199], v145 offset:53248
	ds_read_b128 v[200:203], v145 offset:54272
	ds_read_b128 v[204:207], v145 offset:55296
	ds_read_b128 v[208:211], v145 offset:56320
	s_add_u32 s22, s20, 0x80
	s_addc_u32 s23, s21, 0
	s_mov_b32 s71, m0
	s_mov_b32 m0, s44
	s_nop 0
	global_load_lds_dwordx4 v139, s[22:23]
	s_mov_b32 m0, s71
	s_add_u32 s20, s20, 0x80080
	s_mov_b32 s71, m0
	s_mov_b32 m0, s45
	s_nop 0
	global_load_lds_dwordx4 v141, s[22:23]
	s_mov_b32 m0, s71
	s_addc_u32 s21, s21, 0
	s_mov_b32 s22, m0
	s_mov_b32 m0, s46
	s_nop 0
	global_load_lds_dwordx4 v139, s[20:21]
	s_mov_b32 m0, s22
	s_nop 0
	s_mov_b32 s22, m0
	s_mov_b32 m0, s47
	s_nop 0
	global_load_lds_dwordx4 v141, s[20:21]
	s_mov_b32 m0, s22
	s_waitcnt vmcnt(4)
	s_waitcnt lgkmcnt(0)
	s_barrier
	s_setprio 1
	s_waitcnt lgkmcnt(7)
	v_mfma_f32_16x16x32_bf16 v[62:65], v[148:151], v[180:183], v[62:65]
	v_mfma_f32_16x16x32_bf16 v[58:61], v[156:159], v[180:183], v[58:61]
	s_waitcnt lgkmcnt(5)
	v_mfma_f32_16x16x32_bf16 v[46:49], v[148:151], v[188:191], v[46:49]
	v_mfma_f32_16x16x32_bf16 v[42:45], v[156:159], v[188:191], v[42:45]
	s_waitcnt lgkmcnt(3)
	v_mfma_f32_16x16x32_bf16 v[30:33], v[148:151], v[196:199], v[30:33]
	v_mfma_f32_16x16x32_bf16 v[26:29], v[156:159], v[196:199], v[26:29]
	s_waitcnt lgkmcnt(1)
	v_mfma_f32_16x16x32_bf16 v[14:17], v[148:151], v[204:207], v[14:17]
	v_mfma_f32_16x16x32_bf16 v[10:13], v[156:159], v[204:207], v[10:13]
	v_mfma_f32_16x16x32_bf16 v[62:65], v[152:155], v[184:187], v[62:65]
	v_mfma_f32_16x16x32_bf16 v[58:61], v[160:163], v[184:187], v[58:61]
	v_mfma_f32_16x16x32_bf16 v[46:49], v[152:155], v[192:195], v[46:49]
	v_mfma_f32_16x16x32_bf16 v[42:45], v[160:163], v[192:195], v[42:45]
	v_mfma_f32_16x16x32_bf16 v[30:33], v[152:155], v[200:203], v[30:33]
	v_mfma_f32_16x16x32_bf16 v[26:29], v[160:163], v[200:203], v[26:29]
	s_waitcnt lgkmcnt(0)
	v_mfma_f32_16x16x32_bf16 v[14:17], v[152:155], v[208:211], v[14:17]
	v_mfma_f32_16x16x32_bf16 v[10:13], v[160:163], v[208:211], v[10:13]
	s_setprio 0
	s_setprio 1
	v_mfma_f32_16x16x32_bf16 v[54:57], v[164:167], v[180:183], v[54:57]
	v_mfma_f32_16x16x32_bf16 v[50:53], v[172:175], v[180:183], v[50:53]
	v_mfma_f32_16x16x32_bf16 v[38:41], v[164:167], v[188:191], v[38:41]
	v_mfma_f32_16x16x32_bf16 v[34:37], v[172:175], v[188:191], v[34:37]
	v_mfma_f32_16x16x32_bf16 v[22:25], v[164:167], v[196:199], v[22:25]
	v_mfma_f32_16x16x32_bf16 v[18:21], v[172:175], v[196:199], v[18:21]
	v_mfma_f32_16x16x32_bf16 v[6:9], v[164:167], v[204:207], v[6:9]
	v_mfma_f32_16x16x32_bf16 v[2:5], v[172:175], v[204:207], v[2:5]
	v_mfma_f32_16x16x32_bf16 v[54:57], v[168:171], v[184:187], v[54:57]
	v_mfma_f32_16x16x32_bf16 v[50:53], v[176:179], v[184:187], v[50:53]
	v_mfma_f32_16x16x32_bf16 v[38:41], v[168:171], v[192:195], v[38:41]
	v_mfma_f32_16x16x32_bf16 v[34:37], v[176:179], v[192:195], v[34:37]
	v_mfma_f32_16x16x32_bf16 v[22:25], v[168:171], v[200:203], v[22:25]
	v_mfma_f32_16x16x32_bf16 v[18:21], v[176:179], v[200:203], v[18:21]
	s_setprio 2
	s_barrier
	v_mfma_f32_16x16x32_bf16 v[6:9], v[168:171], v[208:211], v[6:9]
	v_mfma_f32_16x16x32_bf16 v[2:5], v[176:179], v[208:211], v[2:5]
	s_setprio 0
	s_add_i32 s70, s70, 2
	s_add_u32 s64, s64, 0x100
	s_addc_u32 s65, s65, 0
	s_add_u32 s18, s18, 0x100
	s_addc_u32 s19, s19, 0
	s_add_u32 s66, s66, 0x100
	s_addc_u32 s67, s67, 0
	s_cmp_gt_u32 s70, 29
	s_cbranch_scc0 .LBB0_2594
	s_and_b64 vcc, exec, s[6:7]
	s_cbranch_vccz .LBB0_2597
	s_barrier

.LBB0_2792:
	ds_read_b128 v[130:133], v181
	ds_read_b128 v[134:137], v181 offset:1024
	ds_read_b128 v[138:141], v181 offset:2048
	ds_read_b128 v[142:145], v181 offset:3072
	ds_read_b128 v[150:153], v182
	ds_read_b128 v[154:157], v182 offset:1024
	ds_read_b128 v[158:161], v182 offset:2048
	ds_read_b128 v[162:165], v182 offset:3072
	s_cmpk_eq_i32 s69, 0x52
	s_cselect_b32 s31, s19, s66
	s_cselect_b32 s30, s64, s65
	s_cselect_b32 s35, s21, s68
	s_cselect_b32 s34, s63, s67
	ds_read_b128 v[166:169], v183
	ds_read_b128 v[170:173], v183 offset:1024
	ds_read_b128 v[186:189], v183 offset:2048
	ds_read_b128 v[190:193], v183 offset:3072
	ds_read_b128 v[194:197], v183 offset:4096
	ds_read_b128 v[198:201], v183 offset:5120
	ds_read_b128 v[202:205], v183 offset:6144
	ds_read_b128 v[206:209], v183 offset:7168
	s_add_u32 s70, s28, 0xffffc000
	s_addc_u32 s71, s29, -1
	s_mov_b32 s73, m0
	s_mov_b32 m0, s57
	s_nop 0
	global_load_lds_dwordx4 v1, s[70:71]
	s_mov_b32 m0, s73
	s_nop 0
	s_mov_b32 s73, m0
	s_mov_b32 m0, s59
	s_nop 0
	global_load_lds_dwordx4 v177, s[70:71]
	s_mov_b32 m0, s73
	s_mov_b32 s70, m0
	s_mov_b32 m0, s58
	s_nop 0
	global_load_lds_dwordx4 v1, s[28:29]
	s_mov_b32 m0, s70
	s_nop 0
	s_mov_b32 s70, m0
	s_mov_b32 m0, s60
	s_nop 0
	global_load_lds_dwordx4 v177, s[28:29]
	s_mov_b32 m0, s70
	s_waitcnt vmcnt(8)
	s_waitcnt lgkmcnt(0)
	s_barrier
	s_setprio 1
	s_waitcnt lgkmcnt(7)
	v_mfma_f32_16x16x32_bf16 v[126:129], v[130:133], v[166:169], v[126:129]
	v_mfma_f32_16x16x32_bf16 v[122:125], v[138:141], v[166:169], v[122:125]
	s_waitcnt lgkmcnt(5)
	v_mfma_f32_16x16x32_bf16 v[118:121], v[130:133], v[186:189], v[118:121]
	v_mfma_f32_16x16x32_bf16 v[110:113], v[138:141], v[186:189], v[110:113]
	s_waitcnt lgkmcnt(3)
	v_mfma_f32_16x16x32_bf16 v[94:97], v[130:133], v[194:197], v[94:97]
	v_mfma_f32_16x16x32_bf16 v[90:93], v[138:141], v[194:197], v[90:93]
	s_waitcnt lgkmcnt(1)
	v_mfma_f32_16x16x32_bf16 v[86:89], v[130:133], v[202:205], v[86:89]
	v_mfma_f32_16x16x32_bf16 v[78:81], v[138:141], v[202:205], v[78:81]
	v_mfma_f32_16x16x32_bf16 v[126:129], v[134:137], v[170:173], v[126:129]
	v_mfma_f32_16x16x32_bf16 v[122:125], v[142:145], v[170:173], v[122:125]
	v_mfma_f32_16x16x32_bf16 v[118:121], v[134:137], v[190:193], v[118:121]
	v_mfma_f32_16x16x32_bf16 v[110:113], v[142:145], v[190:193], v[110:113]
	v_mfma_f32_16x16x32_bf16 v[94:97], v[134:137], v[198:201], v[94:97]
	v_mfma_f32_16x16x32_bf16 v[90:93], v[142:145], v[198:201], v[90:93]
	s_waitcnt lgkmcnt(0)
	v_mfma_f32_16x16x32_bf16 v[86:89], v[134:137], v[206:209], v[86:89]
	v_mfma_f32_16x16x32_bf16 v[78:81], v[142:145], v[206:209], v[78:81]
	s_setprio 0
	s_setprio 1
	v_mfma_f32_16x16x32_bf16 v[114:117], v[150:153], v[166:169], v[114:117]
	v_mfma_f32_16x16x32_bf16 v[106:109], v[158:161], v[166:169], v[106:109]
	v_mfma_f32_16x16x32_bf16 v[102:105], v[150:153], v[186:189], v[102:105]
	v_mfma_f32_16x16x32_bf16 v[98:101], v[158:161], v[186:189], v[98:101]
	v_mfma_f32_16x16x32_bf16 v[82:85], v[150:153], v[194:197], v[82:85]
	v_mfma_f32_16x16x32_bf16 v[74:77], v[158:161], v[194:197], v[74:77]
	v_mfma_f32_16x16x32_bf16 v[70:73], v[150:153], v[202:205], v[70:73]
	v_mfma_f32_16x16x32_bf16 v[66:69], v[158:161], v[202:205], v[66:69]
	v_mfma_f32_16x16x32_bf16 v[114:117], v[154:157], v[170:173], v[114:117]
	v_mfma_f32_16x16x32_bf16 v[106:109], v[162:165], v[170:173], v[106:109]
	v_mfma_f32_16x16x32_bf16 v[102:105], v[154:157], v[190:193], v[102:105]
	v_mfma_f32_16x16x32_bf16 v[98:101], v[162:165], v[190:193], v[98:101]
	v_mfma_f32_16x16x32_bf16 v[82:85], v[154:157], v[198:201], v[82:85]
	v_mfma_f32_16x16x32_bf16 v[74:77], v[162:165], v[198:201], v[74:77]
	s_setprio 2
	s_barrier
	v_mfma_f32_16x16x32_bf16 v[70:73], v[154:157], v[206:209], v[70:73]
	v_mfma_f32_16x16x32_bf16 v[66:69], v[162:165], v[206:209], v[66:69]
	s_setprio 0
	ds_read_b128 v[166:169], v183 offset:16384
	ds_read_b128 v[170:173], v183 offset:17408
	ds_read_b128 v[186:189], v183 offset:18432
	ds_read_b128 v[190:193], v183 offset:19456
	ds_read_b128 v[194:197], v183 offset:20480
	ds_read_b128 v[198:201], v183 offset:21504
	ds_read_b128 v[202:205], v183 offset:22528
	ds_read_b128 v[206:209], v183 offset:23552
	s_mov_b32 s70, m0
	s_mov_b32 m0, s27
	s_nop 0
	global_load_lds_dwordx4 v176, s[30:31]
	s_mov_b32 m0, s70
	s_nop 0
	s_mov_b32 s70, m0
	s_mov_b32 m0, s45
	s_nop 0
	global_load_lds_dwordx4 v178, s[30:31]
	s_mov_b32 m0, s70
	s_add_u32 s70, s30, 0x4000
	s_addc_u32 s71, s31, 0
	s_mov_b32 s73, m0
	s_mov_b32 m0, s46
	s_nop 0
	global_load_lds_dwordx4 v176, s[70:71]
	s_mov_b32 m0, s73
	s_nop 0
	s_mov_b32 s73, m0
	s_mov_b32 m0, s47
	s_nop 0
	global_load_lds_dwordx4 v178, s[70:71]
	s_mov_b32 m0, s73
	s_waitcnt vmcnt(4)
	s_waitcnt lgkmcnt(0)
	s_barrier
	s_setprio 1
	s_waitcnt lgkmcnt(7)
	v_mfma_f32_16x16x32_bf16 v[62:65], v[130:133], v[166:169], v[62:65]
	v_mfma_f32_16x16x32_bf16 v[58:61], v[138:141], v[166:169], v[58:61]
	s_waitcnt lgkmcnt(5)
	v_mfma_f32_16x16x32_bf16 v[46:49], v[130:133], v[186:189], v[46:49]
	v_mfma_f32_16x16x32_bf16 v[42:45], v[138:141], v[186:189], v[42:45]
	s_waitcnt lgkmcnt(3)
	v_mfma_f32_16x16x32_bf16 v[30:33], v[130:133], v[194:197], v[30:33]
	v_mfma_f32_16x16x32_bf16 v[26:29], v[138:141], v[194:197], v[26:29]
	s_waitcnt lgkmcnt(1)
	v_mfma_f32_16x16x32_bf16 v[14:17], v[130:133], v[202:205], v[14:17]
	v_mfma_f32_16x16x32_bf16 v[10:13], v[138:141], v[202:205], v[10:13]
	v_mfma_f32_16x16x32_bf16 v[62:65], v[134:137], v[170:173], v[62:65]
	v_mfma_f32_16x16x32_bf16 v[58:61], v[142:145], v[170:173], v[58:61]
	v_mfma_f32_16x16x32_bf16 v[46:49], v[134:137], v[190:193], v[46:49]
	v_mfma_f32_16x16x32_bf16 v[42:45], v[142:145], v[190:193], v[42:45]
	v_mfma_f32_16x16x32_bf16 v[30:33], v[134:137], v[198:201], v[30:33]
	v_mfma_f32_16x16x32_bf16 v[26:29], v[142:145], v[198:201], v[26:29]
	s_waitcnt lgkmcnt(0)
	v_mfma_f32_16x16x32_bf16 v[14:17], v[134:137], v[206:209], v[14:17]
	v_mfma_f32_16x16x32_bf16 v[10:13], v[142:145], v[206:209], v[10:13]
	s_setprio 0
	s_setprio 1
	v_mfma_f32_16x16x32_bf16 v[54:57], v[150:153], v[166:169], v[54:57]
	v_mfma_f32_16x16x32_bf16 v[50:53], v[158:161], v[166:169], v[50:53]
	v_mfma_f32_16x16x32_bf16 v[38:41], v[150:153], v[186:189], v[38:41]
	v_mfma_f32_16x16x32_bf16 v[34:37], v[158:161], v[186:189], v[34:37]
	v_mfma_f32_16x16x32_bf16 v[22:25], v[150:153], v[194:197], v[22:25]
	v_mfma_f32_16x16x32_bf16 v[18:21], v[158:161], v[194:197], v[18:21]
	v_mfma_f32_16x16x32_bf16 v[6:9], v[150:153], v[202:205], v[6:9]
	v_mfma_f32_16x16x32_bf16 v[2:5], v[158:161], v[202:205], v[2:5]
	v_mfma_f32_16x16x32_bf16 v[54:57], v[154:157], v[170:173], v[54:57]
	v_mfma_f32_16x16x32_bf16 v[50:53], v[162:165], v[170:173], v[50:53]
	v_mfma_f32_16x16x32_bf16 v[38:41], v[154:157], v[190:193], v[38:41]
	v_mfma_f32_16x16x32_bf16 v[34:37], v[162:165], v[190:193], v[34:37]
	v_mfma_f32_16x16x32_bf16 v[22:25], v[154:157], v[198:201], v[22:25]
	v_mfma_f32_16x16x32_bf16 v[18:21], v[162:165], v[198:201], v[18:21]
	s_setprio 2
	s_barrier
	v_mfma_f32_16x16x32_bf16 v[6:9], v[154:157], v[206:209], v[6:9]
	v_mfma_f32_16x16x32_bf16 v[2:5], v[162:165], v[206:209], v[2:5]
	s_setprio 0
	ds_read_b128 v[130:133], v184
	ds_read_b128 v[134:137], v184 offset:1024
	ds_read_b128 v[138:141], v184 offset:2048
	ds_read_b128 v[142:145], v184 offset:3072
	ds_read_b128 v[150:153], v185
	ds_read_b128 v[154:157], v185 offset:1024
	ds_read_b128 v[158:161], v185 offset:2048
	ds_read_b128 v[162:165], v185 offset:3072
	ds_read_b128 v[166:169], v183 offset:32768
	ds_read_b128 v[170:173], v183 offset:33792
	ds_read_b128 v[186:189], v183 offset:34816
	ds_read_b128 v[190:193], v183 offset:35840
	ds_read_b128 v[194:197], v183 offset:36864
	ds_read_b128 v[198:201], v183 offset:37888
	ds_read_b128 v[202:205], v183 offset:38912
	ds_read_b128 v[206:209], v183 offset:39936
	s_mov_b32 s70, m0
	s_mov_b32 m0, s44
	s_nop 0
	global_load_lds_dwordx4 v1, s[34:35]
	s_mov_b32 m0, s70
	s_nop 0
	s_mov_b32 s70, m0
	s_mov_b32 m0, s48
	s_nop 0
	global_load_lds_dwordx4 v177, s[34:35]
	s_mov_b32 m0, s70
	s_add_u32 s34, s34, 0x4000
	s_addc_u32 s35, s35, 0
	s_mov_b32 s70, m0
	s_mov_b32 m0, s49
	s_nop 0
	global_load_lds_dwordx4 v1, s[34:35]
	s_mov_b32 m0, s70
	s_nop 0
	s_mov_b32 s70, m0
	s_mov_b32 m0, s50
	s_nop 0
	global_load_lds_dwordx4 v177, s[34:35]
	s_mov_b32 m0, s70
	s_waitcnt vmcnt(8)
	s_waitcnt lgkmcnt(0)
	s_barrier
	s_setprio 1
	s_waitcnt lgkmcnt(7)
	v_mfma_f32_16x16x32_bf16 v[126:129], v[130:133], v[166:169], v[126:129]
	v_mfma_f32_16x16x32_bf16 v[122:125], v[138:141], v[166:169], v[122:125]
	s_waitcnt lgkmcnt(5)
	v_mfma_f32_16x16x32_bf16 v[118:121], v[130:133], v[186:189], v[118:121]
	v_mfma_f32_16x16x32_bf16 v[110:113], v[138:141], v[186:189], v[110:113]
	s_waitcnt lgkmcnt(3)
	v_mfma_f32_16x16x32_bf16 v[94:97], v[130:133], v[194:197], v[94:97]
	v_mfma_f32_16x16x32_bf16 v[90:93], v[138:141], v[194:197], v[90:93]
	s_waitcnt lgkmcnt(1)
	v_mfma_f32_16x16x32_bf16 v[86:89], v[130:133], v[202:205], v[86:89]
	v_mfma_f32_16x16x32_bf16 v[78:81], v[138:141], v[202:205], v[78:81]
	v_mfma_f32_16x16x32_bf16 v[126:129], v[134:137], v[170:173], v[126:129]
	v_mfma_f32_16x16x32_bf16 v[122:125], v[142:145], v[170:173], v[122:125]
	v_mfma_f32_16x16x32_bf16 v[118:121], v[134:137], v[190:193], v[118:121]
	v_mfma_f32_16x16x32_bf16 v[110:113], v[142:145], v[190:193], v[110:113]
	v_mfma_f32_16x16x32_bf16 v[94:97], v[134:137], v[198:201], v[94:97]
	v_mfma_f32_16x16x32_bf16 v[90:93], v[142:145], v[198:201], v[90:93]
	s_waitcnt lgkmcnt(0)
	v_mfma_f32_16x16x32_bf16 v[86:89], v[134:137], v[206:209], v[86:89]
	v_mfma_f32_16x16x32_bf16 v[78:81], v[142:145], v[206:209], v[78:81]
	s_setprio 0
	s_setprio 1
	v_mfma_f32_16x16x32_bf16 v[114:117], v[150:153], v[166:169], v[114:117]
	v_mfma_f32_16x16x32_bf16 v[106:109], v[158:161], v[166:169], v[106:109]
	v_mfma_f32_16x16x32_bf16 v[102:105], v[150:153], v[186:189], v[102:105]
	v_mfma_f32_16x16x32_bf16 v[98:101], v[158:161], v[186:189], v[98:101]
	v_mfma_f32_16x16x32_bf16 v[82:85], v[150:153], v[194:197], v[82:85]
	v_mfma_f32_16x16x32_bf16 v[74:77], v[158:161], v[194:197], v[74:77]
	v_mfma_f32_16x16x32_bf16 v[70:73], v[150:153], v[202:205], v[70:73]
	v_mfma_f32_16x16x32_bf16 v[66:69], v[158:161], v[202:205], v[66:69]
	v_mfma_f32_16x16x32_bf16 v[114:117], v[154:157], v[170:173], v[114:117]
	v_mfma_f32_16x16x32_bf16 v[106:109], v[162:165], v[170:173], v[106:109]
	v_mfma_f32_16x16x32_bf16 v[102:105], v[154:157], v[190:193], v[102:105]
	v_mfma_f32_16x16x32_bf16 v[98:101], v[162:165], v[190:193], v[98:101]
	v_mfma_f32_16x16x32_bf16 v[82:85], v[154:157], v[198:201], v[82:85]
	v_mfma_f32_16x16x32_bf16 v[74:77], v[162:165], v[198:201], v[74:77]
	s_setprio 2
	s_barrier
	v_mfma_f32_16x16x32_bf16 v[70:73], v[154:157], v[206:209], v[70:73]
	v_mfma_f32_16x16x32_bf16 v[66:69], v[162:165], v[206:209], v[66:69]
	s_setprio 0
	ds_read_b128 v[166:169], v183 offset:49152
	ds_read_b128 v[170:173], v183 offset:50176
	ds_read_b128 v[186:189], v183 offset:51200
	ds_read_b128 v[190:193], v183 offset:52224
	ds_read_b128 v[194:197], v183 offset:53248
	ds_read_b128 v[198:201], v183 offset:54272
	ds_read_b128 v[202:205], v183 offset:55296
	ds_read_b128 v[206:209], v183 offset:56320
	s_add_u32 s34, s30, 0x40000
	s_addc_u32 s35, s31, 0
	s_mov_b32 s70, m0
	s_mov_b32 m0, s51
	s_nop 0
	global_load_lds_dwordx4 v176, s[34:35]
	s_mov_b32 m0, s70
	s_add_u32 s30, s30, 0x44000
	s_mov_b32 s70, m0
	s_mov_b32 m0, s52
	s_nop 0
	global_load_lds_dwordx4 v178, s[34:35]
	s_mov_b32 m0, s70
	s_addc_u32 s31, s31, 0
	s_mov_b32 s34, m0
	s_mov_b32 m0, s53
	s_nop 0
	global_load_lds_dwordx4 v176, s[30:31]
	s_mov_b32 m0, s34
	s_nop 0
	s_mov_b32 s34, m0
	s_mov_b32 m0, s54
	s_nop 0
	global_load_lds_dwordx4 v178, s[30:31]
	s_mov_b32 m0, s34
	s_waitcnt vmcnt(4)
	s_waitcnt lgkmcnt(0)
	s_barrier
	s_setprio 1
	s_waitcnt lgkmcnt(7)
	v_mfma_f32_16x16x32_bf16 v[62:65], v[130:133], v[166:169], v[62:65]
	v_mfma_f32_16x16x32_bf16 v[58:61], v[138:141], v[166:169], v[58:61]
	s_waitcnt lgkmcnt(5)
	v_mfma_f32_16x16x32_bf16 v[46:49], v[130:133], v[186:189], v[46:49]
	v_mfma_f32_16x16x32_bf16 v[42:45], v[138:141], v[186:189], v[42:45]
	s_waitcnt lgkmcnt(3)
	v_mfma_f32_16x16x32_bf16 v[30:33], v[130:133], v[194:197], v[30:33]
	v_mfma_f32_16x16x32_bf16 v[26:29], v[138:141], v[194:197], v[26:29]
	s_waitcnt lgkmcnt(1)
	v_mfma_f32_16x16x32_bf16 v[14:17], v[130:133], v[202:205], v[14:17]
	v_mfma_f32_16x16x32_bf16 v[10:13], v[138:141], v[202:205], v[10:13]
	v_mfma_f32_16x16x32_bf16 v[62:65], v[134:137], v[170:173], v[62:65]
	v_mfma_f32_16x16x32_bf16 v[58:61], v[142:145], v[170:173], v[58:61]
	v_mfma_f32_16x16x32_bf16 v[46:49], v[134:137], v[190:193], v[46:49]
	v_mfma_f32_16x16x32_bf16 v[42:45], v[142:145], v[190:193], v[42:45]
	v_mfma_f32_16x16x32_bf16 v[30:33], v[134:137], v[198:201], v[30:33]
	v_mfma_f32_16x16x32_bf16 v[26:29], v[142:145], v[198:201], v[26:29]
	s_waitcnt lgkmcnt(0)
	v_mfma_f32_16x16x32_bf16 v[14:17], v[134:137], v[206:209], v[14:17]
	v_mfma_f32_16x16x32_bf16 v[10:13], v[142:145], v[206:209], v[10:13]
	s_setprio 0
	s_setprio 1
	v_mfma_f32_16x16x32_bf16 v[54:57], v[150:153], v[166:169], v[54:57]
	v_mfma_f32_16x16x32_bf16 v[50:53], v[158:161], v[166:169], v[50:53]
	v_mfma_f32_16x16x32_bf16 v[38:41], v[150:153], v[186:189], v[38:41]
	v_mfma_f32_16x16x32_bf16 v[34:37], v[158:161], v[186:189], v[34:37]
	v_mfma_f32_16x16x32_bf16 v[22:25], v[150:153], v[194:197], v[22:25]
	v_mfma_f32_16x16x32_bf16 v[18:21], v[158:161], v[194:197], v[18:21]
	v_mfma_f32_16x16x32_bf16 v[6:9], v[150:153], v[202:205], v[6:9]
	v_mfma_f32_16x16x32_bf16 v[2:5], v[158:161], v[202:205], v[2:5]
	v_mfma_f32_16x16x32_bf16 v[54:57], v[154:157], v[170:173], v[54:57]
	v_mfma_f32_16x16x32_bf16 v[50:53], v[162:165], v[170:173], v[50:53]
	v_mfma_f32_16x16x32_bf16 v[38:41], v[154:157], v[190:193], v[38:41]
	v_mfma_f32_16x16x32_bf16 v[34:37], v[162:165], v[190:193], v[34:37]
	v_mfma_f32_16x16x32_bf16 v[22:25], v[154:157], v[198:201], v[22:25]
	v_mfma_f32_16x16x32_bf16 v[18:21], v[162:165], v[198:201], v[18:21]
	s_setprio 2
	s_barrier
	v_mfma_f32_16x16x32_bf16 v[6:9], v[154:157], v[206:209], v[6:9]
	v_mfma_f32_16x16x32_bf16 v[2:5], v[162:165], v[206:209], v[2:5]
	s_setprio 0
	s_add_i32 s69, s69, 2
	s_add_u32 s65, s65, 0x80000
	s_addc_u32 s66, s66, 0
	s_add_u32 s28, s28, 0x400000
	s_addc_u32 s29, s29, 0
	s_add_u32 s67, s67, 0x400000
	s_addc_u32 s68, s68, 0
	s_cmpk_gt_u32 s69, 0x53
	s_cbranch_scc0 .LBB0_2792
	s_and_b64 vcc, exec, s[8:9]
	s_cbranch_vccz .LBB0_2795
	s_barrier
